# strategy 9 loop-edge rotation: K-loop head pointer-select SALU moved in front of the loop-back barrier (copy before entry), on top of saddr+lbase+nopfill
# speedup vs baseline: 1.0029x; 1.0029x over previous
; #define PG8_STAGE(bufoff, gbase, voff) do { _Pragma("unroll") for (int _i = 0; _i < 2; ++_i) \
;         __builtin_amdgcn_global_load_lds((const unsigned*)((const char*)(gbase) + (voff)[_i]), (LAS unsigned*)(lds + (bufoff) + ldsw + _i * 8192), 16, 0, 0); } while (0)
; #define PG8_LDA(dst, b, h) do { _Pragma("unroll") for (int m = 0; m < 4; ++m) _Pragma("unroll") for (int k = 0; k < 2; ++k) dst[m][k] = *(const LAS bf16x8*)(lds + PG8_SA(b, h) + aoff + m * 2048 + k * 1024); } while (0)
; #define PG8_LDB(dst, b, h) do { _Pragma("unroll") for (int n = 0; n < 2; ++n) _Pragma("unroll") for (int k = 0; k < 2; ++k) dst[n][k] = *(const LAS bf16x8*)(lds + PG8_SB(b, h) + boff + n * 2048 + k * 1024); } while (0)
; #define PG8_SCHED __builtin_amdgcn_sched_barrier(0)
; template <class Epi, class Sched>
; __device__ __forceinline__ void gemm_phase(LAS unsigned char* lds, const Gemm g, const Sched& S, const Epi& E) {
;     ...
;         const bool has_next = S.next(ui + 1, nxt);
;         const char* nA = has_next ? (const char*)g.A + (size_t)nxt.pm * tstep + (size_t)nxt.ks * sstep : cA; const char* nB = has_next ? (const char*)g.Bt + (size_t)nxt.pn * tstep + (size_t)nxt.ks * sstep : cB;
;         for (int t = 0; t < nt; t += 2) {
;             const bool last = (t == nt - 2);
;             const char* a1 = cA + (size_t)(t + 1) * kstep;
;             const char* a2 = last ? nA : cA + (size_t)(t + 2) * kstep; const char* b2 = last ? nB : cB + (size_t)(t + 2) * kstep;
;             const char* a3 = a2 + kstep; const char* b3 = b2 + kstep;
;             PG8_LDB(B0, 0, 0); PG8_SCHED; PG8_LDA(At, 0, 0); PG8_STAGE(PG8_SA(1, 1), a1 + hstep, voffA);
;     ...
; #pragma unroll
;         for (int a = 0; a < 2; ++a)
; #pragma unroll
;             for (int b = 0; b < 2; ++b)
; #pragma unroll
;                 for (int m = 0; m < 4; ++m)
; #pragma unroll
;                     for (int n = 0; n < 2; ++n) acc[a][b][m][n] = (f32x4){0.f, 0.f, 0.f, 0.f};
;         cur = nxt; cA = nA; cB = nB; ++ui;
.LBB0_43:
	s_ashr_i32 s27, s26, 31
	s_lshl_b64 s[38:39], s[26:27], 22
	v_cmp_lt_i64_e32 vcc, s[42:43], v[158:159]
	s_add_u32 s42, s10, s38
	s_addc_u32 s43, s11, s39
	s_and_b64 s[38:39], vcc, exec
	s_cselect_b32 s27, s43, s29
	s_cselect_b32 s71, s42, s28
	s_ashr_i32 s25, s24, 31
	s_lshl_b64 s[38:39], s[24:25], 22
	s_add_u32 s48, s13, s38
	s_addc_u32 s49, s30, s39
	s_and_b64 s[38:39], vcc, exec
	s_cselect_b32 s25, s49, s51
	s_cselect_b32 s72, s48, s50
	s_add_u32 s73, s50, 0x100
	v_mov_b32_e32 v2, 0
	s_addc_u32 s74, s51, 0
	s_mov_b32 s75, -2
	v_mov_b32_e32 v3, v2
	v_mov_b32_e32 v4, v2
	v_mov_b32_e32 v5, v2
	v_mov_b32_e32 v6, v2
	v_mov_b32_e32 v7, v2
	v_mov_b32_e32 v8, v2
	v_mov_b32_e32 v9, v2
	v_mov_b32_e32 v10, v2
	v_mov_b32_e32 v11, v2
	v_mov_b32_e32 v12, v2
	v_mov_b32_e32 v13, v2
	v_mov_b32_e32 v18, v2
	v_mov_b32_e32 v19, v2
	v_mov_b32_e32 v20, v2
	v_mov_b32_e32 v21, v2
	v_mov_b32_e32 v34, v2
	v_mov_b32_e32 v35, v2
	v_mov_b32_e32 v36, v2
	v_mov_b32_e32 v37, v2
	v_mov_b32_e32 v38, v2
	v_mov_b32_e32 v39, v2
	v_mov_b32_e32 v40, v2
	v_mov_b32_e32 v41, v2
	v_mov_b32_e32 v50, v2
	v_mov_b32_e32 v51, v2
	v_mov_b32_e32 v52, v2
	v_mov_b32_e32 v53, v2
	v_mov_b32_e32 v54, v2
	v_mov_b32_e32 v55, v2
	v_mov_b32_e32 v56, v2
	v_mov_b32_e32 v57, v2
	v_mov_b32_e32 v14, v2
	v_mov_b32_e32 v15, v2
	v_mov_b32_e32 v16, v2
	v_mov_b32_e32 v17, v2
	s_waitcnt vmcnt(0)
	v_mov_b32_e32 v22, v2
	v_mov_b32_e32 v23, v2
	v_mov_b32_e32 v24, v2
	v_mov_b32_e32 v25, v2
	v_mov_b32_e32 v26, v2
	v_mov_b32_e32 v27, v2
	v_mov_b32_e32 v28, v2
	v_mov_b32_e32 v29, v2
	v_mov_b32_e32 v30, v2
	v_mov_b32_e32 v31, v2
	v_mov_b32_e32 v32, v2
	v_mov_b32_e32 v33, v2
	v_mov_b32_e32 v42, v2
	v_mov_b32_e32 v43, v2
	v_mov_b32_e32 v44, v2
	v_mov_b32_e32 v45, v2
	v_mov_b32_e32 v46, v2
	v_mov_b32_e32 v47, v2
	v_mov_b32_e32 v48, v2
	v_mov_b32_e32 v49, v2
	v_mov_b32_e32 v58, v2
	v_mov_b32_e32 v59, v2
	v_mov_b32_e32 v60, v2
	v_mov_b32_e32 v61, v2
	v_mov_b32_e32 v62, v2
	v_mov_b32_e32 v63, v2
	v_mov_b32_e32 v64, v2
	v_mov_b32_e32 v65, v2
	v_mov_b32_e32 v82, v2
	v_mov_b32_e32 v83, v2
	v_mov_b32_e32 v84, v2
	v_mov_b32_e32 v85, v2
	v_mov_b32_e32 v86, v2
	v_mov_b32_e32 v87, v2
	v_mov_b32_e32 v88, v2
	v_mov_b32_e32 v89, v2
	v_mov_b32_e32 v90, v2
	v_mov_b32_e32 v91, v2
	v_mov_b32_e32 v92, v2
	v_mov_b32_e32 v93, v2
	v_mov_b32_e32 v94, v2
	v_mov_b32_e32 v95, v2
	v_mov_b32_e32 v96, v2
	v_mov_b32_e32 v97, v2
	v_mov_b32_e32 v114, v2
	v_mov_b32_e32 v115, v2
	v_mov_b32_e32 v116, v2
	v_mov_b32_e32 v117, v2
	v_mov_b32_e32 v118, v2
	v_mov_b32_e32 v119, v2
	v_mov_b32_e32 v120, v2
	v_mov_b32_e32 v121, v2
	v_mov_b32_e32 v130, v2
	v_mov_b32_e32 v131, v2
	v_mov_b32_e32 v132, v2
	v_mov_b32_e32 v133, v2
	v_mov_b32_e32 v134, v2
	v_mov_b32_e32 v135, v2
	v_mov_b32_e32 v136, v2
	v_mov_b32_e32 v137, v2
	v_mov_b32_e32 v98, v2
	v_mov_b32_e32 v99, v2
	v_mov_b32_e32 v100, v2
	v_mov_b32_e32 v101, v2
	v_mov_b32_e32 v102, v2
	v_mov_b32_e32 v103, v2
	v_mov_b32_e32 v104, v2
	v_mov_b32_e32 v105, v2
	v_mov_b32_e32 v106, v2
	v_mov_b32_e32 v107, v2
	v_mov_b32_e32 v108, v2
	v_mov_b32_e32 v109, v2
	v_mov_b32_e32 v110, v2
	v_mov_b32_e32 v111, v2
	v_mov_b32_e32 v112, v2
	v_mov_b32_e32 v113, v2
	v_mov_b32_e32 v122, v2
	v_mov_b32_e32 v123, v2
	v_mov_b32_e32 v124, v2
	v_mov_b32_e32 v125, v2
	v_mov_b32_e32 v126, v2
	v_mov_b32_e32 v127, v2
	v_mov_b32_e32 v128, v2
	v_mov_b32_e32 v129, v2
	v_mov_b32_e32 v138, v2
	v_mov_b32_e32 v139, v2
	v_mov_b32_e32 v140, v2
	v_mov_b32_e32 v141, v2
	v_mov_b32_e32 v142, v2
	v_mov_b32_e32 v143, v2
	v_mov_b32_e32 v144, v2
	v_mov_b32_e32 v145, v2
	s_add_u32 s50, s28, 0x100
	s_addc_u32 s51, s29, 0
	s_cmpk_eq_i32 s75, 0x7c
	s_cselect_b32 s55, s27, s51
	s_cselect_b32 s54, s71, s50
	s_cselect_b32 s53, s25, s74
	s_cselect_b32 s52, s72, s73
.LBB0_44:
	s_add_i32 m0, s9, 0xc000
	ds_read_b128 v[66:69], v226
	global_load_lds_dwordx4 v150, s[28:29]
	s_add_i32 m0, s9, 0xe000
	ds_read_b128 v[70:73], v226 offset:1024
	global_load_lds_dwordx4 v148, s[28:29]
	s_add_i32 s38, 0, 0x10000
	ds_read_b128 v[74:77], v226 offset:2048
	ds_read_b128 v[78:81], v226 offset:3072
	ds_read_b128 v[152:155], v165
	ds_read_b128 v[166:169], v165 offset:1024
	ds_read_b128 v[170:173], v165 offset:2048
	ds_read_b128 v[174:177], v165 offset:3072
	ds_read_b128 v[178:181], v165 offset:4096
	ds_read_b128 v[182:185], v165 offset:5120
	ds_read_b128 v[186:189], v165 offset:6144
	ds_read_b128 v[190:193], v165 offset:7168
	s_add_i32 s39, 0, 0x14000
	ds_read_b128 v[194:197], v226 offset:16384
	ds_read_b128 v[198:201], v226 offset:17408
	ds_read_b128 v[202:205], v226 offset:18432
	ds_read_b128 v[210:213], v226 offset:19456
	s_waitcnt lgkmcnt(4)
	s_barrier
; #define PG8_STAGE(bufoff, gbase, voff) do { _Pragma("unroll") for (int _i = 0; _i < 2; ++_i) \
;         __builtin_amdgcn_global_load_lds((const unsigned*)((const char*)(gbase) + (voff)[_i]), (LAS unsigned*)(lds + (bufoff) + ldsw + _i * 8192), 16, 0, 0); } while (0)
; #define PG8_LDA(dst, b, h) do { _Pragma("unroll") for (int m = 0; m < 4; ++m) _Pragma("unroll") for (int k = 0; k < 2; ++k) dst[m][k] = *(const LAS bf16x8*)(lds + PG8_SA(b, h) + aoff + m * 2048 + k * 1024); } while (0)
; #define PG8_LDB(dst, b, h) do { _Pragma("unroll") for (int n = 0; n < 2; ++n) _Pragma("unroll") for (int k = 0; k < 2; ++k) dst[n][k] = *(const LAS bf16x8*)(lds + PG8_SB(b, h) + boff + n * 2048 + k * 1024); } while (0)
; #define PG8_MMA(ai, bj, At, Bt) do { __builtin_amdgcn_s_setprio(1); _Pragma("unroll") for (int m = 0; m < 4; ++m) _Pragma("unroll") for (int n = 0; n < 2; ++n) _Pragma("unroll") for (int k = 0; k < 2; ++k) \
;         acc[ai][bj][m][n] = __builtin_amdgcn_mfma_f32_16x16x32_bf16(Bt[n][k], At[m][k], acc[ai][bj][m][n], 0, 0, 0); __builtin_amdgcn_s_setprio(0); } while (0)
; #define PG8_WAIT_V(n) asm volatile("s_waitcnt vmcnt(" #n ")" ::: "memory")
; #define PG8_WAIT_L(n) asm volatile("s_waitcnt lgkmcnt(" #n ")" ::: "memory")
; #define PG8_BAR __builtin_amdgcn_s_barrier()
; #define PG8_SCHED __builtin_amdgcn_sched_barrier(0)
; template <class Epi, class Sched>
; __device__ __forceinline__ void gemm_phase(LAS unsigned char* lds, const Gemm g, const Sched& S, const Epi& E) {
;     ...
;             PG8_LDB(B0, 0, 0); PG8_SCHED; PG8_LDA(At, 0, 0); PG8_STAGE(PG8_SA(1, 1), a1 + hstep, voffA);
;             PG8_WAIT_L(8); PG8_BAR; PG8_WAIT_L(0); PG8_MMA(0, 0, At, B0); PG8_BAR; PG8_SCHED;
;             PG8_LDB(B1, 0, 1); PG8_STAGE(PG8_SB(0, 0), b2, voffB);
;             PG8_BAR; PG8_WAIT_L(0); PG8_MMA(0, 1, At, B1); PG8_BAR;
;             PG8_LDA(At, 0, 1); PG8_STAGE(PG8_SA(0, 0), a2, voffA);
;             PG8_BAR; PG8_WAIT_L(0); PG8_MMA(1, 0, At, B0); PG8_BAR; PG8_SCHED;
;             PG8_STAGE(PG8_SB(0, 1), b2 + hstep, voffB);
;             PG8_WAIT_V(6); PG8_BAR; PG8_MMA(1, 1, At, B1); PG8_BAR;
	s_waitcnt lgkmcnt(0)
	v_mfma_f32_16x16x32_bf16 v[142:145], v[66:69], v[152:155], v[142:145]
	v_mfma_f32_16x16x32_bf16 v[138:141], v[74:77], v[152:155], v[138:141]
	v_mfma_f32_16x16x32_bf16 v[126:129], v[66:69], v[170:173], v[126:129]
	v_mfma_f32_16x16x32_bf16 v[122:125], v[74:77], v[170:173], v[122:125]
	v_mfma_f32_16x16x32_bf16 v[110:113], v[66:69], v[178:181], v[110:113]
	v_mfma_f32_16x16x32_bf16 v[106:109], v[74:77], v[178:181], v[106:109]
	v_mfma_f32_16x16x32_bf16 v[102:105], v[66:69], v[186:189], v[102:105]
	v_mfma_f32_16x16x32_bf16 v[98:101], v[74:77], v[186:189], v[98:101]
	v_mfma_f32_16x16x32_bf16 v[142:145], v[70:73], v[166:169], v[142:145]
	v_mfma_f32_16x16x32_bf16 v[138:141], v[78:81], v[166:169], v[138:141]
	v_mfma_f32_16x16x32_bf16 v[126:129], v[70:73], v[174:177], v[126:129]
	v_mfma_f32_16x16x32_bf16 v[122:125], v[78:81], v[174:177], v[122:125]
	v_mfma_f32_16x16x32_bf16 v[110:113], v[70:73], v[182:185], v[110:113]
	v_mfma_f32_16x16x32_bf16 v[106:109], v[78:81], v[182:185], v[106:109]
	v_mfma_f32_16x16x32_bf16 v[102:105], v[70:73], v[190:193], v[102:105]
	v_mfma_f32_16x16x32_bf16 v[98:101], v[78:81], v[190:193], v[98:101]
	v_mfma_f32_16x16x32_bf16 v[134:137], v[194:197], v[152:155], v[134:137]
	v_mfma_f32_16x16x32_bf16 v[130:133], v[202:205], v[152:155], v[130:133]
	v_mfma_f32_16x16x32_bf16 v[118:121], v[194:197], v[170:173], v[118:121]
	v_mfma_f32_16x16x32_bf16 v[114:117], v[202:205], v[170:173], v[114:117]
	v_mfma_f32_16x16x32_bf16 v[94:97], v[194:197], v[178:181], v[94:97]
	v_mfma_f32_16x16x32_bf16 v[90:93], v[202:205], v[178:181], v[90:93]
	v_mfma_f32_16x16x32_bf16 v[86:89], v[194:197], v[186:189], v[86:89]
	v_mfma_f32_16x16x32_bf16 v[82:85], v[202:205], v[186:189], v[82:85]
	v_mfma_f32_16x16x32_bf16 v[134:137], v[198:201], v[166:169], v[134:137]
	v_mfma_f32_16x16x32_bf16 v[130:133], v[210:213], v[166:169], v[130:133]
	v_mfma_f32_16x16x32_bf16 v[118:121], v[198:201], v[174:177], v[118:121]
	v_mfma_f32_16x16x32_bf16 v[114:117], v[210:213], v[174:177], v[114:117]
	v_mfma_f32_16x16x32_bf16 v[94:97], v[198:201], v[182:185], v[94:97]
	v_mfma_f32_16x16x32_bf16 v[90:93], v[210:213], v[182:185], v[90:93]
	v_mfma_f32_16x16x32_bf16 v[86:89], v[198:201], v[190:193], v[86:89]
	v_mfma_f32_16x16x32_bf16 v[82:85], v[210:213], v[190:193], v[82:85]
	s_barrier
	s_add_i32 s28, s38, s60
	s_mov_b32 m0, s28
	ds_read_b128 v[152:155], v165 offset:16384
	global_load_lds_dwordx4 v0, s[52:53]
	s_add_i32 m0, s28, 0x2000
	ds_read_b128 v[166:169], v165 offset:17408
	global_load_lds_dwordx4 v146, s[52:53]
	s_mov_b32 m0, s9
	ds_read_b128 v[170:173], v165 offset:18432
	global_load_lds_dwordx4 v0, s[54:55]
	s_mov_b32 m0, s61
	ds_read_b128 v[174:177], v165 offset:19456
	global_load_lds_dwordx4 v146, s[54:55]
	ds_read_b128 v[178:181], v165 offset:20480
	ds_read_b128 v[182:185], v165 offset:21504
	ds_read_b128 v[186:189], v165 offset:22528
	ds_read_b128 v[190:193], v165 offset:23552
	s_waitcnt vmcnt(4)
	s_waitcnt lgkmcnt(0)
	s_barrier
	v_mfma_f32_16x16x32_bf16 v[62:65], v[66:69], v[152:155], v[62:65]
	v_mfma_f32_16x16x32_bf16 v[58:61], v[74:77], v[152:155], v[58:61]
	v_mfma_f32_16x16x32_bf16 v[46:49], v[66:69], v[170:173], v[46:49]
	v_mfma_f32_16x16x32_bf16 v[42:45], v[74:77], v[170:173], v[42:45]
	v_mfma_f32_16x16x32_bf16 v[30:33], v[66:69], v[178:181], v[30:33]
	v_mfma_f32_16x16x32_bf16 v[26:29], v[74:77], v[178:181], v[26:29]
	v_mfma_f32_16x16x32_bf16 v[22:25], v[66:69], v[186:189], v[22:25]
	v_mfma_f32_16x16x32_bf16 v[14:17], v[74:77], v[186:189], v[14:17]
	v_mfma_f32_16x16x32_bf16 v[62:65], v[70:73], v[166:169], v[62:65]
	v_mfma_f32_16x16x32_bf16 v[58:61], v[78:81], v[166:169], v[58:61]
	v_mfma_f32_16x16x32_bf16 v[46:49], v[70:73], v[174:177], v[46:49]
	v_mfma_f32_16x16x32_bf16 v[42:45], v[78:81], v[174:177], v[42:45]
	v_mfma_f32_16x16x32_bf16 v[30:33], v[70:73], v[182:185], v[30:33]
	v_mfma_f32_16x16x32_bf16 v[26:29], v[78:81], v[182:185], v[26:29]
	v_mfma_f32_16x16x32_bf16 v[22:25], v[70:73], v[190:193], v[22:25]
	v_mfma_f32_16x16x32_bf16 v[14:17], v[78:81], v[190:193], v[14:17]
	v_mfma_f32_16x16x32_bf16 v[54:57], v[194:197], v[152:155], v[54:57]
	v_mfma_f32_16x16x32_bf16 v[50:53], v[202:205], v[152:155], v[50:53]
	v_mfma_f32_16x16x32_bf16 v[38:41], v[194:197], v[170:173], v[38:41]
	v_mfma_f32_16x16x32_bf16 v[34:37], v[202:205], v[170:173], v[34:37]
	v_mfma_f32_16x16x32_bf16 v[18:21], v[194:197], v[178:181], v[18:21]
	v_mfma_f32_16x16x32_bf16 v[10:13], v[202:205], v[178:181], v[10:13]
	v_mfma_f32_16x16x32_bf16 v[6:9], v[194:197], v[186:189], v[6:9]
	v_mfma_f32_16x16x32_bf16 v[2:5], v[202:205], v[186:189], v[2:5]
	v_mfma_f32_16x16x32_bf16 v[54:57], v[198:201], v[166:169], v[54:57]
	v_mfma_f32_16x16x32_bf16 v[50:53], v[210:213], v[166:169], v[50:53]
	v_mfma_f32_16x16x32_bf16 v[38:41], v[198:201], v[174:177], v[38:41]
	v_mfma_f32_16x16x32_bf16 v[34:37], v[210:213], v[174:177], v[34:37]
	v_mfma_f32_16x16x32_bf16 v[18:21], v[198:201], v[182:185], v[18:21]
	v_mfma_f32_16x16x32_bf16 v[10:13], v[210:213], v[182:185], v[10:13]
	v_mfma_f32_16x16x32_bf16 v[6:9], v[198:201], v[190:193], v[6:9]
	v_mfma_f32_16x16x32_bf16 v[2:5], v[210:213], v[190:193], v[2:5]
	s_barrier
; #define PG8_STAGE(bufoff, gbase, voff) do { _Pragma("unroll") for (int _i = 0; _i < 2; ++_i) \
;         __builtin_amdgcn_global_load_lds((const unsigned*)((const char*)(gbase) + (voff)[_i]), (LAS unsigned*)(lds + (bufoff) + ldsw + _i * 8192), 16, 0, 0); } while (0)
; #define PG8_LDA(dst, b, h) do { _Pragma("unroll") for (int m = 0; m < 4; ++m) _Pragma("unroll") for (int k = 0; k < 2; ++k) dst[m][k] = *(const LAS bf16x8*)(lds + PG8_SA(b, h) + aoff + m * 2048 + k * 1024); } while (0)
; #define PG8_LDB(dst, b, h) do { _Pragma("unroll") for (int n = 0; n < 2; ++n) _Pragma("unroll") for (int k = 0; k < 2; ++k) dst[n][k] = *(const LAS bf16x8*)(lds + PG8_SB(b, h) + boff + n * 2048 + k * 1024); } while (0)
; #define PG8_MMA(ai, bj, At, Bt) do { __builtin_amdgcn_s_setprio(1); _Pragma("unroll") for (int m = 0; m < 4; ++m) _Pragma("unroll") for (int n = 0; n < 2; ++n) _Pragma("unroll") for (int k = 0; k < 2; ++k) \
;         acc[ai][bj][m][n] = __builtin_amdgcn_mfma_f32_16x16x32_bf16(Bt[n][k], At[m][k], acc[ai][bj][m][n], 0, 0, 0); __builtin_amdgcn_s_setprio(0); } while (0)
; #define PG8_WAIT_V(n) asm volatile("s_waitcnt vmcnt(" #n ")" ::: "memory")
; #define PG8_WAIT_L(n) asm volatile("s_waitcnt lgkmcnt(" #n ")" ::: "memory")
; #define PG8_BAR __builtin_amdgcn_s_barrier()
; #define PG8_SCHED __builtin_amdgcn_sched_barrier(0)
; template <class Epi, class Sched>
; __device__ __forceinline__ void gemm_phase(LAS unsigned char* lds, const Gemm g, const Sched& S, const Epi& E) {
;     ...
;             PG8_WAIT_V(6); PG8_BAR; PG8_MMA(1, 1, At, B1); PG8_BAR;
;             PG8_LDB(B0, 1, 0); PG8_SCHED; PG8_LDA(At, 1, 0); PG8_STAGE(PG8_SA(0, 1), a2 + hstep, voffA);
;             PG8_WAIT_L(8); PG8_BAR; PG8_WAIT_L(0); PG8_MMA(0, 0, At, B0); PG8_BAR; PG8_SCHED;
;             PG8_LDB(B1, 1, 1); PG8_STAGE(PG8_SB(1, 0), b3, voffB);
;             PG8_BAR; PG8_WAIT_L(0); PG8_MMA(0, 1, At, B1); PG8_BAR;
	s_add_u32 s28, s52, 0x200000
	s_addc_u32 s29, s53, 0
	s_add_i32 s38, s39, s60
	s_mov_b32 m0, s38
	ds_read_b128 v[66:69], v226 offset:32768
	global_load_lds_dwordx4 v0, s[28:29]
	s_add_i32 m0, s38, 0x2000
	ds_read_b128 v[70:73], v226 offset:33792
	global_load_lds_dwordx4 v146, s[28:29]
	s_add_u32 s28, s54, 0x200000
	s_addc_u32 s29, s55, 0
	s_mov_b32 m0, s62
	ds_read_b128 v[74:77], v226 offset:34816
	global_load_lds_dwordx4 v0, s[28:29]
	s_mov_b32 m0, s63
	ds_read_b128 v[78:81], v226 offset:35840
	global_load_lds_dwordx4 v146, s[28:29]
	s_add_i32 s38, 0, 0x18000
	ds_read_b128 v[152:155], v165 offset:32768
	ds_read_b128 v[166:169], v165 offset:33792
	ds_read_b128 v[170:173], v165 offset:34816
	ds_read_b128 v[174:177], v165 offset:35840
	ds_read_b128 v[178:181], v165 offset:36864
	ds_read_b128 v[182:185], v165 offset:37888
	ds_read_b128 v[186:189], v165 offset:38912
	ds_read_b128 v[190:193], v165 offset:39936
	s_add_i32 s39, 0, 0x1c000
	ds_read_b128 v[194:197], v226 offset:49152
	ds_read_b128 v[198:201], v226 offset:50176
	ds_read_b128 v[202:205], v226 offset:51200
	ds_read_b128 v[210:213], v226 offset:52224
	s_waitcnt lgkmcnt(4)
	s_barrier
	s_waitcnt lgkmcnt(0)
	v_mfma_f32_16x16x32_bf16 v[142:145], v[66:69], v[152:155], v[142:145]
	v_mfma_f32_16x16x32_bf16 v[138:141], v[74:77], v[152:155], v[138:141]
	v_mfma_f32_16x16x32_bf16 v[126:129], v[66:69], v[170:173], v[126:129]
	v_mfma_f32_16x16x32_bf16 v[122:125], v[74:77], v[170:173], v[122:125]
	v_mfma_f32_16x16x32_bf16 v[110:113], v[66:69], v[178:181], v[110:113]
	v_mfma_f32_16x16x32_bf16 v[106:109], v[74:77], v[178:181], v[106:109]
	v_mfma_f32_16x16x32_bf16 v[102:105], v[66:69], v[186:189], v[102:105]
	v_mfma_f32_16x16x32_bf16 v[98:101], v[74:77], v[186:189], v[98:101]
	v_mfma_f32_16x16x32_bf16 v[142:145], v[70:73], v[166:169], v[142:145]
	v_mfma_f32_16x16x32_bf16 v[138:141], v[78:81], v[166:169], v[138:141]
	v_mfma_f32_16x16x32_bf16 v[126:129], v[70:73], v[174:177], v[126:129]
	v_mfma_f32_16x16x32_bf16 v[122:125], v[78:81], v[174:177], v[122:125]
	v_mfma_f32_16x16x32_bf16 v[110:113], v[70:73], v[182:185], v[110:113]
	v_mfma_f32_16x16x32_bf16 v[106:109], v[78:81], v[182:185], v[106:109]
	v_mfma_f32_16x16x32_bf16 v[102:105], v[70:73], v[190:193], v[102:105]
	v_mfma_f32_16x16x32_bf16 v[98:101], v[78:81], v[190:193], v[98:101]
	v_mfma_f32_16x16x32_bf16 v[134:137], v[194:197], v[152:155], v[134:137]
	v_mfma_f32_16x16x32_bf16 v[130:133], v[202:205], v[152:155], v[130:133]
	v_mfma_f32_16x16x32_bf16 v[118:121], v[194:197], v[170:173], v[118:121]
	v_mfma_f32_16x16x32_bf16 v[114:117], v[202:205], v[170:173], v[114:117]
	v_mfma_f32_16x16x32_bf16 v[94:97], v[194:197], v[178:181], v[94:97]
	v_mfma_f32_16x16x32_bf16 v[90:93], v[202:205], v[178:181], v[90:93]
	v_mfma_f32_16x16x32_bf16 v[86:89], v[194:197], v[186:189], v[86:89]
	v_mfma_f32_16x16x32_bf16 v[82:85], v[202:205], v[186:189], v[82:85]
	v_mfma_f32_16x16x32_bf16 v[134:137], v[198:201], v[166:169], v[134:137]
	v_mfma_f32_16x16x32_bf16 v[130:133], v[210:213], v[166:169], v[130:133]
	v_mfma_f32_16x16x32_bf16 v[118:121], v[198:201], v[174:177], v[118:121]
	v_mfma_f32_16x16x32_bf16 v[114:117], v[210:213], v[174:177], v[114:117]
	v_mfma_f32_16x16x32_bf16 v[94:97], v[198:201], v[182:185], v[94:97]
	v_mfma_f32_16x16x32_bf16 v[90:93], v[210:213], v[182:185], v[90:93]
	v_mfma_f32_16x16x32_bf16 v[86:89], v[198:201], v[190:193], v[86:89]
	v_mfma_f32_16x16x32_bf16 v[82:85], v[210:213], v[190:193], v[82:85]
	s_barrier
; #define PG8_STAGE(bufoff, gbase, voff) do { _Pragma("unroll") for (int _i = 0; _i < 2; ++_i) \
;         __builtin_amdgcn_global_load_lds((const unsigned*)((const char*)(gbase) + (voff)[_i]), (LAS unsigned*)(lds + (bufoff) + ldsw + _i * 8192), 16, 0, 0); } while (0)
; #define PG8_LDA(dst, b, h) do { _Pragma("unroll") for (int m = 0; m < 4; ++m) _Pragma("unroll") for (int k = 0; k < 2; ++k) dst[m][k] = *(const LAS bf16x8*)(lds + PG8_SA(b, h) + aoff + m * 2048 + k * 1024); } while (0)
; #define PG8_LDB(dst, b, h) do { _Pragma("unroll") for (int n = 0; n < 2; ++n) _Pragma("unroll") for (int k = 0; k < 2; ++k) dst[n][k] = *(const LAS bf16x8*)(lds + PG8_SB(b, h) + boff + n * 2048 + k * 1024); } while (0)
; #define PG8_MMA(ai, bj, At, Bt) do { __builtin_amdgcn_s_setprio(1); _Pragma("unroll") for (int m = 0; m < 4; ++m) _Pragma("unroll") for (int n = 0; n < 2; ++n) _Pragma("unroll") for (int k = 0; k < 2; ++k) \
;         acc[ai][bj][m][n] = __builtin_amdgcn_mfma_f32_16x16x32_bf16(Bt[n][k], At[m][k], acc[ai][bj][m][n], 0, 0, 0); __builtin_amdgcn_s_setprio(0); } while (0)
; #define PG8_WAIT_V(n) asm volatile("s_waitcnt vmcnt(" #n ")" ::: "memory")
; #define PG8_WAIT_L(n) asm volatile("s_waitcnt lgkmcnt(" #n ")" ::: "memory")
; #define PG8_BAR __builtin_amdgcn_s_barrier()
; #define PG8_SCHED __builtin_amdgcn_sched_barrier(0)
; template <class Epi, class Sched>
; __device__ __forceinline__ void gemm_phase(LAS unsigned char* lds, const Gemm g, const Sched& S, const Epi& E) {
;     ...
;             PG8_LDB(B1, 1, 1); PG8_STAGE(PG8_SB(1, 0), b3, voffB);
;             PG8_BAR; PG8_WAIT_L(0); PG8_MMA(0, 1, At, B1); PG8_BAR;
;             PG8_LDA(At, 1, 1); PG8_STAGE(PG8_SA(1, 0), a3, voffA);
;             PG8_BAR; PG8_WAIT_L(0); PG8_MMA(1, 0, At, B0); PG8_BAR; PG8_SCHED;
;             PG8_STAGE(PG8_SB(1, 1), b3 + hstep, voffB);
;             PG8_WAIT_V(6); PG8_BAR; PG8_MMA(1, 1, At, B1); PG8_BAR;
;         }
;         E(acc, cur, wr, wc, fr, fq);
;         if (!has_next) break;
	s_add_i32 s28, s38, s60
	s_add_u32 s100, s52, s36
	s_addc_u32 s101, s53, s37
	s_mov_b32 m0, s28
	ds_read_b128 v[152:155], v165 offset:49152
	global_load_lds_dwordx4 v0, s[100:101]
	s_add_i32 m0, s28, 0x2000
	ds_read_b128 v[166:169], v165 offset:50176
	global_load_lds_dwordx4 v146, s[100:101]
	s_mov_b32 m0, s66
	s_add_u32 s100, s54, s36
	s_addc_u32 s101, s55, s37
	global_load_lds_dwordx4 v0, s[100:101]
	s_mov_b32 m0, s67
	ds_read_b128 v[170:173], v165 offset:51200
	global_load_lds_dwordx4 v146, s[100:101]
	ds_read_b128 v[174:177], v165 offset:52224
	ds_read_b128 v[178:181], v165 offset:53248
	ds_read_b128 v[182:185], v165 offset:54272
	ds_read_b128 v[186:189], v165 offset:55296
	ds_read_b128 v[190:193], v165 offset:56320
	s_waitcnt vmcnt(4)
	s_waitcnt lgkmcnt(0)
	s_barrier
	v_mfma_f32_16x16x32_bf16 v[62:65], v[66:69], v[152:155], v[62:65]
	v_mfma_f32_16x16x32_bf16 v[58:61], v[74:77], v[152:155], v[58:61]
	v_mfma_f32_16x16x32_bf16 v[46:49], v[66:69], v[170:173], v[46:49]
	v_mfma_f32_16x16x32_bf16 v[42:45], v[74:77], v[170:173], v[42:45]
	v_mfma_f32_16x16x32_bf16 v[30:33], v[66:69], v[178:181], v[30:33]
	v_mfma_f32_16x16x32_bf16 v[26:29], v[74:77], v[178:181], v[26:29]
	v_mfma_f32_16x16x32_bf16 v[22:25], v[66:69], v[186:189], v[22:25]
	v_mfma_f32_16x16x32_bf16 v[14:17], v[74:77], v[186:189], v[14:17]
	v_mfma_f32_16x16x32_bf16 v[62:65], v[70:73], v[166:169], v[62:65]
	v_mfma_f32_16x16x32_bf16 v[58:61], v[78:81], v[166:169], v[58:61]
	v_mfma_f32_16x16x32_bf16 v[46:49], v[70:73], v[174:177], v[46:49]
	v_mfma_f32_16x16x32_bf16 v[42:45], v[78:81], v[174:177], v[42:45]
	v_mfma_f32_16x16x32_bf16 v[30:33], v[70:73], v[182:185], v[30:33]
	v_mfma_f32_16x16x32_bf16 v[26:29], v[78:81], v[182:185], v[26:29]
	v_mfma_f32_16x16x32_bf16 v[22:25], v[70:73], v[190:193], v[22:25]
	v_mfma_f32_16x16x32_bf16 v[14:17], v[78:81], v[190:193], v[14:17]
	s_add_u32 s28, s52, 0x200080
	s_addc_u32 s29, s53, 0
	s_add_i32 s38, s39, s60
	s_mov_b32 m0, s38
	s_nop 0
	global_load_lds_dwordx4 v0, s[28:29]
	s_add_i32 m0, s38, 0x2000
	s_nop 0
	global_load_lds_dwordx4 v146, s[28:29]
	v_mfma_f32_16x16x32_bf16 v[54:57], v[194:197], v[152:155], v[54:57]
	v_mfma_f32_16x16x32_bf16 v[50:53], v[202:205], v[152:155], v[50:53]
	v_mfma_f32_16x16x32_bf16 v[38:41], v[194:197], v[170:173], v[38:41]
	v_mfma_f32_16x16x32_bf16 v[34:37], v[202:205], v[170:173], v[34:37]
	v_mfma_f32_16x16x32_bf16 v[18:21], v[194:197], v[178:181], v[18:21]
	v_mfma_f32_16x16x32_bf16 v[10:13], v[202:205], v[178:181], v[10:13]
	v_mfma_f32_16x16x32_bf16 v[6:9], v[194:197], v[186:189], v[6:9]
	v_mfma_f32_16x16x32_bf16 v[2:5], v[202:205], v[186:189], v[2:5]
	v_mfma_f32_16x16x32_bf16 v[54:57], v[198:201], v[166:169], v[54:57]
	v_mfma_f32_16x16x32_bf16 v[50:53], v[210:213], v[166:169], v[50:53]
	v_mfma_f32_16x16x32_bf16 v[38:41], v[198:201], v[174:177], v[38:41]
	v_mfma_f32_16x16x32_bf16 v[34:37], v[210:213], v[174:177], v[34:37]
	v_mfma_f32_16x16x32_bf16 v[18:21], v[198:201], v[182:185], v[18:21]
	v_mfma_f32_16x16x32_bf16 v[10:13], v[210:213], v[182:185], v[10:13]
	v_mfma_f32_16x16x32_bf16 v[6:9], v[198:201], v[190:193], v[6:9]
	v_mfma_f32_16x16x32_bf16 v[2:5], v[210:213], v[190:193], v[2:5]
	s_add_i32 s75, s75, 2
	s_add_u32 s73, s73, 0x100
	s_addc_u32 s74, s74, 0
	s_mov_b64 s[28:29], s[50:51]
	s_add_u32 s50, s28, 0x100
	s_addc_u32 s51, s29, 0
	s_cmpk_eq_i32 s75, 0x7c
	s_cselect_b32 s55, s27, s51
	s_cselect_b32 s54, s71, s50
	s_cselect_b32 s53, s25, s74
	s_cselect_b32 s52, s72, s73
	s_cmpk_gt_u32 s75, 0x7d
	s_barrier
	s_cbranch_scc0 .LBB0_44
	s_cmp_lt_i32 s8, 64
	s_cselect_b64 s[50:51], -1, 0
	s_cmp_gt_i32 s8, 63
	s_cbranch_scc0 .LBB0_35
	s_mov_b64 s[52:53], 0x18000
	s_mov_b64 s[28:29], s[46:47]
	s_branch .LBB0_36

; #define PG8_STAGE(bufoff, gbase, voff) do { _Pragma("unroll") for (int _i = 0; _i < 2; ++_i) \
;         __builtin_amdgcn_global_load_lds((const unsigned*)((const char*)(gbase) + (voff)[_i]), (LAS unsigned*)(lds + (bufoff) + ldsw + _i * 8192), 16, 0, 0); } while (0)
; #define PG8_LDA(dst, b, h) do { _Pragma("unroll") for (int m = 0; m < 4; ++m) _Pragma("unroll") for (int k = 0; k < 2; ++k) dst[m][k] = *(const LAS bf16x8*)(lds + PG8_SA(b, h) + aoff + m * 2048 + k * 1024); } while (0)
; #define PG8_LDB(dst, b, h) do { _Pragma("unroll") for (int n = 0; n < 2; ++n) _Pragma("unroll") for (int k = 0; k < 2; ++k) dst[n][k] = *(const LAS bf16x8*)(lds + PG8_SB(b, h) + boff + n * 2048 + k * 1024); } while (0)
; #define PG8_SCHED __builtin_amdgcn_sched_barrier(0)
; template <class Epi, class Sched>
; __device__ __forceinline__ void gemm_phase(LAS unsigned char* lds, const Gemm g, const Sched& S, const Epi& E) {
;     ...
;         const bool has_next = S.next(ui + 1, nxt);
;         const char* nA = has_next ? (const char*)g.A + (size_t)nxt.pm * tstep + (size_t)nxt.ks * sstep : cA; const char* nB = has_next ? (const char*)g.Bt + (size_t)nxt.pn * tstep + (size_t)nxt.ks * sstep : cB;
;         for (int t = 0; t < nt; t += 2) {
;             const bool last = (t == nt - 2);
;             const char* a1 = cA + (size_t)(t + 1) * kstep;
;             const char* a2 = last ? nA : cA + (size_t)(t + 2) * kstep; const char* b2 = last ? nB : cB + (size_t)(t + 2) * kstep;
;             const char* a3 = a2 + kstep; const char* b3 = b2 + kstep;
;             PG8_LDB(B0, 0, 0); PG8_SCHED; PG8_LDA(At, 0, 0); PG8_STAGE(PG8_SA(1, 1), a1 + hstep, voffA);
;     ...
; #pragma unroll
;         for (int a = 0; a < 2; ++a)
; #pragma unroll
;             for (int b = 0; b < 2; ++b)
; #pragma unroll
;                 for (int m = 0; m < 4; ++m)
; #pragma unroll
;                     for (int n = 0; n < 2; ++n) acc[a][b][m][n] = (f32x4){0.f, 0.f, 0.f, 0.f};
;         cur = nxt; cA = nA; cB = nB; ++ui;
.LBB0_57:
	s_ashr_i32 s43, s42, 31
	s_lshl_b64 s[38:39], s[42:43], 22
	s_add_u32 s11, s61, s38
	s_addc_u32 s41, s62, s39
	s_ashr_i32 s29, s28, 31
	s_lshl_b64 s[38:39], s[28:29], 12
	s_add_u32 s46, s11, s38
	s_addc_u32 s47, s41, s39
	s_and_b64 s[48:49], s[54:55], exec
	s_cselect_b32 s11, s47, s51
	s_cselect_b32 s29, s46, s50
	s_ashr_i32 s41, s40, 31
	s_lshl_b64 s[48:49], s[40:41], 22
	s_add_u32 s41, s13, s48
	s_addc_u32 s43, s30, s49
	s_add_u32 s48, s41, s38
	s_addc_u32 s49, s43, s39
	s_and_b64 s[38:39], s[54:55], exec
	s_cselect_b32 s41, s49, s53
	s_cselect_b32 s43, s48, s52
	s_add_u32 s69, s52, 0x100
	v_mov_b32_e32 v2, 0
	s_addc_u32 s70, s53, 0
	s_mov_b32 s71, -2
	v_mov_b32_e32 v3, v2
	v_mov_b32_e32 v4, v2
	v_mov_b32_e32 v5, v2
	v_mov_b32_e32 v6, v2
	v_mov_b32_e32 v7, v2
	v_mov_b32_e32 v8, v2
	v_mov_b32_e32 v9, v2
	v_mov_b32_e32 v10, v2
	v_mov_b32_e32 v11, v2
	v_mov_b32_e32 v12, v2
	v_mov_b32_e32 v13, v2
	v_mov_b32_e32 v14, v2
	v_mov_b32_e32 v15, v2
	v_mov_b32_e32 v16, v2
	v_mov_b32_e32 v17, v2
	s_waitcnt vmcnt(0)
	v_mov_b32_e32 v26, v2
	v_mov_b32_e32 v27, v2
	v_mov_b32_e32 v28, v2
	v_mov_b32_e32 v29, v2
	v_mov_b32_e32 v30, v2
	v_mov_b32_e32 v31, v2
	v_mov_b32_e32 v32, v2
	v_mov_b32_e32 v33, v2
	v_mov_b32_e32 v42, v2
	v_mov_b32_e32 v43, v2
	v_mov_b32_e32 v44, v2
	v_mov_b32_e32 v45, v2
	v_mov_b32_e32 v46, v2
	v_mov_b32_e32 v47, v2
	v_mov_b32_e32 v48, v2
	v_mov_b32_e32 v49, v2
	v_mov_b32_e32 v18, v2
	v_mov_b32_e32 v19, v2
	v_mov_b32_e32 v20, v2
	v_mov_b32_e32 v21, v2
	v_mov_b32_e32 v22, v2
	v_mov_b32_e32 v23, v2
	v_mov_b32_e32 v24, v2
	v_mov_b32_e32 v25, v2
	v_mov_b32_e32 v34, v2
	v_mov_b32_e32 v35, v2
	v_mov_b32_e32 v36, v2
	v_mov_b32_e32 v37, v2
	v_mov_b32_e32 v38, v2
	v_mov_b32_e32 v39, v2
	v_mov_b32_e32 v40, v2
	v_mov_b32_e32 v41, v2
	v_mov_b32_e32 v50, v2
	v_mov_b32_e32 v51, v2
	v_mov_b32_e32 v52, v2
	v_mov_b32_e32 v53, v2
	v_mov_b32_e32 v54, v2
	v_mov_b32_e32 v55, v2
	v_mov_b32_e32 v56, v2
	v_mov_b32_e32 v57, v2
	v_mov_b32_e32 v58, v2
	v_mov_b32_e32 v59, v2
	v_mov_b32_e32 v60, v2
	v_mov_b32_e32 v61, v2
	v_mov_b32_e32 v62, v2
	v_mov_b32_e32 v63, v2
	v_mov_b32_e32 v64, v2
	v_mov_b32_e32 v65, v2
	v_mov_b32_e32 v66, v2
	v_mov_b32_e32 v67, v2
	v_mov_b32_e32 v68, v2
	v_mov_b32_e32 v69, v2
	v_mov_b32_e32 v70, v2
	v_mov_b32_e32 v71, v2
	v_mov_b32_e32 v72, v2
	v_mov_b32_e32 v73, v2
	v_mov_b32_e32 v74, v2
	v_mov_b32_e32 v75, v2
	v_mov_b32_e32 v76, v2
	v_mov_b32_e32 v77, v2
	v_mov_b32_e32 v78, v2
	v_mov_b32_e32 v79, v2
	v_mov_b32_e32 v80, v2
	v_mov_b32_e32 v81, v2
	v_mov_b32_e32 v86, v2
	v_mov_b32_e32 v87, v2
	v_mov_b32_e32 v88, v2
	v_mov_b32_e32 v89, v2
	v_mov_b32_e32 v94, v2
	v_mov_b32_e32 v95, v2
	v_mov_b32_e32 v96, v2
	v_mov_b32_e32 v97, v2
	v_mov_b32_e32 v102, v2
	v_mov_b32_e32 v103, v2
	v_mov_b32_e32 v104, v2
	v_mov_b32_e32 v105, v2
	v_mov_b32_e32 v110, v2
	v_mov_b32_e32 v111, v2
	v_mov_b32_e32 v112, v2
	v_mov_b32_e32 v113, v2
	v_mov_b32_e32 v82, v2
	v_mov_b32_e32 v83, v2
	v_mov_b32_e32 v84, v2
	v_mov_b32_e32 v85, v2
	v_mov_b32_e32 v90, v2
	v_mov_b32_e32 v91, v2
	v_mov_b32_e32 v92, v2
	v_mov_b32_e32 v93, v2
	v_mov_b32_e32 v98, v2
	v_mov_b32_e32 v99, v2
	v_mov_b32_e32 v100, v2
	v_mov_b32_e32 v101, v2
	v_mov_b32_e32 v106, v2
	v_mov_b32_e32 v107, v2
	v_mov_b32_e32 v108, v2
	v_mov_b32_e32 v109, v2
	v_mov_b32_e32 v114, v2
	v_mov_b32_e32 v115, v2
	v_mov_b32_e32 v116, v2
	v_mov_b32_e32 v117, v2
	v_mov_b32_e32 v118, v2
	v_mov_b32_e32 v119, v2
	v_mov_b32_e32 v120, v2
	v_mov_b32_e32 v121, v2
	v_mov_b32_e32 v122, v2
	v_mov_b32_e32 v123, v2
	v_mov_b32_e32 v124, v2
	v_mov_b32_e32 v125, v2
	v_mov_b32_e32 v126, v2
	v_mov_b32_e32 v127, v2
	v_mov_b32_e32 v128, v2
	v_mov_b32_e32 v129, v2
	s_add_u32 s52, s50, 0x100
	s_addc_u32 s53, s51, 0
	s_cmp_eq_u32 s71, 28
	s_cselect_b32 s57, s11, s53
	s_cselect_b32 s56, s29, s52
	s_cselect_b32 s55, s41, s70
	s_cselect_b32 s54, s43, s69
.LBB0_58:
	s_add_i32 m0, s25, 0xc000
	ds_read_b128 v[140:143], v226
	global_load_lds_dwordx4 v134, s[50:51]
	s_add_i32 m0, s25, 0xe000
	ds_read_b128 v[144:147], v226 offset:1024
	global_load_lds_dwordx4 v132, s[50:51]
	s_add_i32 s38, 0, 0x10000
	ds_read_b128 v[148:151], v226 offset:2048
	ds_read_b128 v[152:155], v226 offset:3072
	ds_read_b128 v[160:163], v139
	ds_read_b128 v[164:167], v139 offset:1024
	ds_read_b128 v[168:171], v139 offset:2048
	ds_read_b128 v[172:175], v139 offset:3072
	ds_read_b128 v[176:179], v139 offset:4096
	ds_read_b128 v[180:183], v139 offset:5120
	ds_read_b128 v[184:187], v139 offset:6144
	ds_read_b128 v[188:191], v139 offset:7168
	s_add_i32 s50, 0, 0x14000
	ds_read_b128 v[192:195], v226 offset:16384
	ds_read_b128 v[196:199], v226 offset:17408
	ds_read_b128 v[200:203], v226 offset:18432
	ds_read_b128 v[204:207], v226 offset:19456
	s_waitcnt lgkmcnt(4)
	s_barrier
; #define PG8_STAGE(bufoff, gbase, voff) do { _Pragma("unroll") for (int _i = 0; _i < 2; ++_i) \
;         __builtin_amdgcn_global_load_lds((const unsigned*)((const char*)(gbase) + (voff)[_i]), (LAS unsigned*)(lds + (bufoff) + ldsw + _i * 8192), 16, 0, 0); } while (0)
; #define PG8_LDA(dst, b, h) do { _Pragma("unroll") for (int m = 0; m < 4; ++m) _Pragma("unroll") for (int k = 0; k < 2; ++k) dst[m][k] = *(const LAS bf16x8*)(lds + PG8_SA(b, h) + aoff + m * 2048 + k * 1024); } while (0)
; #define PG8_LDB(dst, b, h) do { _Pragma("unroll") for (int n = 0; n < 2; ++n) _Pragma("unroll") for (int k = 0; k < 2; ++k) dst[n][k] = *(const LAS bf16x8*)(lds + PG8_SB(b, h) + boff + n * 2048 + k * 1024); } while (0)
; #define PG8_MMA(ai, bj, At, Bt) do { __builtin_amdgcn_s_setprio(1); _Pragma("unroll") for (int m = 0; m < 4; ++m) _Pragma("unroll") for (int n = 0; n < 2; ++n) _Pragma("unroll") for (int k = 0; k < 2; ++k) \
;         acc[ai][bj][m][n] = __builtin_amdgcn_mfma_f32_16x16x32_bf16(Bt[n][k], At[m][k], acc[ai][bj][m][n], 0, 0, 0); __builtin_amdgcn_s_setprio(0); } while (0)
; #define PG8_WAIT_V(n) asm volatile("s_waitcnt vmcnt(" #n ")" ::: "memory")
; #define PG8_WAIT_L(n) asm volatile("s_waitcnt lgkmcnt(" #n ")" ::: "memory")
; #define PG8_BAR __builtin_amdgcn_s_barrier()
; #define PG8_SCHED __builtin_amdgcn_sched_barrier(0)
; template <class Epi, class Sched>
; __device__ __forceinline__ void gemm_phase(LAS unsigned char* lds, const Gemm g, const Sched& S, const Epi& E) {
;     ...
;             PG8_LDB(B0, 0, 0); PG8_SCHED; PG8_LDA(At, 0, 0); PG8_STAGE(PG8_SA(1, 1), a1 + hstep, voffA);
;             PG8_WAIT_L(8); PG8_BAR; PG8_WAIT_L(0); PG8_MMA(0, 0, At, B0); PG8_BAR; PG8_SCHED;
;             PG8_LDB(B1, 0, 1); PG8_STAGE(PG8_SB(0, 0), b2, voffB);
;             PG8_BAR; PG8_WAIT_L(0); PG8_MMA(0, 1, At, B1); PG8_BAR;
;             PG8_LDA(At, 0, 1); PG8_STAGE(PG8_SA(0, 0), a2, voffA);
;             PG8_BAR; PG8_WAIT_L(0); PG8_MMA(1, 0, At, B0); PG8_BAR; PG8_SCHED;
;             PG8_STAGE(PG8_SB(0, 1), b2 + hstep, voffB);
;             PG8_WAIT_V(6); PG8_BAR; PG8_MMA(1, 1, At, B1); PG8_BAR;
	s_waitcnt lgkmcnt(0)
	v_mfma_f32_16x16x32_bf16 v[126:129], v[140:143], v[160:163], v[126:129]
	v_mfma_f32_16x16x32_bf16 v[122:125], v[148:151], v[160:163], v[122:125]
	v_mfma_f32_16x16x32_bf16 v[118:121], v[140:143], v[168:171], v[118:121]
	v_mfma_f32_16x16x32_bf16 v[114:117], v[148:151], v[168:171], v[114:117]
	v_mfma_f32_16x16x32_bf16 v[106:109], v[140:143], v[176:179], v[106:109]
	v_mfma_f32_16x16x32_bf16 v[98:101], v[148:151], v[176:179], v[98:101]
	v_mfma_f32_16x16x32_bf16 v[90:93], v[140:143], v[184:187], v[90:93]
	v_mfma_f32_16x16x32_bf16 v[82:85], v[148:151], v[184:187], v[82:85]
	v_mfma_f32_16x16x32_bf16 v[126:129], v[144:147], v[164:167], v[126:129]
	v_mfma_f32_16x16x32_bf16 v[122:125], v[152:155], v[164:167], v[122:125]
	v_mfma_f32_16x16x32_bf16 v[118:121], v[144:147], v[172:175], v[118:121]
	v_mfma_f32_16x16x32_bf16 v[114:117], v[152:155], v[172:175], v[114:117]
	v_mfma_f32_16x16x32_bf16 v[106:109], v[144:147], v[180:183], v[106:109]
	v_mfma_f32_16x16x32_bf16 v[98:101], v[152:155], v[180:183], v[98:101]
	v_mfma_f32_16x16x32_bf16 v[90:93], v[144:147], v[188:191], v[90:93]
	v_mfma_f32_16x16x32_bf16 v[82:85], v[152:155], v[188:191], v[82:85]
	v_mfma_f32_16x16x32_bf16 v[110:113], v[192:195], v[160:163], v[110:113]
	v_mfma_f32_16x16x32_bf16 v[102:105], v[200:203], v[160:163], v[102:105]
	v_mfma_f32_16x16x32_bf16 v[94:97], v[192:195], v[168:171], v[94:97]
	v_mfma_f32_16x16x32_bf16 v[86:89], v[200:203], v[168:171], v[86:89]
	v_mfma_f32_16x16x32_bf16 v[78:81], v[192:195], v[176:179], v[78:81]
	v_mfma_f32_16x16x32_bf16 v[74:77], v[200:203], v[176:179], v[74:77]
	v_mfma_f32_16x16x32_bf16 v[70:73], v[192:195], v[184:187], v[70:73]
	v_mfma_f32_16x16x32_bf16 v[66:69], v[200:203], v[184:187], v[66:69]
	v_mfma_f32_16x16x32_bf16 v[110:113], v[196:199], v[164:167], v[110:113]
	v_mfma_f32_16x16x32_bf16 v[102:105], v[204:207], v[164:167], v[102:105]
	v_mfma_f32_16x16x32_bf16 v[94:97], v[196:199], v[172:175], v[94:97]
	v_mfma_f32_16x16x32_bf16 v[86:89], v[204:207], v[172:175], v[86:89]
	v_mfma_f32_16x16x32_bf16 v[78:81], v[196:199], v[180:183], v[78:81]
	v_mfma_f32_16x16x32_bf16 v[74:77], v[204:207], v[180:183], v[74:77]
	v_mfma_f32_16x16x32_bf16 v[70:73], v[196:199], v[188:191], v[70:73]
	v_mfma_f32_16x16x32_bf16 v[66:69], v[204:207], v[188:191], v[66:69]
	s_barrier
	s_add_i32 s38, s38, s63
	s_mov_b32 m0, s38
	ds_read_b128 v[160:163], v139 offset:16384
	global_load_lds_dwordx4 v0, s[54:55]
	s_add_i32 m0, s38, 0x2000
	ds_read_b128 v[164:167], v139 offset:17408
	global_load_lds_dwordx4 v130, s[54:55]
	s_mov_b32 m0, s25
	ds_read_b128 v[168:171], v139 offset:18432
	global_load_lds_dwordx4 v0, s[56:57]
	s_mov_b32 m0, s27
	ds_read_b128 v[172:175], v139 offset:19456
	global_load_lds_dwordx4 v130, s[56:57]
	ds_read_b128 v[176:179], v139 offset:20480
	ds_read_b128 v[180:183], v139 offset:21504
	ds_read_b128 v[184:187], v139 offset:22528
	ds_read_b128 v[188:191], v139 offset:23552
	s_waitcnt vmcnt(4)
	s_waitcnt lgkmcnt(0)
	s_barrier
	v_mfma_f32_16x16x32_bf16 v[62:65], v[140:143], v[160:163], v[62:65]
	v_mfma_f32_16x16x32_bf16 v[58:61], v[148:151], v[160:163], v[58:61]
	v_mfma_f32_16x16x32_bf16 v[54:57], v[140:143], v[168:171], v[54:57]
	v_mfma_f32_16x16x32_bf16 v[50:53], v[148:151], v[168:171], v[50:53]
	v_mfma_f32_16x16x32_bf16 v[38:41], v[140:143], v[176:179], v[38:41]
	v_mfma_f32_16x16x32_bf16 v[34:37], v[148:151], v[176:179], v[34:37]
	v_mfma_f32_16x16x32_bf16 v[22:25], v[140:143], v[184:187], v[22:25]
	v_mfma_f32_16x16x32_bf16 v[18:21], v[148:151], v[184:187], v[18:21]
	v_mfma_f32_16x16x32_bf16 v[62:65], v[144:147], v[164:167], v[62:65]
	v_mfma_f32_16x16x32_bf16 v[58:61], v[152:155], v[164:167], v[58:61]
	v_mfma_f32_16x16x32_bf16 v[54:57], v[144:147], v[172:175], v[54:57]
	v_mfma_f32_16x16x32_bf16 v[50:53], v[152:155], v[172:175], v[50:53]
	v_mfma_f32_16x16x32_bf16 v[38:41], v[144:147], v[180:183], v[38:41]
	v_mfma_f32_16x16x32_bf16 v[34:37], v[152:155], v[180:183], v[34:37]
	v_mfma_f32_16x16x32_bf16 v[22:25], v[144:147], v[188:191], v[22:25]
	v_mfma_f32_16x16x32_bf16 v[18:21], v[152:155], v[188:191], v[18:21]
	v_mfma_f32_16x16x32_bf16 v[46:49], v[192:195], v[160:163], v[46:49]
	v_mfma_f32_16x16x32_bf16 v[42:45], v[200:203], v[160:163], v[42:45]
	v_mfma_f32_16x16x32_bf16 v[30:33], v[192:195], v[168:171], v[30:33]
	v_mfma_f32_16x16x32_bf16 v[26:29], v[200:203], v[168:171], v[26:29]
	v_mfma_f32_16x16x32_bf16 v[14:17], v[192:195], v[176:179], v[14:17]
	v_mfma_f32_16x16x32_bf16 v[10:13], v[200:203], v[176:179], v[10:13]
	v_mfma_f32_16x16x32_bf16 v[6:9], v[192:195], v[184:187], v[6:9]
	v_mfma_f32_16x16x32_bf16 v[2:5], v[200:203], v[184:187], v[2:5]
	v_mfma_f32_16x16x32_bf16 v[46:49], v[196:199], v[164:167], v[46:49]
	v_mfma_f32_16x16x32_bf16 v[42:45], v[204:207], v[164:167], v[42:45]
	v_mfma_f32_16x16x32_bf16 v[30:33], v[196:199], v[172:175], v[30:33]
	v_mfma_f32_16x16x32_bf16 v[26:29], v[204:207], v[172:175], v[26:29]
	v_mfma_f32_16x16x32_bf16 v[14:17], v[196:199], v[180:183], v[14:17]
	v_mfma_f32_16x16x32_bf16 v[10:13], v[204:207], v[180:183], v[10:13]
	v_mfma_f32_16x16x32_bf16 v[6:9], v[196:199], v[188:191], v[6:9]
	v_mfma_f32_16x16x32_bf16 v[2:5], v[204:207], v[188:191], v[2:5]
	s_barrier
; #define PG8_STAGE(bufoff, gbase, voff) do { _Pragma("unroll") for (int _i = 0; _i < 2; ++_i) \
;         __builtin_amdgcn_global_load_lds((const unsigned*)((const char*)(gbase) + (voff)[_i]), (LAS unsigned*)(lds + (bufoff) + ldsw + _i * 8192), 16, 0, 0); } while (0)
; #define PG8_LDA(dst, b, h) do { _Pragma("unroll") for (int m = 0; m < 4; ++m) _Pragma("unroll") for (int k = 0; k < 2; ++k) dst[m][k] = *(const LAS bf16x8*)(lds + PG8_SA(b, h) + aoff + m * 2048 + k * 1024); } while (0)
; #define PG8_LDB(dst, b, h) do { _Pragma("unroll") for (int n = 0; n < 2; ++n) _Pragma("unroll") for (int k = 0; k < 2; ++k) dst[n][k] = *(const LAS bf16x8*)(lds + PG8_SB(b, h) + boff + n * 2048 + k * 1024); } while (0)
; #define PG8_MMA(ai, bj, At, Bt) do { __builtin_amdgcn_s_setprio(1); _Pragma("unroll") for (int m = 0; m < 4; ++m) _Pragma("unroll") for (int n = 0; n < 2; ++n) _Pragma("unroll") for (int k = 0; k < 2; ++k) \
;         acc[ai][bj][m][n] = __builtin_amdgcn_mfma_f32_16x16x32_bf16(Bt[n][k], At[m][k], acc[ai][bj][m][n], 0, 0, 0); __builtin_amdgcn_s_setprio(0); } while (0)
; #define PG8_WAIT_V(n) asm volatile("s_waitcnt vmcnt(" #n ")" ::: "memory")
; #define PG8_WAIT_L(n) asm volatile("s_waitcnt lgkmcnt(" #n ")" ::: "memory")
; #define PG8_BAR __builtin_amdgcn_s_barrier()
; #define PG8_SCHED __builtin_amdgcn_sched_barrier(0)
; template <class Epi, class Sched>
; __device__ __forceinline__ void gemm_phase(LAS unsigned char* lds, const Gemm g, const Sched& S, const Epi& E) {
;     ...
;             PG8_WAIT_V(6); PG8_BAR; PG8_MMA(1, 1, At, B1); PG8_BAR;
;             PG8_LDB(B0, 1, 0); PG8_SCHED; PG8_LDA(At, 1, 0); PG8_STAGE(PG8_SA(0, 1), a2 + hstep, voffA);
;             PG8_WAIT_L(8); PG8_BAR; PG8_WAIT_L(0); PG8_MMA(0, 0, At, B0); PG8_BAR; PG8_SCHED;
;             PG8_LDB(B1, 1, 1); PG8_STAGE(PG8_SB(1, 0), b3, voffB);
;             PG8_BAR; PG8_WAIT_L(0); PG8_MMA(0, 1, At, B1); PG8_BAR;
;             PG8_LDA(At, 1, 1); PG8_STAGE(PG8_SA(1, 0), a3, voffA);
;             PG8_BAR; PG8_WAIT_L(0); PG8_MMA(1, 0, At, B0); PG8_BAR; PG8_SCHED;
	s_add_u32 s38, s54, 0x200000
	s_addc_u32 s39, s55, 0
	s_add_i32 s50, s50, s63
	s_mov_b32 m0, s50
	ds_read_b128 v[140:143], v226 offset:32768
	global_load_lds_dwordx4 v0, s[38:39]
	s_add_i32 m0, s50, 0x2000
	ds_read_b128 v[144:147], v226 offset:33792
	global_load_lds_dwordx4 v130, s[38:39]
	s_add_u32 s38, s56, 0x200000
	s_addc_u32 s39, s57, 0
	s_mov_b32 m0, s64
	ds_read_b128 v[148:151], v226 offset:34816
	global_load_lds_dwordx4 v0, s[38:39]
	s_mov_b32 m0, s65
	ds_read_b128 v[152:155], v226 offset:35840
	global_load_lds_dwordx4 v130, s[38:39]
	s_add_i32 s50, 0, 0x18000
	ds_read_b128 v[160:163], v139 offset:32768
	ds_read_b128 v[164:167], v139 offset:33792
	ds_read_b128 v[168:171], v139 offset:34816
	ds_read_b128 v[172:175], v139 offset:35840
	ds_read_b128 v[176:179], v139 offset:36864
	ds_read_b128 v[180:183], v139 offset:37888
	ds_read_b128 v[184:187], v139 offset:38912
	ds_read_b128 v[188:191], v139 offset:39936
	s_add_i32 s51, 0, 0x1c000
	ds_read_b128 v[192:195], v226 offset:49152
	ds_read_b128 v[196:199], v226 offset:50176
	ds_read_b128 v[200:203], v226 offset:51200
	ds_read_b128 v[204:207], v226 offset:52224
	s_waitcnt lgkmcnt(4)
	s_barrier
	s_waitcnt lgkmcnt(0)
	v_mfma_f32_16x16x32_bf16 v[126:129], v[140:143], v[160:163], v[126:129]
	v_mfma_f32_16x16x32_bf16 v[122:125], v[148:151], v[160:163], v[122:125]
	v_mfma_f32_16x16x32_bf16 v[118:121], v[140:143], v[168:171], v[118:121]
	v_mfma_f32_16x16x32_bf16 v[114:117], v[148:151], v[168:171], v[114:117]
	v_mfma_f32_16x16x32_bf16 v[106:109], v[140:143], v[176:179], v[106:109]
	v_mfma_f32_16x16x32_bf16 v[98:101], v[148:151], v[176:179], v[98:101]
	v_mfma_f32_16x16x32_bf16 v[90:93], v[140:143], v[184:187], v[90:93]
	v_mfma_f32_16x16x32_bf16 v[82:85], v[148:151], v[184:187], v[82:85]
	v_mfma_f32_16x16x32_bf16 v[126:129], v[144:147], v[164:167], v[126:129]
	v_mfma_f32_16x16x32_bf16 v[122:125], v[152:155], v[164:167], v[122:125]
	v_mfma_f32_16x16x32_bf16 v[118:121], v[144:147], v[172:175], v[118:121]
	v_mfma_f32_16x16x32_bf16 v[114:117], v[152:155], v[172:175], v[114:117]
	v_mfma_f32_16x16x32_bf16 v[106:109], v[144:147], v[180:183], v[106:109]
	v_mfma_f32_16x16x32_bf16 v[98:101], v[152:155], v[180:183], v[98:101]
	v_mfma_f32_16x16x32_bf16 v[90:93], v[144:147], v[188:191], v[90:93]
	v_mfma_f32_16x16x32_bf16 v[82:85], v[152:155], v[188:191], v[82:85]
	v_mfma_f32_16x16x32_bf16 v[110:113], v[192:195], v[160:163], v[110:113]
	v_mfma_f32_16x16x32_bf16 v[102:105], v[200:203], v[160:163], v[102:105]
	v_mfma_f32_16x16x32_bf16 v[94:97], v[192:195], v[168:171], v[94:97]
	v_mfma_f32_16x16x32_bf16 v[86:89], v[200:203], v[168:171], v[86:89]
	v_mfma_f32_16x16x32_bf16 v[78:81], v[192:195], v[176:179], v[78:81]
	v_mfma_f32_16x16x32_bf16 v[74:77], v[200:203], v[176:179], v[74:77]
	v_mfma_f32_16x16x32_bf16 v[70:73], v[192:195], v[184:187], v[70:73]
	v_mfma_f32_16x16x32_bf16 v[66:69], v[200:203], v[184:187], v[66:69]
	v_mfma_f32_16x16x32_bf16 v[110:113], v[196:199], v[164:167], v[110:113]
	v_mfma_f32_16x16x32_bf16 v[102:105], v[204:207], v[164:167], v[102:105]
	v_mfma_f32_16x16x32_bf16 v[94:97], v[196:199], v[172:175], v[94:97]
	v_mfma_f32_16x16x32_bf16 v[86:89], v[204:207], v[172:175], v[86:89]
	v_mfma_f32_16x16x32_bf16 v[78:81], v[196:199], v[180:183], v[78:81]
	v_mfma_f32_16x16x32_bf16 v[74:77], v[204:207], v[180:183], v[74:77]
	v_mfma_f32_16x16x32_bf16 v[70:73], v[196:199], v[188:191], v[70:73]
	v_mfma_f32_16x16x32_bf16 v[66:69], v[204:207], v[188:191], v[66:69]
	s_barrier
	s_add_i32 s38, s50, s63
	s_add_u32 s100, s54, s36
	s_addc_u32 s101, s55, s37
	s_mov_b32 m0, s38
	ds_read_b128 v[160:163], v139 offset:49152
	global_load_lds_dwordx4 v0, s[100:101]
	s_add_i32 m0, s38, 0x2000
	ds_read_b128 v[164:167], v139 offset:50176
	global_load_lds_dwordx4 v130, s[100:101]
	s_mov_b32 m0, s66
	s_add_u32 s100, s56, s36
	s_addc_u32 s101, s57, s37
	global_load_lds_dwordx4 v0, s[100:101]
	s_mov_b32 m0, s67
	ds_read_b128 v[168:171], v139 offset:51200
	global_load_lds_dwordx4 v130, s[100:101]
	ds_read_b128 v[172:175], v139 offset:52224
	ds_read_b128 v[176:179], v139 offset:53248
	ds_read_b128 v[180:183], v139 offset:54272
	ds_read_b128 v[184:187], v139 offset:55296
	ds_read_b128 v[188:191], v139 offset:56320
	s_waitcnt vmcnt(4)
	s_waitcnt lgkmcnt(0)
	s_barrier
; #define PG8_STAGE(bufoff, gbase, voff) do { _Pragma("unroll") for (int _i = 0; _i < 2; ++_i) \
;         __builtin_amdgcn_global_load_lds((const unsigned*)((const char*)(gbase) + (voff)[_i]), (LAS unsigned*)(lds + (bufoff) + ldsw + _i * 8192), 16, 0, 0); } while (0)
; #define PG8_MMA(ai, bj, At, Bt) do { __builtin_amdgcn_s_setprio(1); _Pragma("unroll") for (int m = 0; m < 4; ++m) _Pragma("unroll") for (int n = 0; n < 2; ++n) _Pragma("unroll") for (int k = 0; k < 2; ++k) \
;         acc[ai][bj][m][n] = __builtin_amdgcn_mfma_f32_16x16x32_bf16(Bt[n][k], At[m][k], acc[ai][bj][m][n], 0, 0, 0); __builtin_amdgcn_s_setprio(0); } while (0)
; #define PG8_WAIT_V(n) asm volatile("s_waitcnt vmcnt(" #n ")" ::: "memory")
; #define PG8_WAIT_L(n) asm volatile("s_waitcnt lgkmcnt(" #n ")" ::: "memory")
; #define PG8_BAR __builtin_amdgcn_s_barrier()
; #define PG8_SCHED __builtin_amdgcn_sched_barrier(0)
;     __device__ __forceinline__ void operator()(const f32x4 (&acc)[2][2][4][2], const Unit& u, int wr, int wc, int fr, int fq) const {
;         const int row0 = u.pm * BM + wr * 64 + fr, col0 = u.pn * BM + wc * 32 + 4 * fq;
;         float* base = part + (size_t)u.ks * Mp * ldc;
; #pragma unroll
;         for (int ai = 0; ai < 2; ++ai)
; #pragma unroll
;             for (int m = 0; m < 4; ++m) { float* rowp = base + (size_t)(row0 + ai * HALF + m * 16) * ldc + col0;
; #pragma unroll
;                 for (int bj = 0; bj < 2; ++bj)
; #pragma unroll
;                     for (int n = 0; n < 2; ++n) *(f32x4*)(rowp + bj * HALF + n * 16) = acc[ai][bj][m][n]; }
;     }
; template <class Epi, class Sched>
; __device__ __forceinline__ void gemm_phase(LAS unsigned char* lds, const Gemm g, const Sched& S, const Epi& E) {
;     ...
;             PG8_BAR; PG8_WAIT_L(0); PG8_MMA(1, 0, At, B0); PG8_BAR; PG8_SCHED;
;             PG8_STAGE(PG8_SB(1, 1), b3 + hstep, voffB);
;             PG8_WAIT_V(6); PG8_BAR; PG8_MMA(1, 1, At, B1); PG8_BAR;
	v_mfma_f32_16x16x32_bf16 v[62:65], v[140:143], v[160:163], v[62:65]
	v_mfma_f32_16x16x32_bf16 v[58:61], v[148:151], v[160:163], v[58:61]
	v_mfma_f32_16x16x32_bf16 v[54:57], v[140:143], v[168:171], v[54:57]
	v_mfma_f32_16x16x32_bf16 v[50:53], v[148:151], v[168:171], v[50:53]
	v_mfma_f32_16x16x32_bf16 v[38:41], v[140:143], v[176:179], v[38:41]
	v_mfma_f32_16x16x32_bf16 v[34:37], v[148:151], v[176:179], v[34:37]
	v_mfma_f32_16x16x32_bf16 v[22:25], v[140:143], v[184:187], v[22:25]
	v_mfma_f32_16x16x32_bf16 v[18:21], v[148:151], v[184:187], v[18:21]
	v_mfma_f32_16x16x32_bf16 v[62:65], v[144:147], v[164:167], v[62:65]
	v_mfma_f32_16x16x32_bf16 v[58:61], v[152:155], v[164:167], v[58:61]
	v_mfma_f32_16x16x32_bf16 v[54:57], v[144:147], v[172:175], v[54:57]
	v_mfma_f32_16x16x32_bf16 v[50:53], v[152:155], v[172:175], v[50:53]
	v_mfma_f32_16x16x32_bf16 v[38:41], v[144:147], v[180:183], v[38:41]
	v_mfma_f32_16x16x32_bf16 v[34:37], v[152:155], v[180:183], v[34:37]
	v_mfma_f32_16x16x32_bf16 v[22:25], v[144:147], v[188:191], v[22:25]
	v_mfma_f32_16x16x32_bf16 v[18:21], v[152:155], v[188:191], v[18:21]
	s_add_u32 s38, s54, 0x200080
	s_addc_u32 s39, s55, 0
	s_add_i32 s50, s51, s63
	s_mov_b32 m0, s50
	s_nop 0
	global_load_lds_dwordx4 v0, s[38:39]
	s_add_i32 m0, s50, 0x2000
	s_nop 0
	global_load_lds_dwordx4 v130, s[38:39]
	v_mfma_f32_16x16x32_bf16 v[46:49], v[192:195], v[160:163], v[46:49]
	v_mfma_f32_16x16x32_bf16 v[42:45], v[200:203], v[160:163], v[42:45]
	v_mfma_f32_16x16x32_bf16 v[30:33], v[192:195], v[168:171], v[30:33]
	v_mfma_f32_16x16x32_bf16 v[26:29], v[200:203], v[168:171], v[26:29]
	v_mfma_f32_16x16x32_bf16 v[14:17], v[192:195], v[176:179], v[14:17]
	v_mfma_f32_16x16x32_bf16 v[10:13], v[200:203], v[176:179], v[10:13]
	v_mfma_f32_16x16x32_bf16 v[6:9], v[192:195], v[184:187], v[6:9]
	v_mfma_f32_16x16x32_bf16 v[2:5], v[200:203], v[184:187], v[2:5]
	v_mfma_f32_16x16x32_bf16 v[46:49], v[196:199], v[164:167], v[46:49]
	v_mfma_f32_16x16x32_bf16 v[42:45], v[204:207], v[164:167], v[42:45]
	v_mfma_f32_16x16x32_bf16 v[30:33], v[196:199], v[172:175], v[30:33]
	v_mfma_f32_16x16x32_bf16 v[26:29], v[204:207], v[172:175], v[26:29]
	v_mfma_f32_16x16x32_bf16 v[14:17], v[196:199], v[180:183], v[14:17]
	v_mfma_f32_16x16x32_bf16 v[10:13], v[204:207], v[180:183], v[10:13]
	v_mfma_f32_16x16x32_bf16 v[6:9], v[196:199], v[188:191], v[6:9]
	v_mfma_f32_16x16x32_bf16 v[2:5], v[204:207], v[188:191], v[2:5]
	s_add_i32 s71, s71, 2
	s_add_u32 s69, s69, 0x100
	s_addc_u32 s70, s70, 0
	s_mov_b64 s[50:51], s[52:53]
	s_add_u32 s52, s50, 0x100
	s_addc_u32 s53, s51, 0
	s_cmp_eq_u32 s71, 28
	s_cselect_b32 s57, s11, s53
	s_cselect_b32 s56, s29, s52
	s_cselect_b32 s55, s41, s70
	s_cselect_b32 s54, s43, s69
	s_cmp_gt_u32 s71, 29
	s_barrier
	s_cbranch_scc0 .LBB0_58
	s_ashr_i32 s11, s10, 31
	s_lshl_b64 s[10:11], s[10:11], 24
	v_lshl_or_b32 v140, s26, 8, v138
	s_add_u32 s10, s8, s10
	v_lshl_add_u32 v142, s24, 8, v136
	s_addc_u32 s11, s9, s11
	v_ashrrev_i32_e32 v141, 31, v140
	v_ashrrev_i32_e32 v143, 31, v142
	v_lshl_add_u64 v[140:141], v[140:141], 2, s[10:11]
	v_lshlrev_b64 v[144:145], 13, v[142:143]
	v_lshl_add_u64 v[144:145], v[140:141], 0, v[144:145]
	global_store_dwordx4 v[144:145], v[126:129], off
	global_store_dwordx4 v[144:145], v[122:125], off offset:64
	global_store_dwordx4 v[144:145], v[110:113], off offset:512
	global_store_dwordx4 v[144:145], v[102:105], off offset:576
	s_mov_b64 s[10:11], 0x100000
	s_mov_b32 s26, s40
	v_or_b32_e32 v102, 16, v142
	v_ashrrev_i32_e32 v103, 31, v102
	v_lshlrev_b64 v[102:103], 13, v[102:103]
	v_lshl_add_u64 v[102:103], v[140:141], 0, v[102:103]
	global_store_dwordx4 v[102:103], v[118:121], off
	global_store_dwordx4 v[102:103], v[114:117], off offset:64
	global_store_dwordx4 v[102:103], v[94:97], off offset:512
	global_store_dwordx4 v[102:103], v[86:89], off offset:576
	s_mov_b32 s24, s42
	s_mov_b64 s[52:53], s[48:49]
	v_or_b32_e32 v86, 32, v142
	v_ashrrev_i32_e32 v87, 31, v86
	v_lshlrev_b64 v[86:87], 13, v[86:87]
	v_lshl_add_u64 v[86:87], v[140:141], 0, v[86:87]
	global_store_dwordx4 v[86:87], v[106:109], off
	global_store_dwordx4 v[86:87], v[98:101], off offset:64
	global_store_dwordx4 v[86:87], v[78:81], off offset:512
	global_store_dwordx4 v[86:87], v[74:77], off offset:576
	s_mov_b64 s[50:51], s[46:47]
	s_nop 0
	v_or_b32_e32 v74, 48, v142
	v_ashrrev_i32_e32 v75, 31, v74
	v_lshlrev_b64 v[74:75], 13, v[74:75]
	v_lshl_add_u64 v[74:75], v[140:141], 0, v[74:75]
	global_store_dwordx4 v[74:75], v[90:93], off
	global_store_dwordx4 v[74:75], v[82:85], off offset:64
	global_store_dwordx4 v[74:75], v[70:73], off offset:512
	global_store_dwordx4 v[74:75], v[66:69], off offset:576
	s_nop 1
	v_add_co_u32_e32 v68, vcc, s93, v144
	v_lshl_add_u64 v[66:67], v[144:145], 0, s[10:11]
	s_nop 0
	v_addc_co_u32_e32 v69, vcc, 0, v145, vcc
	s_mov_b64 s[10:11], 0x120000
	global_store_dwordx4 v[68:69], v[62:65], off
	global_store_dwordx4 v[66:67], v[58:61], off offset:64
	global_store_dwordx4 v[66:67], v[46:49], off offset:512
	global_store_dwordx4 v[66:67], v[42:45], off offset:576
	s_nop 1
	v_lshl_add_u64 v[42:43], v[144:145], 0, s[10:11]
	s_mov_b32 s10, 0x120000
	v_add_co_u32_e32 v44, vcc, s10, v144
	s_mov_b64 s[10:11], 0x140000
	s_nop 0
	v_addc_co_u32_e32 v45, vcc, 0, v145, vcc
	global_store_dwordx4 v[44:45], v[54:57], off
	global_store_dwordx4 v[42:43], v[50:53], off offset:64
	global_store_dwordx4 v[42:43], v[30:33], off offset:512
	global_store_dwordx4 v[42:43], v[26:29], off offset:576
	s_nop 1
	v_lshl_add_u64 v[26:27], v[144:145], 0, s[10:11]
	s_mov_b32 s10, 0x140000
	v_add_co_u32_e32 v28, vcc, s10, v144
	s_mov_b64 s[10:11], 0x160000
	s_nop 0
	v_addc_co_u32_e32 v29, vcc, 0, v145, vcc
	global_store_dwordx4 v[28:29], v[38:41], off
	global_store_dwordx4 v[26:27], v[34:37], off offset:64
	global_store_dwordx4 v[26:27], v[14:17], off offset:512
	global_store_dwordx4 v[26:27], v[10:13], off offset:576
	s_nop 1
	v_add_co_u32_e32 v12, vcc, 0x160000, v144
	v_lshl_add_u64 v[10:11], v[144:145], 0, s[10:11]
	s_nop 0
	v_addc_co_u32_e32 v13, vcc, 0, v145, vcc
	s_and_b64 vcc, exec, s[44:45]
	s_mov_b32 s10, s28
	global_store_dwordx4 v[12:13], v[22:25], off
	global_store_dwordx4 v[10:11], v[18:21], off offset:64
	global_store_dwordx4 v[10:11], v[6:9], off offset:512
	global_store_dwordx4 v[10:11], v[2:5], off offset:576
	s_cbranch_vccz .LBB0_55
	s_waitcnt vmcnt(0)
	s_cmpk_gt_u32 s60, 0xff
	s_cbranch_scc1 .LBB0_62
	s_barrier

; #define PG8_STAGE(bufoff, gbase, voff) do { _Pragma("unroll") for (int _i = 0; _i < 2; ++_i) \
;         __builtin_amdgcn_global_load_lds((const unsigned*)((const char*)(gbase) + (voff)[_i]), (LAS unsigned*)(lds + (bufoff) + ldsw + _i * 8192), 16, 0, 0); } while (0)
; #define PG8_LDA(dst, b, h) do { _Pragma("unroll") for (int m = 0; m < 4; ++m) _Pragma("unroll") for (int k = 0; k < 2; ++k) dst[m][k] = *(const LAS bf16x8*)(lds + PG8_SA(b, h) + aoff + m * 2048 + k * 1024); } while (0)
; #define PG8_LDB(dst, b, h) do { _Pragma("unroll") for (int n = 0; n < 2; ++n) _Pragma("unroll") for (int k = 0; k < 2; ++k) dst[n][k] = *(const LAS bf16x8*)(lds + PG8_SB(b, h) + boff + n * 2048 + k * 1024); } while (0)
; #define PG8_SCHED __builtin_amdgcn_sched_barrier(0)
; template <class Epi, class Sched>
; __device__ __forceinline__ void gemm_phase(LAS unsigned char* lds, const Gemm g, const Sched& S, const Epi& E) {
;     ...
;         const bool has_next = S.next(ui + 1, nxt);
;         const char* nA = has_next ? (const char*)g.A + (size_t)nxt.pm * tstep + (size_t)nxt.ks * sstep : cA; const char* nB = has_next ? (const char*)g.Bt + (size_t)nxt.pn * tstep + (size_t)nxt.ks * sstep : cB;
;         for (int t = 0; t < nt; t += 2) {
;             const bool last = (t == nt - 2);
;             const char* a1 = cA + (size_t)(t + 1) * kstep;
;             const char* a2 = last ? nA : cA + (size_t)(t + 2) * kstep; const char* b2 = last ? nB : cB + (size_t)(t + 2) * kstep;
;             const char* a3 = a2 + kstep; const char* b3 = b2 + kstep;
;             PG8_LDB(B0, 0, 0); PG8_SCHED; PG8_LDA(At, 0, 0); PG8_STAGE(PG8_SA(1, 1), a1 + hstep, voffA);
;     ...
; #pragma unroll
;         for (int a = 0; a < 2; ++a)
; #pragma unroll
;             for (int b = 0; b < 2; ++b)
; #pragma unroll
;                 for (int m = 0; m < 4; ++m)
; #pragma unroll
;                     for (int n = 0; n < 2; ++n) acc[a][b][m][n] = (f32x4){0.f, 0.f, 0.f, 0.f};
;         cur = nxt; cA = nA; cB = nB; ++ui;
.LBB0_72:
	s_ashr_i32 s29, s28, 31
	v_mov_b64_e32 v[2:3], s[30:31]
	s_lshl_b64 s[38:39], s[28:29], 20
	v_cmp_lt_i64_e32 vcc, s[42:43], v[2:3]
	s_add_u32 s42, s10, s38
	s_addc_u32 s43, s11, s39
	s_and_b64 s[38:39], vcc, exec
	s_cselect_b32 s29, s43, s49
	s_cselect_b32 s69, s42, s48
	s_ashr_i32 s27, s26, 31
	s_lshl_b64 s[38:39], s[26:27], 20
	s_add_u32 s44, s53, s38
	s_addc_u32 s45, s54, s39
	s_and_b64 s[38:39], vcc, exec
	s_cselect_b32 s27, s45, s47
	s_cselect_b32 s70, s44, s46
	s_add_u32 s71, s46, 0x100
	s_addc_u32 s72, s47, 0
	s_add_u32 s46, s48, 0x80080
	v_mov_b32_e32 v2, 0
	s_addc_u32 s47, s49, 0
	s_mov_b32 s73, -2
	v_mov_b32_e32 v3, v2
	v_mov_b32_e32 v4, v2
	v_mov_b32_e32 v5, v2
	v_mov_b32_e32 v6, v2
	v_mov_b32_e32 v7, v2
	v_mov_b32_e32 v8, v2
	v_mov_b32_e32 v9, v2
	v_mov_b32_e32 v18, v2
	v_mov_b32_e32 v19, v2
	v_mov_b32_e32 v20, v2
	v_mov_b32_e32 v21, v2
	v_mov_b32_e32 v22, v2
	v_mov_b32_e32 v23, v2
	v_mov_b32_e32 v24, v2
	v_mov_b32_e32 v25, v2
	v_mov_b32_e32 v34, v2
	v_mov_b32_e32 v35, v2
	v_mov_b32_e32 v36, v2
	v_mov_b32_e32 v37, v2
	v_mov_b32_e32 v38, v2
	v_mov_b32_e32 v39, v2
	v_mov_b32_e32 v40, v2
	v_mov_b32_e32 v41, v2
	v_mov_b32_e32 v50, v2
	v_mov_b32_e32 v51, v2
	v_mov_b32_e32 v52, v2
	v_mov_b32_e32 v53, v2
	v_mov_b32_e32 v54, v2
	v_mov_b32_e32 v55, v2
	v_mov_b32_e32 v56, v2
	v_mov_b32_e32 v57, v2
	v_mov_b32_e32 v10, v2
	v_mov_b32_e32 v11, v2
	v_mov_b32_e32 v12, v2
	v_mov_b32_e32 v13, v2
	v_mov_b32_e32 v14, v2
	v_mov_b32_e32 v15, v2
	v_mov_b32_e32 v16, v2
	v_mov_b32_e32 v17, v2
	v_mov_b32_e32 v26, v2
	v_mov_b32_e32 v27, v2
	v_mov_b32_e32 v28, v2
	v_mov_b32_e32 v29, v2
	v_mov_b32_e32 v30, v2
	v_mov_b32_e32 v31, v2
	v_mov_b32_e32 v32, v2
	v_mov_b32_e32 v33, v2
	v_mov_b32_e32 v42, v2
	v_mov_b32_e32 v43, v2
	v_mov_b32_e32 v44, v2
	v_mov_b32_e32 v45, v2
	v_mov_b32_e32 v46, v2
	v_mov_b32_e32 v47, v2
	v_mov_b32_e32 v48, v2
	v_mov_b32_e32 v49, v2
	v_mov_b32_e32 v58, v2
	v_mov_b32_e32 v59, v2
	v_mov_b32_e32 v60, v2
	v_mov_b32_e32 v61, v2
	v_mov_b32_e32 v62, v2
	v_mov_b32_e32 v63, v2
	v_mov_b32_e32 v64, v2
	v_mov_b32_e32 v65, v2
	v_mov_b32_e32 v66, v2
	v_mov_b32_e32 v67, v2
	v_mov_b32_e32 v68, v2
	v_mov_b32_e32 v69, v2
	v_mov_b32_e32 v70, v2
	v_mov_b32_e32 v71, v2
	v_mov_b32_e32 v72, v2
	v_mov_b32_e32 v73, v2
	v_mov_b32_e32 v82, v2
	v_mov_b32_e32 v83, v2
	v_mov_b32_e32 v84, v2
	v_mov_b32_e32 v85, v2
	v_mov_b32_e32 v86, v2
	v_mov_b32_e32 v87, v2
	v_mov_b32_e32 v88, v2
	v_mov_b32_e32 v89, v2
	v_mov_b32_e32 v98, v2
	v_mov_b32_e32 v99, v2
	v_mov_b32_e32 v100, v2
	v_mov_b32_e32 v101, v2
	v_mov_b32_e32 v102, v2
	v_mov_b32_e32 v103, v2
	v_mov_b32_e32 v104, v2
	v_mov_b32_e32 v105, v2
	v_mov_b32_e32 v114, v2
	v_mov_b32_e32 v115, v2
	v_mov_b32_e32 v116, v2
	v_mov_b32_e32 v117, v2
	v_mov_b32_e32 v118, v2
	v_mov_b32_e32 v119, v2
	v_mov_b32_e32 v120, v2
	v_mov_b32_e32 v121, v2
	v_mov_b32_e32 v74, v2
	v_mov_b32_e32 v75, v2
	v_mov_b32_e32 v76, v2
	v_mov_b32_e32 v77, v2
	v_mov_b32_e32 v78, v2
	v_mov_b32_e32 v79, v2
	v_mov_b32_e32 v80, v2
	v_mov_b32_e32 v81, v2
	v_mov_b32_e32 v90, v2
	v_mov_b32_e32 v91, v2
	v_mov_b32_e32 v92, v2
	v_mov_b32_e32 v93, v2
	v_mov_b32_e32 v94, v2
	v_mov_b32_e32 v95, v2
	v_mov_b32_e32 v96, v2
	v_mov_b32_e32 v97, v2
	v_mov_b32_e32 v106, v2
	v_mov_b32_e32 v107, v2
	v_mov_b32_e32 v108, v2
	v_mov_b32_e32 v109, v2
	v_mov_b32_e32 v110, v2
	v_mov_b32_e32 v111, v2
	v_mov_b32_e32 v112, v2
	v_mov_b32_e32 v113, v2
	v_mov_b32_e32 v122, v2
	v_mov_b32_e32 v123, v2
	v_mov_b32_e32 v124, v2
	v_mov_b32_e32 v125, v2
	v_mov_b32_e32 v126, v2
	v_mov_b32_e32 v127, v2
	v_mov_b32_e32 v128, v2
	v_mov_b32_e32 v129, v2
	s_add_u32 s38, s46, 0xfff80080
	s_addc_u32 s39, s47, -1
	s_cmp_eq_u32 s73, 28
	s_cselect_b32 s51, s29, s39
	s_cselect_b32 s50, s69, s38
	s_cselect_b32 s49, s27, s72
	s_cselect_b32 s48, s70, s71
.LBB0_73:
	s_add_i32 m0, s9, 0xc000
	ds_read_b128 v[146:149], v226
	global_load_lds_dwordx4 v138, s[46:47]
	s_add_i32 m0, s9, 0xe000
	ds_read_b128 v[150:153], v226 offset:1024
	global_load_lds_dwordx4 v136, s[46:47]
	s_add_i32 s74, 0, 0x10000
	ds_read_b128 v[154:157], v226 offset:2048
	ds_read_b128 v[160:163], v226 offset:3072
	ds_read_b128 v[164:167], v145
	ds_read_b128 v[168:171], v145 offset:1024
	ds_read_b128 v[172:175], v145 offset:2048
	ds_read_b128 v[176:179], v145 offset:3072
	ds_read_b128 v[180:183], v145 offset:4096
	ds_read_b128 v[184:187], v145 offset:5120
	ds_read_b128 v[188:191], v145 offset:6144
	ds_read_b128 v[192:195], v145 offset:7168
	s_add_i32 s75, 0, 0x14000
	ds_read_b128 v[196:199], v226 offset:16384
	ds_read_b128 v[200:203], v226 offset:17408
	ds_read_b128 v[204:207], v226 offset:18432
	ds_read_b128 v[210:213], v226 offset:19456
	s_waitcnt lgkmcnt(4)
	s_barrier
; #define PG8_STAGE(bufoff, gbase, voff) do { _Pragma("unroll") for (int _i = 0; _i < 2; ++_i) \
;         __builtin_amdgcn_global_load_lds((const unsigned*)((const char*)(gbase) + (voff)[_i]), (LAS unsigned*)(lds + (bufoff) + ldsw + _i * 8192), 16, 0, 0); } while (0)
; #define PG8_LDA(dst, b, h) do { _Pragma("unroll") for (int m = 0; m < 4; ++m) _Pragma("unroll") for (int k = 0; k < 2; ++k) dst[m][k] = *(const LAS bf16x8*)(lds + PG8_SA(b, h) + aoff + m * 2048 + k * 1024); } while (0)
; #define PG8_LDB(dst, b, h) do { _Pragma("unroll") for (int n = 0; n < 2; ++n) _Pragma("unroll") for (int k = 0; k < 2; ++k) dst[n][k] = *(const LAS bf16x8*)(lds + PG8_SB(b, h) + boff + n * 2048 + k * 1024); } while (0)
; #define PG8_MMA(ai, bj, At, Bt) do { __builtin_amdgcn_s_setprio(1); _Pragma("unroll") for (int m = 0; m < 4; ++m) _Pragma("unroll") for (int n = 0; n < 2; ++n) _Pragma("unroll") for (int k = 0; k < 2; ++k) \
;         acc[ai][bj][m][n] = __builtin_amdgcn_mfma_f32_16x16x32_bf16(Bt[n][k], At[m][k], acc[ai][bj][m][n], 0, 0, 0); __builtin_amdgcn_s_setprio(0); } while (0)
; #define PG8_WAIT_V(n) asm volatile("s_waitcnt vmcnt(" #n ")" ::: "memory")
; #define PG8_WAIT_L(n) asm volatile("s_waitcnt lgkmcnt(" #n ")" ::: "memory")
; #define PG8_BAR __builtin_amdgcn_s_barrier()
; #define PG8_SCHED __builtin_amdgcn_sched_barrier(0)
; template <class Epi, class Sched>
; __device__ __forceinline__ void gemm_phase(LAS unsigned char* lds, const Gemm g, const Sched& S, const Epi& E) {
;     ...
;             PG8_LDB(B0, 0, 0); PG8_SCHED; PG8_LDA(At, 0, 0); PG8_STAGE(PG8_SA(1, 1), a1 + hstep, voffA);
;             PG8_WAIT_L(8); PG8_BAR; PG8_WAIT_L(0); PG8_MMA(0, 0, At, B0); PG8_BAR; PG8_SCHED;
;             PG8_LDB(B1, 0, 1); PG8_STAGE(PG8_SB(0, 0), b2, voffB);
;             PG8_BAR; PG8_WAIT_L(0); PG8_MMA(0, 1, At, B1); PG8_BAR;
;             PG8_LDA(At, 0, 1); PG8_STAGE(PG8_SA(0, 0), a2, voffA);
;             PG8_BAR; PG8_WAIT_L(0); PG8_MMA(1, 0, At, B0); PG8_BAR; PG8_SCHED;
;             PG8_STAGE(PG8_SB(0, 1), b2 + hstep, voffB);
;             PG8_WAIT_V(6); PG8_BAR; PG8_MMA(1, 1, At, B1); PG8_BAR;
	s_waitcnt lgkmcnt(0)
	v_mfma_f32_16x16x32_bf16 v[126:129], v[146:149], v[164:167], v[126:129]
	v_mfma_f32_16x16x32_bf16 v[122:125], v[154:157], v[164:167], v[122:125]
	v_mfma_f32_16x16x32_bf16 v[110:113], v[146:149], v[172:175], v[110:113]
	v_mfma_f32_16x16x32_bf16 v[106:109], v[154:157], v[172:175], v[106:109]
	v_mfma_f32_16x16x32_bf16 v[94:97], v[146:149], v[180:183], v[94:97]
	v_mfma_f32_16x16x32_bf16 v[90:93], v[154:157], v[180:183], v[90:93]
	v_mfma_f32_16x16x32_bf16 v[78:81], v[146:149], v[188:191], v[78:81]
	v_mfma_f32_16x16x32_bf16 v[74:77], v[154:157], v[188:191], v[74:77]
	v_mfma_f32_16x16x32_bf16 v[126:129], v[150:153], v[168:171], v[126:129]
	v_mfma_f32_16x16x32_bf16 v[122:125], v[160:163], v[168:171], v[122:125]
	v_mfma_f32_16x16x32_bf16 v[110:113], v[150:153], v[176:179], v[110:113]
	v_mfma_f32_16x16x32_bf16 v[106:109], v[160:163], v[176:179], v[106:109]
	v_mfma_f32_16x16x32_bf16 v[94:97], v[150:153], v[184:187], v[94:97]
	v_mfma_f32_16x16x32_bf16 v[90:93], v[160:163], v[184:187], v[90:93]
	v_mfma_f32_16x16x32_bf16 v[78:81], v[150:153], v[192:195], v[78:81]
	v_mfma_f32_16x16x32_bf16 v[74:77], v[160:163], v[192:195], v[74:77]
	v_mfma_f32_16x16x32_bf16 v[118:121], v[196:199], v[164:167], v[118:121]
	v_mfma_f32_16x16x32_bf16 v[114:117], v[204:207], v[164:167], v[114:117]
	v_mfma_f32_16x16x32_bf16 v[102:105], v[196:199], v[172:175], v[102:105]
	v_mfma_f32_16x16x32_bf16 v[98:101], v[204:207], v[172:175], v[98:101]
	v_mfma_f32_16x16x32_bf16 v[86:89], v[196:199], v[180:183], v[86:89]
	v_mfma_f32_16x16x32_bf16 v[82:85], v[204:207], v[180:183], v[82:85]
	v_mfma_f32_16x16x32_bf16 v[70:73], v[196:199], v[188:191], v[70:73]
	v_mfma_f32_16x16x32_bf16 v[66:69], v[204:207], v[188:191], v[66:69]
	v_mfma_f32_16x16x32_bf16 v[118:121], v[200:203], v[168:171], v[118:121]
	v_mfma_f32_16x16x32_bf16 v[114:117], v[210:213], v[168:171], v[114:117]
	v_mfma_f32_16x16x32_bf16 v[102:105], v[200:203], v[176:179], v[102:105]
	v_mfma_f32_16x16x32_bf16 v[98:101], v[210:213], v[176:179], v[98:101]
	v_mfma_f32_16x16x32_bf16 v[86:89], v[200:203], v[184:187], v[86:89]
	v_mfma_f32_16x16x32_bf16 v[82:85], v[210:213], v[184:187], v[82:85]
	v_mfma_f32_16x16x32_bf16 v[70:73], v[200:203], v[192:195], v[70:73]
	v_mfma_f32_16x16x32_bf16 v[66:69], v[210:213], v[192:195], v[66:69]
	s_barrier
	s_add_i32 s38, s74, s56
	s_mov_b32 m0, s38
	ds_read_b128 v[164:167], v145 offset:16384
	global_load_lds_dwordx4 v0, s[48:49]
	s_add_i32 m0, s38, 0x2000
	ds_read_b128 v[168:171], v145 offset:17408
	global_load_lds_dwordx4 v130, s[48:49]
	s_mov_b32 m0, s9
	ds_read_b128 v[172:175], v145 offset:18432
	global_load_lds_dwordx4 v134, s[50:51]
	s_mov_b32 m0, s60
	ds_read_b128 v[176:179], v145 offset:19456
	global_load_lds_dwordx4 v132, s[50:51]
	ds_read_b128 v[180:183], v145 offset:20480
	ds_read_b128 v[184:187], v145 offset:21504
	ds_read_b128 v[188:191], v145 offset:22528
	ds_read_b128 v[192:195], v145 offset:23552
	s_waitcnt vmcnt(4)
	s_waitcnt lgkmcnt(0)
	s_barrier
	v_mfma_f32_16x16x32_bf16 v[62:65], v[146:149], v[164:167], v[62:65]
	v_mfma_f32_16x16x32_bf16 v[58:61], v[154:157], v[164:167], v[58:61]
	v_mfma_f32_16x16x32_bf16 v[46:49], v[146:149], v[172:175], v[46:49]
	v_mfma_f32_16x16x32_bf16 v[42:45], v[154:157], v[172:175], v[42:45]
	v_mfma_f32_16x16x32_bf16 v[30:33], v[146:149], v[180:183], v[30:33]
	v_mfma_f32_16x16x32_bf16 v[26:29], v[154:157], v[180:183], v[26:29]
	v_mfma_f32_16x16x32_bf16 v[14:17], v[146:149], v[188:191], v[14:17]
	v_mfma_f32_16x16x32_bf16 v[10:13], v[154:157], v[188:191], v[10:13]
	v_mfma_f32_16x16x32_bf16 v[62:65], v[150:153], v[168:171], v[62:65]
	v_mfma_f32_16x16x32_bf16 v[58:61], v[160:163], v[168:171], v[58:61]
	v_mfma_f32_16x16x32_bf16 v[46:49], v[150:153], v[176:179], v[46:49]
	v_mfma_f32_16x16x32_bf16 v[42:45], v[160:163], v[176:179], v[42:45]
	v_mfma_f32_16x16x32_bf16 v[30:33], v[150:153], v[184:187], v[30:33]
	v_mfma_f32_16x16x32_bf16 v[26:29], v[160:163], v[184:187], v[26:29]
	v_mfma_f32_16x16x32_bf16 v[14:17], v[150:153], v[192:195], v[14:17]
	v_mfma_f32_16x16x32_bf16 v[10:13], v[160:163], v[192:195], v[10:13]
	v_mfma_f32_16x16x32_bf16 v[54:57], v[196:199], v[164:167], v[54:57]
	v_mfma_f32_16x16x32_bf16 v[50:53], v[204:207], v[164:167], v[50:53]
	v_mfma_f32_16x16x32_bf16 v[38:41], v[196:199], v[172:175], v[38:41]
	v_mfma_f32_16x16x32_bf16 v[34:37], v[204:207], v[172:175], v[34:37]
	v_mfma_f32_16x16x32_bf16 v[22:25], v[196:199], v[180:183], v[22:25]
	v_mfma_f32_16x16x32_bf16 v[18:21], v[204:207], v[180:183], v[18:21]
	v_mfma_f32_16x16x32_bf16 v[6:9], v[196:199], v[188:191], v[6:9]
	v_mfma_f32_16x16x32_bf16 v[2:5], v[204:207], v[188:191], v[2:5]
	v_mfma_f32_16x16x32_bf16 v[54:57], v[200:203], v[168:171], v[54:57]
	v_mfma_f32_16x16x32_bf16 v[50:53], v[210:213], v[168:171], v[50:53]
	v_mfma_f32_16x16x32_bf16 v[38:41], v[200:203], v[176:179], v[38:41]
	v_mfma_f32_16x16x32_bf16 v[34:37], v[210:213], v[176:179], v[34:37]
	v_mfma_f32_16x16x32_bf16 v[22:25], v[200:203], v[184:187], v[22:25]
	v_mfma_f32_16x16x32_bf16 v[18:21], v[210:213], v[184:187], v[18:21]
	v_mfma_f32_16x16x32_bf16 v[6:9], v[200:203], v[192:195], v[6:9]
	v_mfma_f32_16x16x32_bf16 v[2:5], v[210:213], v[192:195], v[2:5]
	s_barrier
; #define PG8_STAGE(bufoff, gbase, voff) do { _Pragma("unroll") for (int _i = 0; _i < 2; ++_i) \
;         __builtin_amdgcn_global_load_lds((const unsigned*)((const char*)(gbase) + (voff)[_i]), (LAS unsigned*)(lds + (bufoff) + ldsw + _i * 8192), 16, 0, 0); } while (0)
; #define PG8_LDA(dst, b, h) do { _Pragma("unroll") for (int m = 0; m < 4; ++m) _Pragma("unroll") for (int k = 0; k < 2; ++k) dst[m][k] = *(const LAS bf16x8*)(lds + PG8_SA(b, h) + aoff + m * 2048 + k * 1024); } while (0)
; #define PG8_LDB(dst, b, h) do { _Pragma("unroll") for (int n = 0; n < 2; ++n) _Pragma("unroll") for (int k = 0; k < 2; ++k) dst[n][k] = *(const LAS bf16x8*)(lds + PG8_SB(b, h) + boff + n * 2048 + k * 1024); } while (0)
; #define PG8_MMA(ai, bj, At, Bt) do { __builtin_amdgcn_s_setprio(1); _Pragma("unroll") for (int m = 0; m < 4; ++m) _Pragma("unroll") for (int n = 0; n < 2; ++n) _Pragma("unroll") for (int k = 0; k < 2; ++k) \
;         acc[ai][bj][m][n] = __builtin_amdgcn_mfma_f32_16x16x32_bf16(Bt[n][k], At[m][k], acc[ai][bj][m][n], 0, 0, 0); __builtin_amdgcn_s_setprio(0); } while (0)
; #define PG8_WAIT_V(n) asm volatile("s_waitcnt vmcnt(" #n ")" ::: "memory")
; #define PG8_WAIT_L(n) asm volatile("s_waitcnt lgkmcnt(" #n ")" ::: "memory")
; #define PG8_BAR __builtin_amdgcn_s_barrier()
; #define PG8_SCHED __builtin_amdgcn_sched_barrier(0)
; template <class Epi, class Sched>
; __device__ __forceinline__ void gemm_phase(LAS unsigned char* lds, const Gemm g, const Sched& S, const Epi& E) {
;     ...
;             PG8_WAIT_V(6); PG8_BAR; PG8_MMA(1, 1, At, B1); PG8_BAR;
;             PG8_LDB(B0, 1, 0); PG8_SCHED; PG8_LDA(At, 1, 0); PG8_STAGE(PG8_SA(0, 1), a2 + hstep, voffA);
;             PG8_WAIT_L(8); PG8_BAR; PG8_WAIT_L(0); PG8_MMA(0, 0, At, B0); PG8_BAR; PG8_SCHED;
;             PG8_LDB(B1, 1, 1); PG8_STAGE(PG8_SB(1, 0), b3, voffB);
;             PG8_BAR; PG8_WAIT_L(0); PG8_MMA(0, 1, At, B1); PG8_BAR;
;             PG8_LDA(At, 1, 1); PG8_STAGE(PG8_SA(1, 0), a3, voffA);
;             PG8_BAR; PG8_WAIT_L(0); PG8_MMA(1, 0, At, B0); PG8_BAR; PG8_SCHED;
;             PG8_STAGE(PG8_SB(1, 1), b3 + hstep, voffB);
;             PG8_WAIT_V(6); PG8_BAR; PG8_MMA(1, 1, At, B1); PG8_BAR;
	s_add_u32 s38, s48, 0x80000
	s_addc_u32 s39, s49, 0
	s_add_i32 s74, s75, s56
	s_mov_b32 m0, s74
	ds_read_b128 v[146:149], v226 offset:32768
	global_load_lds_dwordx4 v0, s[38:39]
	s_add_i32 m0, s74, 0x2000
	ds_read_b128 v[150:153], v226 offset:33792
	global_load_lds_dwordx4 v130, s[38:39]
	s_add_u32 s38, s50, 0x80000
	s_addc_u32 s39, s51, 0
	s_mov_b32 m0, s61
	ds_read_b128 v[154:157], v226 offset:34816
	global_load_lds_dwordx4 v134, s[38:39]
	s_mov_b32 m0, s62
	ds_read_b128 v[160:163], v226 offset:35840
	global_load_lds_dwordx4 v132, s[38:39]
	s_add_i32 s74, 0, 0x18000
	ds_read_b128 v[164:167], v145 offset:32768
	ds_read_b128 v[168:171], v145 offset:33792
	ds_read_b128 v[172:175], v145 offset:34816
	ds_read_b128 v[176:179], v145 offset:35840
	ds_read_b128 v[180:183], v145 offset:36864
	ds_read_b128 v[184:187], v145 offset:37888
	ds_read_b128 v[188:191], v145 offset:38912
	ds_read_b128 v[192:195], v145 offset:39936
	s_nop 0
	ds_read_b128 v[196:199], v226 offset:49152
	ds_read_b128 v[200:203], v226 offset:50176
	ds_read_b128 v[204:207], v226 offset:51200
	ds_read_b128 v[210:213], v226 offset:52224
	s_waitcnt lgkmcnt(4)
	s_barrier
	s_waitcnt lgkmcnt(0)
	v_mfma_f32_16x16x32_bf16 v[126:129], v[146:149], v[164:167], v[126:129]
	v_mfma_f32_16x16x32_bf16 v[122:125], v[154:157], v[164:167], v[122:125]
	v_mfma_f32_16x16x32_bf16 v[110:113], v[146:149], v[172:175], v[110:113]
	v_mfma_f32_16x16x32_bf16 v[106:109], v[154:157], v[172:175], v[106:109]
	v_mfma_f32_16x16x32_bf16 v[94:97], v[146:149], v[180:183], v[94:97]
	v_mfma_f32_16x16x32_bf16 v[90:93], v[154:157], v[180:183], v[90:93]
	v_mfma_f32_16x16x32_bf16 v[78:81], v[146:149], v[188:191], v[78:81]
	v_mfma_f32_16x16x32_bf16 v[74:77], v[154:157], v[188:191], v[74:77]
	v_mfma_f32_16x16x32_bf16 v[126:129], v[150:153], v[168:171], v[126:129]
	v_mfma_f32_16x16x32_bf16 v[122:125], v[160:163], v[168:171], v[122:125]
	v_mfma_f32_16x16x32_bf16 v[110:113], v[150:153], v[176:179], v[110:113]
	v_mfma_f32_16x16x32_bf16 v[106:109], v[160:163], v[176:179], v[106:109]
	v_mfma_f32_16x16x32_bf16 v[94:97], v[150:153], v[184:187], v[94:97]
	v_mfma_f32_16x16x32_bf16 v[90:93], v[160:163], v[184:187], v[90:93]
	v_mfma_f32_16x16x32_bf16 v[78:81], v[150:153], v[192:195], v[78:81]
	v_mfma_f32_16x16x32_bf16 v[74:77], v[160:163], v[192:195], v[74:77]
	v_mfma_f32_16x16x32_bf16 v[118:121], v[196:199], v[164:167], v[118:121]
	v_mfma_f32_16x16x32_bf16 v[114:117], v[204:207], v[164:167], v[114:117]
	v_mfma_f32_16x16x32_bf16 v[102:105], v[196:199], v[172:175], v[102:105]
	v_mfma_f32_16x16x32_bf16 v[98:101], v[204:207], v[172:175], v[98:101]
	v_mfma_f32_16x16x32_bf16 v[86:89], v[196:199], v[180:183], v[86:89]
	v_mfma_f32_16x16x32_bf16 v[82:85], v[204:207], v[180:183], v[82:85]
	v_mfma_f32_16x16x32_bf16 v[70:73], v[196:199], v[188:191], v[70:73]
	v_mfma_f32_16x16x32_bf16 v[66:69], v[204:207], v[188:191], v[66:69]
	v_mfma_f32_16x16x32_bf16 v[118:121], v[200:203], v[168:171], v[118:121]
	v_mfma_f32_16x16x32_bf16 v[114:117], v[210:213], v[168:171], v[114:117]
	v_mfma_f32_16x16x32_bf16 v[102:105], v[200:203], v[176:179], v[102:105]
	v_mfma_f32_16x16x32_bf16 v[98:101], v[210:213], v[176:179], v[98:101]
	v_mfma_f32_16x16x32_bf16 v[86:89], v[200:203], v[184:187], v[86:89]
	v_mfma_f32_16x16x32_bf16 v[82:85], v[210:213], v[184:187], v[82:85]
	v_mfma_f32_16x16x32_bf16 v[70:73], v[200:203], v[192:195], v[70:73]
	v_mfma_f32_16x16x32_bf16 v[66:69], v[210:213], v[192:195], v[66:69]
	s_barrier
	s_add_i32 s38, s74, s56
	s_add_u32 s100, s48, s36
	s_addc_u32 s101, s49, s37
	s_mov_b32 m0, s38
	ds_read_b128 v[164:167], v145 offset:49152
	global_load_lds_dwordx4 v0, s[100:101]
	s_add_i32 m0, s38, 0x2000
	ds_read_b128 v[168:171], v145 offset:50176
	global_load_lds_dwordx4 v130, s[100:101]
	s_mov_b32 m0, s64
	s_add_u32 s100, s50, s36
	s_addc_u32 s101, s51, s37
	global_load_lds_dwordx4 v134, s[100:101]
	s_mov_b32 m0, s65
	ds_read_b128 v[172:175], v145 offset:51200
	global_load_lds_dwordx4 v132, s[100:101]
	ds_read_b128 v[176:179], v145 offset:52224
	ds_read_b128 v[180:183], v145 offset:53248
	ds_read_b128 v[184:187], v145 offset:54272
	ds_read_b128 v[188:191], v145 offset:55296
	ds_read_b128 v[192:195], v145 offset:56320
	s_waitcnt vmcnt(4)
	s_waitcnt lgkmcnt(0)
	s_barrier
	v_mfma_f32_16x16x32_bf16 v[62:65], v[146:149], v[164:167], v[62:65]
	v_mfma_f32_16x16x32_bf16 v[58:61], v[154:157], v[164:167], v[58:61]
	v_mfma_f32_16x16x32_bf16 v[46:49], v[146:149], v[172:175], v[46:49]
	v_mfma_f32_16x16x32_bf16 v[42:45], v[154:157], v[172:175], v[42:45]
	v_mfma_f32_16x16x32_bf16 v[30:33], v[146:149], v[180:183], v[30:33]
	v_mfma_f32_16x16x32_bf16 v[26:29], v[154:157], v[180:183], v[26:29]
	v_mfma_f32_16x16x32_bf16 v[14:17], v[146:149], v[188:191], v[14:17]
	v_mfma_f32_16x16x32_bf16 v[10:13], v[154:157], v[188:191], v[10:13]
	v_mfma_f32_16x16x32_bf16 v[62:65], v[150:153], v[168:171], v[62:65]
	v_mfma_f32_16x16x32_bf16 v[58:61], v[160:163], v[168:171], v[58:61]
	v_mfma_f32_16x16x32_bf16 v[46:49], v[150:153], v[176:179], v[46:49]
	v_mfma_f32_16x16x32_bf16 v[42:45], v[160:163], v[176:179], v[42:45]
	v_mfma_f32_16x16x32_bf16 v[30:33], v[150:153], v[184:187], v[30:33]
	v_mfma_f32_16x16x32_bf16 v[26:29], v[160:163], v[184:187], v[26:29]
	v_mfma_f32_16x16x32_bf16 v[14:17], v[150:153], v[192:195], v[14:17]
	v_mfma_f32_16x16x32_bf16 v[10:13], v[160:163], v[192:195], v[10:13]
	s_add_u32 s38, s48, 0x80080
	s_addc_u32 s39, s49, 0
	s_add_i32 s48, s56, 0x1c000
	s_mov_b32 m0, s48
	s_nop 0
	global_load_lds_dwordx4 v0, s[38:39]
	s_add_i32 m0, s48, 0x2000
	s_nop 0
	global_load_lds_dwordx4 v130, s[38:39]
	v_mfma_f32_16x16x32_bf16 v[54:57], v[196:199], v[164:167], v[54:57]
	v_mfma_f32_16x16x32_bf16 v[50:53], v[204:207], v[164:167], v[50:53]
	v_mfma_f32_16x16x32_bf16 v[38:41], v[196:199], v[172:175], v[38:41]
	v_mfma_f32_16x16x32_bf16 v[34:37], v[204:207], v[172:175], v[34:37]
	v_mfma_f32_16x16x32_bf16 v[22:25], v[196:199], v[180:183], v[22:25]
	v_mfma_f32_16x16x32_bf16 v[18:21], v[204:207], v[180:183], v[18:21]
	v_mfma_f32_16x16x32_bf16 v[6:9], v[196:199], v[188:191], v[6:9]
	v_mfma_f32_16x16x32_bf16 v[2:5], v[204:207], v[188:191], v[2:5]
	v_mfma_f32_16x16x32_bf16 v[54:57], v[200:203], v[168:171], v[54:57]
	v_mfma_f32_16x16x32_bf16 v[50:53], v[210:213], v[168:171], v[50:53]
	v_mfma_f32_16x16x32_bf16 v[38:41], v[200:203], v[176:179], v[38:41]
	v_mfma_f32_16x16x32_bf16 v[34:37], v[210:213], v[176:179], v[34:37]
	v_mfma_f32_16x16x32_bf16 v[22:25], v[200:203], v[184:187], v[22:25]
	v_mfma_f32_16x16x32_bf16 v[18:21], v[210:213], v[184:187], v[18:21]
	v_mfma_f32_16x16x32_bf16 v[6:9], v[200:203], v[192:195], v[6:9]
	v_mfma_f32_16x16x32_bf16 v[2:5], v[210:213], v[192:195], v[2:5]
	s_add_i32 s73, s73, 2
	s_add_u32 s71, s71, 0x100
	s_addc_u32 s72, s72, 0
	s_add_u32 s46, s46, 0x100
	s_addc_u32 s47, s47, 0
	s_add_u32 s38, s46, 0xfff80080
	s_addc_u32 s39, s47, -1
	s_cmp_eq_u32 s73, 28
	s_cselect_b32 s51, s29, s39
	s_cselect_b32 s50, s69, s38
	s_cselect_b32 s49, s27, s72
	s_cselect_b32 s48, s70, s71
	s_cmp_gt_u32 s73, 29
	s_barrier
; __device__ __forceinline__ unsigned cvt_pk_bf16(float lo, float hi) { unsigned r; asm("v_cvt_pk_bf16_f32 %0, %1, %2" : "=v"(r) : "v"(lo), "v"(hi)); return r; }
;     __device__ __forceinline__ void operator()(const f32x4 (&acc)[2][2][4][2], const Unit& u, int wr, int wc, int fr, int fq) const {
;     ...
;                 for (int bj = 0; bj < 2; ++bj) { f32x4 v0 = acc[ai][bj][m][0], v1 = acc[ai][bj][m][1];
;                     if (ACT == 1) {
; #pragma unroll
;                         for (int j = 0; j < 4; ++j) { float a = fmaxf(v0[j], 0.f), b = fmaxf(v1[j], 0.f); v0[j] = a * a; v1[j] = b * b; } }
;                     u32x4 w; w.x = cvt_pk_bf16(v0[0], v0[1]); w.y = cvt_pk_bf16(v0[2], v0[3]); w.z = cvt_pk_bf16(v1[0], v1[1]); w.w = cvt_pk_bf16(v1[2], v1[3]);
;                     if (ACT == 1) __builtin_nontemporal_store(w, (u32x4*)(rowp + bj * HALF));
;                     else *(u32x4*)(rowp + bj * HALF) = w; } }
	s_cbranch_scc0 .LBB0_73
	v_lshl_add_u32 v146, s8, 8, v142
	v_max_f32_e32 v122, v122, v122
	v_ashrrev_i32_e32 v147, 31, v146
	v_max_f32_e32 v122, 0, v122
	v_max_f32_e32 v123, v123, v123
	v_max_f32_e32 v124, v124, v124
	v_lshl_or_b32 v140, s68, 8, v144
	v_lshlrev_b64 v[148:149], 14, v[146:147]
	v_mul_f32_e32 v147, v122, v122
	v_max_f32_e32 v122, v127, v127
	v_max_f32_e32 v123, 0, v123
	v_max_f32_e32 v124, 0, v124
	v_ashrrev_i32_e32 v141, 31, v140
	v_max_f32_e32 v126, v126, v126
	v_max_f32_e32 v122, 0, v122
	v_mul_f32_e32 v127, v123, v123
	v_max_f32_e32 v123, v128, v128
	v_mul_f32_e32 v128, v124, v124
	v_max_f32_e32 v124, v129, v129
	v_max_f32_e32 v125, v125, v125
	v_lshl_add_u64 v[148:149], s[24:25], 0, v[148:149]
	v_lshlrev_b64 v[150:151], 1, v[140:141]
	v_max_f32_e32 v126, 0, v126
	v_mul_f32_e32 v122, v122, v122
	v_max_f32_e32 v123, 0, v123
	v_max_f32_e32 v124, 0, v124
	v_max_f32_e32 v125, 0, v125
	v_max_f32_e32 v114, v114, v114
	v_lshl_add_u64 v[140:141], v[148:149], 0, v[150:151]
	v_mul_f32_e32 v126, v126, v126
	v_mul_f32_e32 v123, v123, v123
	v_mul_f32_e32 v124, v124, v124
	v_mul_f32_e32 v125, v125, v125
	v_cvt_pk_bf16_f32 v122, v126, v122
	v_max_f32_e32 v114, 0, v114
	v_max_f32_e32 v115, v115, v115
	v_max_f32_e32 v116, v116, v116
	v_cvt_pk_bf16_f32 v123, v123, v124
	v_cvt_pk_bf16_f32 v124, v147, v127
	v_cvt_pk_bf16_f32 v125, v128, v125
	global_store_dwordx4 v[140:141], v[122:125], off nt
	v_max_f32_e32 v115, 0, v115
	v_max_f32_e32 v116, 0, v116
	v_mul_f32_e32 v122, v114, v114
	v_max_f32_e32 v114, v119, v119
	v_max_f32_e32 v118, v118, v118
	v_max_f32_e32 v114, 0, v114
	v_mul_f32_e32 v119, v115, v115
	v_max_f32_e32 v115, v120, v120
	v_mul_f32_e32 v120, v116, v116
	v_max_f32_e32 v116, v121, v121
	v_max_f32_e32 v117, v117, v117
	v_max_f32_e32 v118, 0, v118
	v_mul_f32_e32 v114, v114, v114
	v_max_f32_e32 v115, 0, v115
	v_max_f32_e32 v116, 0, v116
	v_max_f32_e32 v117, 0, v117
	v_mul_f32_e32 v118, v118, v118
	v_mul_f32_e32 v115, v115, v115
	v_mul_f32_e32 v116, v116, v116
	v_mul_f32_e32 v117, v117, v117
	v_cvt_pk_bf16_f32 v114, v118, v114
	v_max_f32_e32 v106, v106, v106
	v_cvt_pk_bf16_f32 v115, v115, v116
	v_cvt_pk_bf16_f32 v116, v122, v119
	v_cvt_pk_bf16_f32 v117, v120, v117
	global_store_dwordx4 v[140:141], v[114:117], off offset:256 nt
	v_max_f32_e32 v106, 0, v106
	v_max_f32_e32 v107, v107, v107
	v_or_b32_e32 v114, 16, v146
	v_max_f32_e32 v108, v108, v108
	v_ashrrev_i32_e32 v115, 31, v114
	v_mul_f32_e32 v116, v106, v106
	v_max_f32_e32 v106, v111, v111
	v_max_f32_e32 v107, 0, v107
	v_max_f32_e32 v108, 0, v108
	v_lshlrev_b64 v[114:115], 14, v[114:115]
	v_max_f32_e32 v110, v110, v110
	v_max_f32_e32 v106, 0, v106
	v_mul_f32_e32 v111, v107, v107
	v_max_f32_e32 v107, v112, v112
	v_mul_f32_e32 v112, v108, v108
	v_max_f32_e32 v108, v113, v113
	v_max_f32_e32 v109, v109, v109
	v_lshl_add_u64 v[114:115], s[24:25], 0, v[114:115]
	v_max_f32_e32 v110, 0, v110
	v_mul_f32_e32 v106, v106, v106
	v_max_f32_e32 v107, 0, v107
	v_max_f32_e32 v108, 0, v108
	v_max_f32_e32 v109, 0, v109
	v_max_f32_e32 v98, v98, v98
	v_lshl_add_u64 v[114:115], v[114:115], 0, v[150:151]
	v_mul_f32_e32 v110, v110, v110
	v_mul_f32_e32 v107, v107, v107
	v_mul_f32_e32 v108, v108, v108
	v_mul_f32_e32 v109, v109, v109
	v_cvt_pk_bf16_f32 v106, v110, v106
	v_max_f32_e32 v98, 0, v98
	v_max_f32_e32 v99, v99, v99
	v_max_f32_e32 v100, v100, v100
	v_cvt_pk_bf16_f32 v107, v107, v108
	v_cvt_pk_bf16_f32 v108, v116, v111
	v_cvt_pk_bf16_f32 v109, v112, v109
	global_store_dwordx4 v[114:115], v[106:109], off nt
	v_max_f32_e32 v99, 0, v99
	v_max_f32_e32 v100, 0, v100
	v_mul_f32_e32 v106, v98, v98
	v_max_f32_e32 v98, v103, v103
	v_max_f32_e32 v102, v102, v102
	v_max_f32_e32 v98, 0, v98
	v_mul_f32_e32 v103, v99, v99
	v_max_f32_e32 v99, v104, v104
	v_mul_f32_e32 v104, v100, v100
	v_max_f32_e32 v100, v105, v105
	v_max_f32_e32 v101, v101, v101
	v_max_f32_e32 v102, 0, v102
	v_mul_f32_e32 v98, v98, v98
	v_max_f32_e32 v99, 0, v99
	v_max_f32_e32 v100, 0, v100
	v_max_f32_e32 v101, 0, v101
	v_mul_f32_e32 v102, v102, v102
	v_mul_f32_e32 v99, v99, v99
	v_mul_f32_e32 v100, v100, v100
	v_mul_f32_e32 v101, v101, v101
	v_cvt_pk_bf16_f32 v98, v102, v98
	v_max_f32_e32 v90, v90, v90
	v_cvt_pk_bf16_f32 v99, v99, v100
	v_cvt_pk_bf16_f32 v100, v106, v103
	v_cvt_pk_bf16_f32 v101, v104, v101
	global_store_dwordx4 v[114:115], v[98:101], off offset:256 nt
	v_max_f32_e32 v90, 0, v90
	v_max_f32_e32 v91, v91, v91
	v_or_b32_e32 v98, 32, v146
	v_max_f32_e32 v92, v92, v92
	v_ashrrev_i32_e32 v99, 31, v98
	v_mul_f32_e32 v100, v90, v90
	v_max_f32_e32 v90, v95, v95
	v_max_f32_e32 v91, 0, v91
	v_max_f32_e32 v92, 0, v92
	v_lshlrev_b64 v[98:99], 14, v[98:99]
	v_max_f32_e32 v94, v94, v94
	v_max_f32_e32 v90, 0, v90
	v_mul_f32_e32 v95, v91, v91
	v_max_f32_e32 v91, v96, v96
	v_mul_f32_e32 v96, v92, v92
	v_max_f32_e32 v92, v97, v97
	v_max_f32_e32 v93, v93, v93
	v_lshl_add_u64 v[98:99], s[24:25], 0, v[98:99]
	v_max_f32_e32 v94, 0, v94
	v_mul_f32_e32 v90, v90, v90
	v_max_f32_e32 v91, 0, v91
	v_max_f32_e32 v92, 0, v92
	v_max_f32_e32 v93, 0, v93
	v_max_f32_e32 v82, v82, v82
	v_lshl_add_u64 v[98:99], v[98:99], 0, v[150:151]
	v_mul_f32_e32 v94, v94, v94
	v_mul_f32_e32 v91, v91, v91
	v_mul_f32_e32 v92, v92, v92
	v_mul_f32_e32 v93, v93, v93
	v_cvt_pk_bf16_f32 v90, v94, v90
	v_max_f32_e32 v82, 0, v82
	v_max_f32_e32 v83, v83, v83
	v_max_f32_e32 v84, v84, v84
	v_cvt_pk_bf16_f32 v91, v91, v92
	v_cvt_pk_bf16_f32 v92, v100, v95
	v_cvt_pk_bf16_f32 v93, v96, v93
	global_store_dwordx4 v[98:99], v[90:93], off nt
	v_max_f32_e32 v83, 0, v83
	v_max_f32_e32 v84, 0, v84
	v_mul_f32_e32 v90, v82, v82
	v_max_f32_e32 v82, v87, v87
	v_max_f32_e32 v86, v86, v86
; __device__ __forceinline__ unsigned cvt_pk_bf16(float lo, float hi) { unsigned r; asm("v_cvt_pk_bf16_f32 %0, %1, %2" : "=v"(r) : "v"(lo), "v"(hi)); return r; }
;     __device__ __forceinline__ void operator()(const f32x4 (&acc)[2][2][4][2], const Unit& u, int wr, int wc, int fr, int fq) const {
;     ...
;                 for (int bj = 0; bj < 2; ++bj) { f32x4 v0 = acc[ai][bj][m][0], v1 = acc[ai][bj][m][1];
;                     if (ACT == 1) {
; #pragma unroll
;                         for (int j = 0; j < 4; ++j) { float a = fmaxf(v0[j], 0.f), b = fmaxf(v1[j], 0.f); v0[j] = a * a; v1[j] = b * b; } }
;                     u32x4 w; w.x = cvt_pk_bf16(v0[0], v0[1]); w.y = cvt_pk_bf16(v0[2], v0[3]); w.z = cvt_pk_bf16(v1[0], v1[1]); w.w = cvt_pk_bf16(v1[2], v1[3]);
;                     if (ACT == 1) __builtin_nontemporal_store(w, (u32x4*)(rowp + bj * HALF));
;                     else *(u32x4*)(rowp + bj * HALF) = w; } }
	v_max_f32_e32 v82, 0, v82
	v_mul_f32_e32 v87, v83, v83
	v_max_f32_e32 v83, v88, v88
	v_mul_f32_e32 v88, v84, v84
	v_max_f32_e32 v84, v89, v89
	v_max_f32_e32 v85, v85, v85
	v_max_f32_e32 v86, 0, v86
	v_mul_f32_e32 v82, v82, v82
	v_max_f32_e32 v83, 0, v83
	v_max_f32_e32 v84, 0, v84
	v_max_f32_e32 v85, 0, v85
	v_mul_f32_e32 v86, v86, v86
	v_mul_f32_e32 v83, v83, v83
	v_mul_f32_e32 v84, v84, v84
	v_mul_f32_e32 v85, v85, v85
	v_cvt_pk_bf16_f32 v82, v86, v82
	v_max_f32_e32 v74, v74, v74
	v_cvt_pk_bf16_f32 v83, v83, v84
	v_cvt_pk_bf16_f32 v84, v90, v87
	v_cvt_pk_bf16_f32 v85, v88, v85
	global_store_dwordx4 v[98:99], v[82:85], off offset:256 nt
	v_max_f32_e32 v74, 0, v74
	v_max_f32_e32 v75, v75, v75
	v_or_b32_e32 v82, 48, v146
	v_max_f32_e32 v76, v76, v76
	v_ashrrev_i32_e32 v83, 31, v82
	v_mul_f32_e32 v84, v74, v74
	v_max_f32_e32 v74, v79, v79
	v_max_f32_e32 v75, 0, v75
	v_max_f32_e32 v76, 0, v76
	v_lshlrev_b64 v[82:83], 14, v[82:83]
	v_max_f32_e32 v78, v78, v78
	v_max_f32_e32 v74, 0, v74
	v_mul_f32_e32 v79, v75, v75
	v_max_f32_e32 v75, v80, v80
	v_mul_f32_e32 v80, v76, v76
	v_max_f32_e32 v76, v81, v81
	v_max_f32_e32 v77, v77, v77
	v_lshl_add_u64 v[82:83], s[24:25], 0, v[82:83]
	v_max_f32_e32 v78, 0, v78
	v_mul_f32_e32 v74, v74, v74
	v_max_f32_e32 v75, 0, v75
	v_max_f32_e32 v76, 0, v76
	v_max_f32_e32 v77, 0, v77
	v_max_f32_e32 v66, v66, v66
	v_max_f32_e32 v67, v67, v67
	v_max_f32_e32 v68, v68, v68
	v_lshl_add_u64 v[82:83], v[82:83], 0, v[150:151]
	v_mul_f32_e32 v78, v78, v78
	v_mul_f32_e32 v75, v75, v75
	v_mul_f32_e32 v76, v76, v76
	v_mul_f32_e32 v77, v77, v77
	v_cvt_pk_bf16_f32 v74, v78, v74
	v_max_f32_e32 v66, 0, v66
	v_max_f32_e32 v67, 0, v67
	v_max_f32_e32 v68, 0, v68
	v_cvt_pk_bf16_f32 v75, v75, v76
	v_cvt_pk_bf16_f32 v76, v84, v79
	v_cvt_pk_bf16_f32 v77, v80, v77
	global_store_dwordx4 v[82:83], v[74:77], off nt
	v_max_f32_e32 v69, v69, v69
	v_max_f32_e32 v70, v70, v70
	v_mul_f32_e32 v74, v66, v66
	v_max_f32_e32 v66, v71, v71
	v_mul_f32_e32 v71, v67, v67
	v_max_f32_e32 v67, v72, v72
	v_mul_f32_e32 v72, v68, v68
	v_max_f32_e32 v68, v73, v73
	v_max_f32_e32 v67, 0, v67
	v_max_f32_e32 v68, 0, v68
	v_max_f32_e32 v66, 0, v66
	v_mul_f32_e32 v67, v67, v67
	v_max_f32_e32 v69, 0, v69
	v_mul_f32_e32 v68, v68, v68
	v_max_f32_e32 v58, v58, v58
	v_max_f32_e32 v70, 0, v70
	v_mul_f32_e32 v66, v66, v66
	v_mul_f32_e32 v69, v69, v69
	v_cvt_pk_bf16_f32 v67, v67, v68
	v_cvt_pk_bf16_f32 v68, v74, v71
	v_max_f32_e32 v58, 0, v58
	v_max_f32_e32 v59, v59, v59
	v_max_f32_e32 v60, v60, v60
	v_mul_f32_e32 v70, v70, v70
	v_cvt_pk_bf16_f32 v66, v70, v66
	v_cvt_pk_bf16_f32 v69, v72, v69
	global_store_dwordx4 v[82:83], v[66:69], off offset:256 nt
	v_max_f32_e32 v62, v62, v62
	v_max_f32_e32 v59, 0, v59
	v_mul_f32_e32 v68, v58, v58
	v_max_f32_e32 v58, v63, v63
	v_max_f32_e32 v60, 0, v60
	v_max_f32_e32 v62, 0, v62
	v_max_f32_e32 v58, 0, v58
	v_mul_f32_e32 v63, v59, v59
	v_max_f32_e32 v59, v64, v64
	v_mul_f32_e32 v64, v60, v60
	v_max_f32_e32 v60, v65, v65
	v_mul_f32_e32 v62, v62, v62
	v_mul_f32_e32 v58, v58, v58
	v_max_f32_e32 v59, 0, v59
	v_max_f32_e32 v60, 0, v60
	v_max_f32_e32 v61, v61, v61
	s_mov_b32 s8, 0x200000
	v_mul_f32_e32 v59, v59, v59
	v_max_f32_e32 v61, 0, v61
	v_mul_f32_e32 v60, v60, v60
	v_cvt_pk_bf16_f32 v58, v62, v58
	v_add_co_u32_e32 v62, vcc, s8, v140
	v_max_f32_e32 v50, v50, v50
	v_max_f32_e32 v51, v51, v51
	v_max_f32_e32 v52, v52, v52
	v_mul_f32_e32 v61, v61, v61
	v_cvt_pk_bf16_f32 v59, v59, v60
	v_cvt_pk_bf16_f32 v60, v68, v63
	v_addc_co_u32_e32 v63, vcc, 0, v141, vcc
	v_max_f32_e32 v50, 0, v50
	v_max_f32_e32 v51, 0, v51
	v_max_f32_e32 v52, 0, v52
	v_cvt_pk_bf16_f32 v61, v64, v61
	global_store_dwordx4 v[62:63], v[58:61], off nt
	v_max_f32_e32 v53, v53, v53
	s_mov_b64 s[38:39], 0x200000
	v_mul_f32_e32 v58, v50, v50
	v_max_f32_e32 v50, v55, v55
	v_mul_f32_e32 v55, v51, v51
	v_max_f32_e32 v51, v56, v56
	v_mul_f32_e32 v56, v52, v52
	v_max_f32_e32 v52, v57, v57
	v_max_f32_e32 v51, 0, v51
	v_max_f32_e32 v52, 0, v52
	v_max_f32_e32 v54, v54, v54
	v_max_f32_e32 v50, 0, v50
	v_mul_f32_e32 v51, v51, v51
	v_max_f32_e32 v53, 0, v53
	v_mul_f32_e32 v52, v52, v52
	v_max_f32_e32 v42, v42, v42
	v_lshl_add_u64 v[66:67], v[140:141], 0, s[38:39]
	v_max_f32_e32 v54, 0, v54
	v_mul_f32_e32 v50, v50, v50
	v_mul_f32_e32 v53, v53, v53
	v_cvt_pk_bf16_f32 v51, v51, v52
	v_cvt_pk_bf16_f32 v52, v58, v55
	v_max_f32_e32 v42, 0, v42
	v_max_f32_e32 v43, v43, v43
	v_max_f32_e32 v44, v44, v44
	v_mul_f32_e32 v54, v54, v54
	v_cvt_pk_bf16_f32 v50, v54, v50
	v_cvt_pk_bf16_f32 v53, v56, v53
	global_store_dwordx4 v[66:67], v[50:53], off offset:256 nt
	v_max_f32_e32 v46, v46, v46
	v_max_f32_e32 v43, 0, v43
	v_mul_f32_e32 v52, v42, v42
	v_max_f32_e32 v42, v47, v47
	v_max_f32_e32 v44, 0, v44
	v_max_f32_e32 v46, 0, v46
	v_max_f32_e32 v42, 0, v42
	v_mul_f32_e32 v47, v43, v43
	v_max_f32_e32 v43, v48, v48
	v_mul_f32_e32 v48, v44, v44
	v_max_f32_e32 v44, v49, v49
	v_mul_f32_e32 v46, v46, v46
	v_mul_f32_e32 v42, v42, v42
	v_max_f32_e32 v43, 0, v43
	v_max_f32_e32 v44, 0, v44
	v_max_f32_e32 v45, v45, v45
	s_mov_b32 s8, 0x240000
	v_mul_f32_e32 v43, v43, v43
	v_max_f32_e32 v45, 0, v45
	v_mul_f32_e32 v44, v44, v44
	v_cvt_pk_bf16_f32 v42, v46, v42
; __device__ __forceinline__ unsigned cvt_pk_bf16(float lo, float hi) { unsigned r; asm("v_cvt_pk_bf16_f32 %0, %1, %2" : "=v"(r) : "v"(lo), "v"(hi)); return r; }
; #define PG8_WAIT_V(n) asm volatile("s_waitcnt vmcnt(" #n ")" ::: "memory")
; #define PG8_BAR __builtin_amdgcn_s_barrier()
;     __device__ __forceinline__ void operator()(const f32x4 (&acc)[2][2][4][2], const Unit& u, int wr, int wc, int fr, int fq) const {
;     ...
;             for (int m = 0; m < 4; ++m) { bf16_t* rowp = O + (size_t)(row0 + ai * HALF + m * 16) * ldc + col0;
; #pragma unroll
;                 for (int bj = 0; bj < 2; ++bj) { f32x4 v0 = acc[ai][bj][m][0], v1 = acc[ai][bj][m][1];
;                     if (ACT == 1) {
; #pragma unroll
;                         for (int j = 0; j < 4; ++j) { float a = fmaxf(v0[j], 0.f), b = fmaxf(v1[j], 0.f); v0[j] = a * a; v1[j] = b * b; } }
;                     u32x4 w; w.x = cvt_pk_bf16(v0[0], v0[1]); w.y = cvt_pk_bf16(v0[2], v0[3]); w.z = cvt_pk_bf16(v1[0], v1[1]); w.w = cvt_pk_bf16(v1[2], v1[3]);
;                     if (ACT == 1) __builtin_nontemporal_store(w, (u32x4*)(rowp + bj * HALF));
;                     else *(u32x4*)(rowp + bj * HALF) = w; } }
; template <class Epi, class Sched>
; __device__ __forceinline__ void gemm_phase(LAS unsigned char* lds, const Gemm g, const Sched& S, const Epi& E) {
;     ...
;     PG8_WAIT_V(0);
;     if (wr == 0) PG8_BAR;
;     PG8_BAR;
	v_add_co_u32_e32 v46, vcc, s8, v140
	v_max_f32_e32 v34, v34, v34
	v_max_f32_e32 v35, v35, v35
	v_max_f32_e32 v36, v36, v36
	v_mul_f32_e32 v45, v45, v45
	v_cvt_pk_bf16_f32 v43, v43, v44
	v_cvt_pk_bf16_f32 v44, v52, v47
	v_addc_co_u32_e32 v47, vcc, 0, v141, vcc
	v_max_f32_e32 v34, 0, v34
	v_max_f32_e32 v35, 0, v35
	v_max_f32_e32 v36, 0, v36
	v_cvt_pk_bf16_f32 v45, v48, v45
	global_store_dwordx4 v[46:47], v[42:45], off nt
	v_max_f32_e32 v37, v37, v37
	s_mov_b64 s[38:39], 0x240000
	v_mul_f32_e32 v42, v34, v34
	v_max_f32_e32 v34, v39, v39
	v_mul_f32_e32 v39, v35, v35
	v_max_f32_e32 v35, v40, v40
	v_mul_f32_e32 v40, v36, v36
	v_max_f32_e32 v36, v41, v41
	v_max_f32_e32 v35, 0, v35
	v_max_f32_e32 v36, 0, v36
	v_max_f32_e32 v38, v38, v38
	v_max_f32_e32 v34, 0, v34
	v_mul_f32_e32 v35, v35, v35
	v_max_f32_e32 v37, 0, v37
	v_mul_f32_e32 v36, v36, v36
	v_max_f32_e32 v26, v26, v26
	v_lshl_add_u64 v[50:51], v[140:141], 0, s[38:39]
	v_max_f32_e32 v38, 0, v38
	v_mul_f32_e32 v34, v34, v34
	v_mul_f32_e32 v37, v37, v37
	v_cvt_pk_bf16_f32 v35, v35, v36
	v_cvt_pk_bf16_f32 v36, v42, v39
	v_max_f32_e32 v26, 0, v26
	v_max_f32_e32 v27, v27, v27
	v_max_f32_e32 v28, v28, v28
	v_mul_f32_e32 v38, v38, v38
	v_cvt_pk_bf16_f32 v34, v38, v34
	v_cvt_pk_bf16_f32 v37, v40, v37
	global_store_dwordx4 v[50:51], v[34:37], off offset:256 nt
	v_max_f32_e32 v30, v30, v30
	v_max_f32_e32 v27, 0, v27
	v_mul_f32_e32 v36, v26, v26
	v_max_f32_e32 v26, v31, v31
	v_max_f32_e32 v28, 0, v28
	v_max_f32_e32 v30, 0, v30
	v_max_f32_e32 v26, 0, v26
	v_mul_f32_e32 v31, v27, v27
	v_max_f32_e32 v27, v32, v32
	v_mul_f32_e32 v32, v28, v28
	v_max_f32_e32 v28, v33, v33
	v_mul_f32_e32 v30, v30, v30
	v_mul_f32_e32 v26, v26, v26
	v_max_f32_e32 v27, 0, v27
	v_max_f32_e32 v28, 0, v28
	v_max_f32_e32 v29, v29, v29
	s_mov_b32 s8, 0x280000
	v_mul_f32_e32 v27, v27, v27
	v_max_f32_e32 v29, 0, v29
	v_mul_f32_e32 v28, v28, v28
	v_cvt_pk_bf16_f32 v26, v30, v26
	v_add_co_u32_e32 v30, vcc, s8, v140
	v_max_f32_e32 v18, v18, v18
	v_max_f32_e32 v19, v19, v19
	v_max_f32_e32 v20, v20, v20
	v_mul_f32_e32 v29, v29, v29
	v_cvt_pk_bf16_f32 v27, v27, v28
	v_cvt_pk_bf16_f32 v28, v36, v31
	v_addc_co_u32_e32 v31, vcc, 0, v141, vcc
	v_max_f32_e32 v18, 0, v18
	v_max_f32_e32 v19, 0, v19
	v_max_f32_e32 v20, 0, v20
	v_cvt_pk_bf16_f32 v29, v32, v29
	global_store_dwordx4 v[30:31], v[26:29], off nt
	v_max_f32_e32 v21, v21, v21
	s_mov_b64 s[38:39], 0x280000
	v_mul_f32_e32 v26, v18, v18
	v_max_f32_e32 v18, v23, v23
	v_mul_f32_e32 v23, v19, v19
	v_max_f32_e32 v19, v24, v24
	v_mul_f32_e32 v24, v20, v20
	v_max_f32_e32 v20, v25, v25
	v_max_f32_e32 v19, 0, v19
	v_max_f32_e32 v20, 0, v20
	v_max_f32_e32 v22, v22, v22
	v_max_f32_e32 v18, 0, v18
	v_mul_f32_e32 v19, v19, v19
	v_max_f32_e32 v21, 0, v21
	v_mul_f32_e32 v20, v20, v20
	v_max_f32_e32 v10, v10, v10
	v_lshl_add_u64 v[34:35], v[140:141], 0, s[38:39]
	v_max_f32_e32 v22, 0, v22
	v_mul_f32_e32 v18, v18, v18
	v_mul_f32_e32 v21, v21, v21
	v_cvt_pk_bf16_f32 v19, v19, v20
	v_cvt_pk_bf16_f32 v20, v26, v23
	v_max_f32_e32 v10, 0, v10
	v_max_f32_e32 v11, v11, v11
	v_max_f32_e32 v12, v12, v12
	v_mul_f32_e32 v22, v22, v22
	v_cvt_pk_bf16_f32 v18, v22, v18
	v_cvt_pk_bf16_f32 v21, v24, v21
	global_store_dwordx4 v[34:35], v[18:21], off offset:256 nt
	v_max_f32_e32 v14, v14, v14
	v_max_f32_e32 v11, 0, v11
	v_mul_f32_e32 v20, v10, v10
	v_max_f32_e32 v10, v15, v15
	v_max_f32_e32 v12, 0, v12
	v_max_f32_e32 v14, 0, v14
	v_max_f32_e32 v10, 0, v10
	v_mul_f32_e32 v15, v11, v11
	v_max_f32_e32 v11, v16, v16
	v_mul_f32_e32 v16, v12, v12
	v_max_f32_e32 v12, v17, v17
	v_mul_f32_e32 v14, v14, v14
	v_mul_f32_e32 v10, v10, v10
	v_max_f32_e32 v11, 0, v11
	v_max_f32_e32 v12, 0, v12
	v_max_f32_e32 v13, v13, v13
	s_mov_b32 s8, 0x2c0000
	v_mul_f32_e32 v11, v11, v11
	v_max_f32_e32 v13, 0, v13
	v_mul_f32_e32 v12, v12, v12
	v_cvt_pk_bf16_f32 v10, v14, v10
	v_add_co_u32_e32 v14, vcc, s8, v140
	v_max_f32_e32 v2, v2, v2
	v_max_f32_e32 v3, v3, v3
	v_max_f32_e32 v4, v4, v4
	v_mul_f32_e32 v13, v13, v13
	v_cvt_pk_bf16_f32 v11, v11, v12
	v_cvt_pk_bf16_f32 v12, v20, v15
	v_addc_co_u32_e32 v15, vcc, 0, v141, vcc
	v_max_f32_e32 v2, 0, v2
	v_max_f32_e32 v3, 0, v3
	v_max_f32_e32 v4, 0, v4
	v_cvt_pk_bf16_f32 v13, v16, v13
	global_store_dwordx4 v[14:15], v[10:13], off nt
	v_max_f32_e32 v5, v5, v5
	s_mov_b64 s[38:39], 0x2c0000
	v_mul_f32_e32 v10, v2, v2
	v_max_f32_e32 v2, v7, v7
	v_mul_f32_e32 v7, v3, v3
	v_max_f32_e32 v3, v8, v8
	v_mul_f32_e32 v8, v4, v4
	v_max_f32_e32 v4, v9, v9
	v_max_f32_e32 v6, v6, v6
	v_max_f32_e32 v2, 0, v2
	v_max_f32_e32 v3, 0, v3
	v_max_f32_e32 v4, 0, v4
	v_max_f32_e32 v5, 0, v5
	v_lshl_add_u64 v[18:19], v[140:141], 0, s[38:39]
	v_max_f32_e32 v6, 0, v6
	v_mul_f32_e32 v2, v2, v2
	v_mul_f32_e32 v3, v3, v3
	v_mul_f32_e32 v4, v4, v4
	v_mul_f32_e32 v5, v5, v5
	s_and_b64 vcc, exec, s[40:41]
	s_mov_b32 s68, s26
	s_mov_b32 s8, s28
	s_mov_b64 s[46:47], s[44:45]
	s_mov_b64 s[48:49], s[42:43]
	v_mul_f32_e32 v6, v6, v6
	v_cvt_pk_bf16_f32 v2, v6, v2
	v_cvt_pk_bf16_f32 v3, v3, v4
	v_cvt_pk_bf16_f32 v4, v10, v7
	v_cvt_pk_bf16_f32 v5, v8, v5
	global_store_dwordx4 v[18:19], v[2:5], off offset:256 nt
	s_cbranch_vccz .LBB0_70
	s_waitcnt vmcnt(0)
	s_cmpk_gt_u32 s52, 0xff
	s_cbranch_scc1 .LBB0_77
	s_barrier

; #define PG8_STAGE(bufoff, gbase, voff) do { _Pragma("unroll") for (int _i = 0; _i < 2; ++_i) \
;         __builtin_amdgcn_global_load_lds((const unsigned*)((const char*)(gbase) + (voff)[_i]), (LAS unsigned*)(lds + (bufoff) + ldsw + _i * 8192), 16, 0, 0); } while (0)
; #define PG8_LDA(dst, b, h) do { _Pragma("unroll") for (int m = 0; m < 4; ++m) _Pragma("unroll") for (int k = 0; k < 2; ++k) dst[m][k] = *(const LAS bf16x8*)(lds + PG8_SA(b, h) + aoff + m * 2048 + k * 1024); } while (0)
; #define PG8_LDB(dst, b, h) do { _Pragma("unroll") for (int n = 0; n < 2; ++n) _Pragma("unroll") for (int k = 0; k < 2; ++k) dst[n][k] = *(const LAS bf16x8*)(lds + PG8_SB(b, h) + boff + n * 2048 + k * 1024); } while (0)
; #define PG8_SCHED __builtin_amdgcn_sched_barrier(0)
; template <class Epi, class Sched>
; __device__ __forceinline__ void gemm_phase(LAS unsigned char* lds, const Gemm g, const Sched& S, const Epi& E) {
;     ...
;         const bool has_next = S.next(ui + 1, nxt);
;         const char* nA = has_next ? (const char*)g.A + (size_t)nxt.pm * tstep + (size_t)nxt.ks * sstep : cA; const char* nB = has_next ? (const char*)g.Bt + (size_t)nxt.pn * tstep + (size_t)nxt.ks * sstep : cB;
;         for (int t = 0; t < nt; t += 2) {
;             const bool last = (t == nt - 2);
;             const char* a1 = cA + (size_t)(t + 1) * kstep;
;             const char* a2 = last ? nA : cA + (size_t)(t + 2) * kstep; const char* b2 = last ? nB : cB + (size_t)(t + 2) * kstep;
;             const char* a3 = a2 + kstep; const char* b3 = b2 + kstep;
;             PG8_LDB(B0, 0, 0); PG8_SCHED; PG8_LDA(At, 0, 0); PG8_STAGE(PG8_SA(1, 1), a1 + hstep, voffA);
;     ...
; #pragma unroll
;         for (int a = 0; a < 2; ++a)
; #pragma unroll
;             for (int b = 0; b < 2; ++b)
; #pragma unroll
;                 for (int m = 0; m < 4; ++m)
; #pragma unroll
;                     for (int n = 0; n < 2; ++n) acc[a][b][m][n] = (f32x4){0.f, 0.f, 0.f, 0.f};
;         cur = nxt; cA = nA; cB = nB; ++ui;
.LBB0_98:
	s_ashr_i32 s51, s50, 31
	s_lshl_b64 s[38:39], s[50:51], 20
	v_cmp_lt_i64_e32 vcc, s[52:53], v[158:159]
	s_add_u32 s52, s10, s38
	s_addc_u32 s53, s11, s39
	s_and_b64 s[38:39], vcc, exec
	s_cselect_b32 s51, s53, s29
	s_cselect_b32 s77, s52, s28
	s_ashr_i32 s49, s48, 31
	s_lshl_b64 s[38:39], s[48:49], 20
	s_add_u32 s54, s13, s38
	s_addc_u32 s55, s62, s39
	s_and_b64 s[38:39], vcc, exec
	s_cselect_b32 s49, s55, s57
	s_cselect_b32 s78, s54, s56
	s_add_u32 s79, s56, 0x100
	v_mov_b32_e32 v2, 0
	s_addc_u32 s80, s57, 0
	s_mov_b32 s81, -2
	v_mov_b32_e32 v3, v2
	v_mov_b32_e32 v4, v2
	v_mov_b32_e32 v5, v2
	v_mov_b32_e32 v6, v2
	v_mov_b32_e32 v7, v2
	v_mov_b32_e32 v8, v2
	v_mov_b32_e32 v9, v2
	v_mov_b32_e32 v10, v2
	v_mov_b32_e32 v11, v2
	v_mov_b32_e32 v12, v2
	v_mov_b32_e32 v13, v2
	v_mov_b32_e32 v14, v2
	v_mov_b32_e32 v15, v2
	v_mov_b32_e32 v16, v2
	v_mov_b32_e32 v17, v2
	v_mov_b32_e32 v34, v2
	v_mov_b32_e32 v35, v2
	v_mov_b32_e32 v36, v2
	v_mov_b32_e32 v37, v2
	v_mov_b32_e32 v38, v2
	v_mov_b32_e32 v39, v2
	v_mov_b32_e32 v40, v2
	v_mov_b32_e32 v41, v2
	v_mov_b32_e32 v50, v2
	v_mov_b32_e32 v51, v2
	v_mov_b32_e32 v52, v2
	v_mov_b32_e32 v53, v2
	v_mov_b32_e32 v54, v2
	v_mov_b32_e32 v55, v2
	v_mov_b32_e32 v56, v2
	v_mov_b32_e32 v57, v2
	v_mov_b32_e32 v18, v2
	v_mov_b32_e32 v19, v2
	v_mov_b32_e32 v20, v2
	v_mov_b32_e32 v21, v2
	s_waitcnt vmcnt(0)
	v_mov_b32_e32 v22, v2
	v_mov_b32_e32 v23, v2
	v_mov_b32_e32 v24, v2
	v_mov_b32_e32 v25, v2
	v_mov_b32_e32 v26, v2
	v_mov_b32_e32 v27, v2
	v_mov_b32_e32 v28, v2
	v_mov_b32_e32 v29, v2
	v_mov_b32_e32 v30, v2
	v_mov_b32_e32 v31, v2
	v_mov_b32_e32 v32, v2
	v_mov_b32_e32 v33, v2
	v_mov_b32_e32 v42, v2
	v_mov_b32_e32 v43, v2
	v_mov_b32_e32 v44, v2
	v_mov_b32_e32 v45, v2
	v_mov_b32_e32 v46, v2
	v_mov_b32_e32 v47, v2
	v_mov_b32_e32 v48, v2
	v_mov_b32_e32 v49, v2
	v_mov_b32_e32 v58, v2
	v_mov_b32_e32 v59, v2
	v_mov_b32_e32 v60, v2
	v_mov_b32_e32 v61, v2
	v_mov_b32_e32 v62, v2
	v_mov_b32_e32 v63, v2
	v_mov_b32_e32 v64, v2
	v_mov_b32_e32 v65, v2
	v_mov_b32_e32 v66, v2
	v_mov_b32_e32 v67, v2
	v_mov_b32_e32 v68, v2
	v_mov_b32_e32 v69, v2
	v_mov_b32_e32 v70, v2
	v_mov_b32_e32 v71, v2
	v_mov_b32_e32 v72, v2
	v_mov_b32_e32 v73, v2
	v_mov_b32_e32 v74, v2
	v_mov_b32_e32 v75, v2
	v_mov_b32_e32 v76, v2
	v_mov_b32_e32 v77, v2
	v_mov_b32_e32 v78, v2
	v_mov_b32_e32 v79, v2
	v_mov_b32_e32 v80, v2
	v_mov_b32_e32 v81, v2
	v_mov_b32_e32 v114, v2
	v_mov_b32_e32 v115, v2
	v_mov_b32_e32 v116, v2
	v_mov_b32_e32 v117, v2
	v_mov_b32_e32 v118, v2
	v_mov_b32_e32 v119, v2
	v_mov_b32_e32 v120, v2
	v_mov_b32_e32 v121, v2
	v_mov_b32_e32 v130, v2
	v_mov_b32_e32 v131, v2
	v_mov_b32_e32 v132, v2
	v_mov_b32_e32 v133, v2
	v_mov_b32_e32 v134, v2
	v_mov_b32_e32 v135, v2
	v_mov_b32_e32 v136, v2
	v_mov_b32_e32 v137, v2
	v_mov_b32_e32 v82, v2
	v_mov_b32_e32 v83, v2
	v_mov_b32_e32 v84, v2
	v_mov_b32_e32 v85, v2
	v_mov_b32_e32 v86, v2
	v_mov_b32_e32 v87, v2
	v_mov_b32_e32 v88, v2
	v_mov_b32_e32 v89, v2
	v_mov_b32_e32 v90, v2
	v_mov_b32_e32 v91, v2
	v_mov_b32_e32 v92, v2
	v_mov_b32_e32 v93, v2
	v_mov_b32_e32 v94, v2
	v_mov_b32_e32 v95, v2
	v_mov_b32_e32 v96, v2
	v_mov_b32_e32 v97, v2
	v_mov_b32_e32 v122, v2
	v_mov_b32_e32 v123, v2
	v_mov_b32_e32 v124, v2
	v_mov_b32_e32 v125, v2
	v_mov_b32_e32 v126, v2
	v_mov_b32_e32 v127, v2
	v_mov_b32_e32 v128, v2
	v_mov_b32_e32 v129, v2
	v_mov_b32_e32 v138, v2
	v_mov_b32_e32 v139, v2
	v_mov_b32_e32 v140, v2
	v_mov_b32_e32 v141, v2
	v_mov_b32_e32 v142, v2
	v_mov_b32_e32 v143, v2
	v_mov_b32_e32 v144, v2
	v_mov_b32_e32 v145, v2
	s_add_u32 s56, s28, 0x100
	s_addc_u32 s57, s29, 0
	s_cmp_eq_u32 s81, 28
	s_cselect_b32 s61, s51, s57
	s_cselect_b32 s60, s77, s56
	s_cselect_b32 s59, s49, s80
	s_cselect_b32 s58, s78, s79
.LBB0_99:
	s_add_i32 m0, s9, 0xc000
	ds_read_b128 v[98:101], v226
	global_load_lds_dwordx4 v150, s[28:29]
	s_add_i32 m0, s9, 0xe000
	ds_read_b128 v[102:105], v226 offset:1024
	global_load_lds_dwordx4 v148, s[28:29]
	s_add_i32 s38, 0, 0x10000
	ds_read_b128 v[106:109], v226 offset:2048
	ds_read_b128 v[110:113], v226 offset:3072
	ds_read_b128 v[152:155], v171
	ds_read_b128 v[160:163], v171 offset:1024
	ds_read_b128 v[164:167], v171 offset:2048
	ds_read_b128 v[172:175], v171 offset:3072
	ds_read_b128 v[176:179], v171 offset:4096
	ds_read_b128 v[180:183], v171 offset:5120
	ds_read_b128 v[184:187], v171 offset:6144
	ds_read_b128 v[188:191], v171 offset:7168
	s_add_i32 s39, 0, 0x14000
	ds_read_b128 v[192:195], v226 offset:16384
	ds_read_b128 v[196:199], v226 offset:17408
	ds_read_b128 v[200:203], v226 offset:18432
	ds_read_b128 v[204:207], v226 offset:19456
	s_waitcnt lgkmcnt(4)
	s_barrier
; #define PG8_STAGE(bufoff, gbase, voff) do { _Pragma("unroll") for (int _i = 0; _i < 2; ++_i) \
;         __builtin_amdgcn_global_load_lds((const unsigned*)((const char*)(gbase) + (voff)[_i]), (LAS unsigned*)(lds + (bufoff) + ldsw + _i * 8192), 16, 0, 0); } while (0)
; #define PG8_LDA(dst, b, h) do { _Pragma("unroll") for (int m = 0; m < 4; ++m) _Pragma("unroll") for (int k = 0; k < 2; ++k) dst[m][k] = *(const LAS bf16x8*)(lds + PG8_SA(b, h) + aoff + m * 2048 + k * 1024); } while (0)
; #define PG8_LDB(dst, b, h) do { _Pragma("unroll") for (int n = 0; n < 2; ++n) _Pragma("unroll") for (int k = 0; k < 2; ++k) dst[n][k] = *(const LAS bf16x8*)(lds + PG8_SB(b, h) + boff + n * 2048 + k * 1024); } while (0)
; #define PG8_MMA(ai, bj, At, Bt) do { __builtin_amdgcn_s_setprio(1); _Pragma("unroll") for (int m = 0; m < 4; ++m) _Pragma("unroll") for (int n = 0; n < 2; ++n) _Pragma("unroll") for (int k = 0; k < 2; ++k) \
;         acc[ai][bj][m][n] = __builtin_amdgcn_mfma_f32_16x16x32_bf16(Bt[n][k], At[m][k], acc[ai][bj][m][n], 0, 0, 0); __builtin_amdgcn_s_setprio(0); } while (0)
; #define PG8_WAIT_V(n) asm volatile("s_waitcnt vmcnt(" #n ")" ::: "memory")
; #define PG8_WAIT_L(n) asm volatile("s_waitcnt lgkmcnt(" #n ")" ::: "memory")
; #define PG8_BAR __builtin_amdgcn_s_barrier()
; #define PG8_SCHED __builtin_amdgcn_sched_barrier(0)
; template <class Epi, class Sched>
; __device__ __forceinline__ void gemm_phase(LAS unsigned char* lds, const Gemm g, const Sched& S, const Epi& E) {
;     ...
;             PG8_LDB(B0, 0, 0); PG8_SCHED; PG8_LDA(At, 0, 0); PG8_STAGE(PG8_SA(1, 1), a1 + hstep, voffA);
;             PG8_WAIT_L(8); PG8_BAR; PG8_WAIT_L(0); PG8_MMA(0, 0, At, B0); PG8_BAR; PG8_SCHED;
;             PG8_LDB(B1, 0, 1); PG8_STAGE(PG8_SB(0, 0), b2, voffB);
;             PG8_BAR; PG8_WAIT_L(0); PG8_MMA(0, 1, At, B1); PG8_BAR;
;             PG8_LDA(At, 0, 1); PG8_STAGE(PG8_SA(0, 0), a2, voffA);
;             PG8_BAR; PG8_WAIT_L(0); PG8_MMA(1, 0, At, B0); PG8_BAR; PG8_SCHED;
;             PG8_STAGE(PG8_SB(0, 1), b2 + hstep, voffB);
;             PG8_WAIT_V(6); PG8_BAR; PG8_MMA(1, 1, At, B1); PG8_BAR;
	s_waitcnt lgkmcnt(0)
	v_mfma_f32_16x16x32_bf16 v[142:145], v[98:101], v[152:155], v[142:145]
	v_mfma_f32_16x16x32_bf16 v[138:141], v[106:109], v[152:155], v[138:141]
	v_mfma_f32_16x16x32_bf16 v[126:129], v[98:101], v[164:167], v[126:129]
	v_mfma_f32_16x16x32_bf16 v[122:125], v[106:109], v[164:167], v[122:125]
	v_mfma_f32_16x16x32_bf16 v[94:97], v[98:101], v[176:179], v[94:97]
	v_mfma_f32_16x16x32_bf16 v[90:93], v[106:109], v[176:179], v[90:93]
	v_mfma_f32_16x16x32_bf16 v[86:89], v[98:101], v[184:187], v[86:89]
	v_mfma_f32_16x16x32_bf16 v[82:85], v[106:109], v[184:187], v[82:85]
	v_mfma_f32_16x16x32_bf16 v[142:145], v[102:105], v[160:163], v[142:145]
	v_mfma_f32_16x16x32_bf16 v[138:141], v[110:113], v[160:163], v[138:141]
	v_mfma_f32_16x16x32_bf16 v[126:129], v[102:105], v[172:175], v[126:129]
	v_mfma_f32_16x16x32_bf16 v[122:125], v[110:113], v[172:175], v[122:125]
	v_mfma_f32_16x16x32_bf16 v[94:97], v[102:105], v[180:183], v[94:97]
	v_mfma_f32_16x16x32_bf16 v[90:93], v[110:113], v[180:183], v[90:93]
	v_mfma_f32_16x16x32_bf16 v[86:89], v[102:105], v[188:191], v[86:89]
	v_mfma_f32_16x16x32_bf16 v[82:85], v[110:113], v[188:191], v[82:85]
	v_mfma_f32_16x16x32_bf16 v[134:137], v[192:195], v[152:155], v[134:137]
	v_mfma_f32_16x16x32_bf16 v[130:133], v[200:203], v[152:155], v[130:133]
	v_mfma_f32_16x16x32_bf16 v[118:121], v[192:195], v[164:167], v[118:121]
	v_mfma_f32_16x16x32_bf16 v[114:117], v[200:203], v[164:167], v[114:117]
	v_mfma_f32_16x16x32_bf16 v[78:81], v[192:195], v[176:179], v[78:81]
	v_mfma_f32_16x16x32_bf16 v[74:77], v[200:203], v[176:179], v[74:77]
	v_mfma_f32_16x16x32_bf16 v[70:73], v[192:195], v[184:187], v[70:73]
	v_mfma_f32_16x16x32_bf16 v[66:69], v[200:203], v[184:187], v[66:69]
	v_mfma_f32_16x16x32_bf16 v[134:137], v[196:199], v[160:163], v[134:137]
	v_mfma_f32_16x16x32_bf16 v[130:133], v[204:207], v[160:163], v[130:133]
	v_mfma_f32_16x16x32_bf16 v[118:121], v[196:199], v[172:175], v[118:121]
	v_mfma_f32_16x16x32_bf16 v[114:117], v[204:207], v[172:175], v[114:117]
	v_mfma_f32_16x16x32_bf16 v[78:81], v[196:199], v[180:183], v[78:81]
	v_mfma_f32_16x16x32_bf16 v[74:77], v[204:207], v[180:183], v[74:77]
	v_mfma_f32_16x16x32_bf16 v[70:73], v[196:199], v[188:191], v[70:73]
	v_mfma_f32_16x16x32_bf16 v[66:69], v[204:207], v[188:191], v[66:69]
	s_barrier
	s_add_i32 s28, s38, s67
	s_mov_b32 m0, s28
	ds_read_b128 v[152:155], v171 offset:16384
	global_load_lds_dwordx4 v0, s[58:59]
	s_add_i32 m0, s28, 0x2000
	ds_read_b128 v[160:163], v171 offset:17408
	global_load_lds_dwordx4 v146, s[58:59]
	s_mov_b32 m0, s9
	ds_read_b128 v[164:167], v171 offset:18432
	global_load_lds_dwordx4 v0, s[60:61]
	s_mov_b32 m0, s68
	ds_read_b128 v[172:175], v171 offset:19456
	global_load_lds_dwordx4 v146, s[60:61]
	ds_read_b128 v[176:179], v171 offset:20480
	ds_read_b128 v[180:183], v171 offset:21504
	ds_read_b128 v[184:187], v171 offset:22528
	ds_read_b128 v[188:191], v171 offset:23552
	s_waitcnt vmcnt(4)
	s_waitcnt lgkmcnt(0)
	s_barrier
	v_mfma_f32_16x16x32_bf16 v[62:65], v[98:101], v[152:155], v[62:65]
	v_mfma_f32_16x16x32_bf16 v[58:61], v[106:109], v[152:155], v[58:61]
	v_mfma_f32_16x16x32_bf16 v[46:49], v[98:101], v[164:167], v[46:49]
	v_mfma_f32_16x16x32_bf16 v[42:45], v[106:109], v[164:167], v[42:45]
	v_mfma_f32_16x16x32_bf16 v[30:33], v[98:101], v[176:179], v[30:33]
	v_mfma_f32_16x16x32_bf16 v[26:29], v[106:109], v[176:179], v[26:29]
	v_mfma_f32_16x16x32_bf16 v[22:25], v[98:101], v[184:187], v[22:25]
	v_mfma_f32_16x16x32_bf16 v[18:21], v[106:109], v[184:187], v[18:21]
	v_mfma_f32_16x16x32_bf16 v[62:65], v[102:105], v[160:163], v[62:65]
	v_mfma_f32_16x16x32_bf16 v[58:61], v[110:113], v[160:163], v[58:61]
	v_mfma_f32_16x16x32_bf16 v[46:49], v[102:105], v[172:175], v[46:49]
	v_mfma_f32_16x16x32_bf16 v[42:45], v[110:113], v[172:175], v[42:45]
	v_mfma_f32_16x16x32_bf16 v[30:33], v[102:105], v[180:183], v[30:33]
	v_mfma_f32_16x16x32_bf16 v[26:29], v[110:113], v[180:183], v[26:29]
	v_mfma_f32_16x16x32_bf16 v[22:25], v[102:105], v[188:191], v[22:25]
	v_mfma_f32_16x16x32_bf16 v[18:21], v[110:113], v[188:191], v[18:21]
	v_mfma_f32_16x16x32_bf16 v[54:57], v[192:195], v[152:155], v[54:57]
	v_mfma_f32_16x16x32_bf16 v[50:53], v[200:203], v[152:155], v[50:53]
	v_mfma_f32_16x16x32_bf16 v[38:41], v[192:195], v[164:167], v[38:41]
	v_mfma_f32_16x16x32_bf16 v[34:37], v[200:203], v[164:167], v[34:37]
	v_mfma_f32_16x16x32_bf16 v[14:17], v[192:195], v[176:179], v[14:17]
	v_mfma_f32_16x16x32_bf16 v[10:13], v[200:203], v[176:179], v[10:13]
	v_mfma_f32_16x16x32_bf16 v[6:9], v[192:195], v[184:187], v[6:9]
	v_mfma_f32_16x16x32_bf16 v[2:5], v[200:203], v[184:187], v[2:5]
	v_mfma_f32_16x16x32_bf16 v[54:57], v[196:199], v[160:163], v[54:57]
	v_mfma_f32_16x16x32_bf16 v[50:53], v[204:207], v[160:163], v[50:53]
	v_mfma_f32_16x16x32_bf16 v[38:41], v[196:199], v[172:175], v[38:41]
	v_mfma_f32_16x16x32_bf16 v[34:37], v[204:207], v[172:175], v[34:37]
	v_mfma_f32_16x16x32_bf16 v[14:17], v[196:199], v[180:183], v[14:17]
	v_mfma_f32_16x16x32_bf16 v[10:13], v[204:207], v[180:183], v[10:13]
	v_mfma_f32_16x16x32_bf16 v[6:9], v[196:199], v[188:191], v[6:9]
	v_mfma_f32_16x16x32_bf16 v[2:5], v[204:207], v[188:191], v[2:5]
	s_barrier
; #define PG8_STAGE(bufoff, gbase, voff) do { _Pragma("unroll") for (int _i = 0; _i < 2; ++_i) \
;         __builtin_amdgcn_global_load_lds((const unsigned*)((const char*)(gbase) + (voff)[_i]), (LAS unsigned*)(lds + (bufoff) + ldsw + _i * 8192), 16, 0, 0); } while (0)
; #define PG8_LDA(dst, b, h) do { _Pragma("unroll") for (int m = 0; m < 4; ++m) _Pragma("unroll") for (int k = 0; k < 2; ++k) dst[m][k] = *(const LAS bf16x8*)(lds + PG8_SA(b, h) + aoff + m * 2048 + k * 1024); } while (0)
; #define PG8_LDB(dst, b, h) do { _Pragma("unroll") for (int n = 0; n < 2; ++n) _Pragma("unroll") for (int k = 0; k < 2; ++k) dst[n][k] = *(const LAS bf16x8*)(lds + PG8_SB(b, h) + boff + n * 2048 + k * 1024); } while (0)
; #define PG8_MMA(ai, bj, At, Bt) do { __builtin_amdgcn_s_setprio(1); _Pragma("unroll") for (int m = 0; m < 4; ++m) _Pragma("unroll") for (int n = 0; n < 2; ++n) _Pragma("unroll") for (int k = 0; k < 2; ++k) \
;         acc[ai][bj][m][n] = __builtin_amdgcn_mfma_f32_16x16x32_bf16(Bt[n][k], At[m][k], acc[ai][bj][m][n], 0, 0, 0); __builtin_amdgcn_s_setprio(0); } while (0)
; #define PG8_WAIT_L(n) asm volatile("s_waitcnt lgkmcnt(" #n ")" ::: "memory")
; #define PG8_BAR __builtin_amdgcn_s_barrier()
; #define PG8_SCHED __builtin_amdgcn_sched_barrier(0)
; template <class Epi, class Sched>
; __device__ __forceinline__ void gemm_phase(LAS unsigned char* lds, const Gemm g, const Sched& S, const Epi& E) {
;     ...
;             PG8_LDB(B0, 1, 0); PG8_SCHED; PG8_LDA(At, 1, 0); PG8_STAGE(PG8_SA(0, 1), a2 + hstep, voffA);
;             PG8_WAIT_L(8); PG8_BAR; PG8_WAIT_L(0); PG8_MMA(0, 0, At, B0); PG8_BAR; PG8_SCHED;
;             PG8_LDB(B1, 1, 1); PG8_STAGE(PG8_SB(1, 0), b3, voffB);
;             PG8_BAR; PG8_WAIT_L(0); PG8_MMA(0, 1, At, B1); PG8_BAR;
;             PG8_LDA(At, 1, 1); PG8_STAGE(PG8_SA(1, 0), a3, voffA);
;             PG8_BAR; PG8_WAIT_L(0); PG8_MMA(1, 0, At, B0); PG8_BAR; PG8_SCHED;
	s_add_u32 s28, s58, 0x80000
	s_addc_u32 s29, s59, 0
	s_add_i32 s38, s39, s67
	s_mov_b32 m0, s38
	ds_read_b128 v[98:101], v226 offset:32768
	global_load_lds_dwordx4 v0, s[28:29]
	s_add_i32 m0, s38, 0x2000
	ds_read_b128 v[102:105], v226 offset:33792
	global_load_lds_dwordx4 v146, s[28:29]
	s_add_u32 s28, s60, 0x80000
	s_addc_u32 s29, s61, 0
	s_mov_b32 m0, s69
	ds_read_b128 v[106:109], v226 offset:34816
	global_load_lds_dwordx4 v0, s[28:29]
	s_mov_b32 m0, s70
	ds_read_b128 v[110:113], v226 offset:35840
	global_load_lds_dwordx4 v146, s[28:29]
	s_add_i32 s38, 0, 0x18000
	ds_read_b128 v[152:155], v171 offset:32768
	ds_read_b128 v[160:163], v171 offset:33792
	ds_read_b128 v[164:167], v171 offset:34816
	ds_read_b128 v[172:175], v171 offset:35840
	ds_read_b128 v[176:179], v171 offset:36864
	ds_read_b128 v[180:183], v171 offset:37888
	ds_read_b128 v[184:187], v171 offset:38912
	ds_read_b128 v[188:191], v171 offset:39936
	s_add_i32 s39, 0, 0x1c000
	ds_read_b128 v[192:195], v226 offset:49152
	ds_read_b128 v[196:199], v226 offset:50176
	ds_read_b128 v[200:203], v226 offset:51200
	ds_read_b128 v[204:207], v226 offset:52224
	s_waitcnt lgkmcnt(4)
	s_barrier
	s_waitcnt lgkmcnt(0)
	v_mfma_f32_16x16x32_bf16 v[142:145], v[98:101], v[152:155], v[142:145]
	v_mfma_f32_16x16x32_bf16 v[138:141], v[106:109], v[152:155], v[138:141]
	v_mfma_f32_16x16x32_bf16 v[126:129], v[98:101], v[164:167], v[126:129]
	v_mfma_f32_16x16x32_bf16 v[122:125], v[106:109], v[164:167], v[122:125]
	v_mfma_f32_16x16x32_bf16 v[94:97], v[98:101], v[176:179], v[94:97]
	v_mfma_f32_16x16x32_bf16 v[90:93], v[106:109], v[176:179], v[90:93]
	v_mfma_f32_16x16x32_bf16 v[86:89], v[98:101], v[184:187], v[86:89]
	v_mfma_f32_16x16x32_bf16 v[82:85], v[106:109], v[184:187], v[82:85]
	v_mfma_f32_16x16x32_bf16 v[142:145], v[102:105], v[160:163], v[142:145]
	v_mfma_f32_16x16x32_bf16 v[138:141], v[110:113], v[160:163], v[138:141]
	v_mfma_f32_16x16x32_bf16 v[126:129], v[102:105], v[172:175], v[126:129]
	v_mfma_f32_16x16x32_bf16 v[122:125], v[110:113], v[172:175], v[122:125]
	v_mfma_f32_16x16x32_bf16 v[94:97], v[102:105], v[180:183], v[94:97]
	v_mfma_f32_16x16x32_bf16 v[90:93], v[110:113], v[180:183], v[90:93]
	v_mfma_f32_16x16x32_bf16 v[86:89], v[102:105], v[188:191], v[86:89]
	v_mfma_f32_16x16x32_bf16 v[82:85], v[110:113], v[188:191], v[82:85]
	v_mfma_f32_16x16x32_bf16 v[134:137], v[192:195], v[152:155], v[134:137]
	v_mfma_f32_16x16x32_bf16 v[130:133], v[200:203], v[152:155], v[130:133]
	v_mfma_f32_16x16x32_bf16 v[118:121], v[192:195], v[164:167], v[118:121]
	v_mfma_f32_16x16x32_bf16 v[114:117], v[200:203], v[164:167], v[114:117]
	v_mfma_f32_16x16x32_bf16 v[78:81], v[192:195], v[176:179], v[78:81]
	v_mfma_f32_16x16x32_bf16 v[74:77], v[200:203], v[176:179], v[74:77]
	v_mfma_f32_16x16x32_bf16 v[70:73], v[192:195], v[184:187], v[70:73]
	v_mfma_f32_16x16x32_bf16 v[66:69], v[200:203], v[184:187], v[66:69]
	v_mfma_f32_16x16x32_bf16 v[134:137], v[196:199], v[160:163], v[134:137]
	v_mfma_f32_16x16x32_bf16 v[130:133], v[204:207], v[160:163], v[130:133]
	v_mfma_f32_16x16x32_bf16 v[118:121], v[196:199], v[172:175], v[118:121]
	v_mfma_f32_16x16x32_bf16 v[114:117], v[204:207], v[172:175], v[114:117]
	v_mfma_f32_16x16x32_bf16 v[78:81], v[196:199], v[180:183], v[78:81]
	v_mfma_f32_16x16x32_bf16 v[74:77], v[204:207], v[180:183], v[74:77]
	v_mfma_f32_16x16x32_bf16 v[70:73], v[196:199], v[188:191], v[70:73]
	v_mfma_f32_16x16x32_bf16 v[66:69], v[204:207], v[188:191], v[66:69]
	s_barrier
; #define PG8_STAGE(bufoff, gbase, voff) do { _Pragma("unroll") for (int _i = 0; _i < 2; ++_i) \
;         __builtin_amdgcn_global_load_lds((const unsigned*)((const char*)(gbase) + (voff)[_i]), (LAS unsigned*)(lds + (bufoff) + ldsw + _i * 8192), 16, 0, 0); } while (0)
; #define PG8_LDA(dst, b, h) do { _Pragma("unroll") for (int m = 0; m < 4; ++m) _Pragma("unroll") for (int k = 0; k < 2; ++k) dst[m][k] = *(const LAS bf16x8*)(lds + PG8_SA(b, h) + aoff + m * 2048 + k * 1024); } while (0)
; #define PG8_LDB(dst, b, h) do { _Pragma("unroll") for (int n = 0; n < 2; ++n) _Pragma("unroll") for (int k = 0; k < 2; ++k) dst[n][k] = *(const LAS bf16x8*)(lds + PG8_SB(b, h) + boff + n * 2048 + k * 1024); } while (0)
; #define PG8_MMA(ai, bj, At, Bt) do { __builtin_amdgcn_s_setprio(1); _Pragma("unroll") for (int m = 0; m < 4; ++m) _Pragma("unroll") for (int n = 0; n < 2; ++n) _Pragma("unroll") for (int k = 0; k < 2; ++k) \
;         acc[ai][bj][m][n] = __builtin_amdgcn_mfma_f32_16x16x32_bf16(Bt[n][k], At[m][k], acc[ai][bj][m][n], 0, 0, 0); __builtin_amdgcn_s_setprio(0); } while (0)
; #define PG8_BAR __builtin_amdgcn_s_barrier()
;     __device__ __forceinline__ void operator()(const f32x4 (&acc)[2][2][4][2], const Unit& u, int wr, int wc, int fr, int fq) const {
;         const bool lat = u.pm < 64; const int r = lat ? (u.pm >> 3) : 8;
;         const float* s = lat ? src_lat : src_ctx; float* d = lat ? dst_lat : dst_ctx;
;         const int row0 = (lat ? u.pm : u.pm - 64) * BM + wr * 64 + fr, col0 = u.pn * BM + wc * 32 + 4 * fq;
; template <class Epi, class Sched>
; __device__ __forceinline__ void gemm_phase(LAS unsigned char* lds, const Gemm g, const Sched& S, const Epi& E) {
;     ...
;             PG8_WAIT_V(6); PG8_BAR; PG8_MMA(1, 1, At, B1); PG8_BAR;
;             PG8_LDB(B0, 1, 0); PG8_SCHED; PG8_LDA(At, 1, 0); PG8_STAGE(PG8_SA(0, 1), a2 + hstep, voffA);
;             PG8_WAIT_L(8); PG8_BAR; PG8_WAIT_L(0); PG8_MMA(0, 0, At, B0); PG8_BAR; PG8_SCHED;
;             PG8_LDB(B1, 1, 1); PG8_STAGE(PG8_SB(1, 0), b3, voffB);
;             PG8_BAR; PG8_WAIT_L(0); PG8_MMA(0, 1, At, B1); PG8_BAR;
;             PG8_LDA(At, 1, 1); PG8_STAGE(PG8_SA(1, 0), a3, voffA);
;             PG8_BAR; PG8_WAIT_L(0); PG8_MMA(1, 0, At, B0); PG8_BAR; PG8_SCHED;
;             PG8_STAGE(PG8_SB(1, 1), b3 + hstep, voffB);
;             PG8_WAIT_V(6); PG8_BAR; PG8_MMA(1, 1, At, B1); PG8_BAR;
	s_add_i32 s28, s38, s67
	s_add_u32 s100, s58, s36
	s_addc_u32 s101, s59, s37
	s_mov_b32 m0, s28
	ds_read_b128 v[152:155], v171 offset:49152
	global_load_lds_dwordx4 v0, s[100:101]
	s_add_i32 m0, s28, 0x2000
	ds_read_b128 v[160:163], v171 offset:50176
	global_load_lds_dwordx4 v146, s[100:101]
	s_mov_b32 m0, s72
	s_add_u32 s100, s60, s36
	s_addc_u32 s101, s61, s37
	global_load_lds_dwordx4 v0, s[100:101]
	s_mov_b32 m0, s73
	ds_read_b128 v[164:167], v171 offset:51200
	global_load_lds_dwordx4 v146, s[100:101]
	ds_read_b128 v[172:175], v171 offset:52224
	ds_read_b128 v[176:179], v171 offset:53248
	ds_read_b128 v[180:183], v171 offset:54272
	ds_read_b128 v[184:187], v171 offset:55296
	ds_read_b128 v[188:191], v171 offset:56320
	s_waitcnt vmcnt(4)
	s_waitcnt lgkmcnt(0)
	s_barrier
	v_mfma_f32_16x16x32_bf16 v[62:65], v[98:101], v[152:155], v[62:65]
	v_mfma_f32_16x16x32_bf16 v[58:61], v[106:109], v[152:155], v[58:61]
	v_mfma_f32_16x16x32_bf16 v[46:49], v[98:101], v[164:167], v[46:49]
	v_mfma_f32_16x16x32_bf16 v[42:45], v[106:109], v[164:167], v[42:45]
	v_mfma_f32_16x16x32_bf16 v[30:33], v[98:101], v[176:179], v[30:33]
	v_mfma_f32_16x16x32_bf16 v[26:29], v[106:109], v[176:179], v[26:29]
	v_mfma_f32_16x16x32_bf16 v[22:25], v[98:101], v[184:187], v[22:25]
	v_mfma_f32_16x16x32_bf16 v[18:21], v[106:109], v[184:187], v[18:21]
	v_mfma_f32_16x16x32_bf16 v[62:65], v[102:105], v[160:163], v[62:65]
	v_mfma_f32_16x16x32_bf16 v[58:61], v[110:113], v[160:163], v[58:61]
	v_mfma_f32_16x16x32_bf16 v[46:49], v[102:105], v[172:175], v[46:49]
	v_mfma_f32_16x16x32_bf16 v[42:45], v[110:113], v[172:175], v[42:45]
	v_mfma_f32_16x16x32_bf16 v[30:33], v[102:105], v[180:183], v[30:33]
	v_mfma_f32_16x16x32_bf16 v[26:29], v[110:113], v[180:183], v[26:29]
	v_mfma_f32_16x16x32_bf16 v[22:25], v[102:105], v[188:191], v[22:25]
	v_mfma_f32_16x16x32_bf16 v[18:21], v[110:113], v[188:191], v[18:21]
	s_add_u32 s28, s58, 0x80080
	s_addc_u32 s29, s59, 0
	s_add_i32 s38, s39, s67
	s_mov_b32 m0, s38
	s_nop 0
	global_load_lds_dwordx4 v0, s[28:29]
	s_add_i32 m0, s38, 0x2000
	s_nop 0
	global_load_lds_dwordx4 v146, s[28:29]
	v_mfma_f32_16x16x32_bf16 v[54:57], v[192:195], v[152:155], v[54:57]
	v_mfma_f32_16x16x32_bf16 v[50:53], v[200:203], v[152:155], v[50:53]
	v_mfma_f32_16x16x32_bf16 v[38:41], v[192:195], v[164:167], v[38:41]
	v_mfma_f32_16x16x32_bf16 v[34:37], v[200:203], v[164:167], v[34:37]
	v_mfma_f32_16x16x32_bf16 v[14:17], v[192:195], v[176:179], v[14:17]
	v_mfma_f32_16x16x32_bf16 v[10:13], v[200:203], v[176:179], v[10:13]
	v_mfma_f32_16x16x32_bf16 v[6:9], v[192:195], v[184:187], v[6:9]
	v_mfma_f32_16x16x32_bf16 v[2:5], v[200:203], v[184:187], v[2:5]
	v_mfma_f32_16x16x32_bf16 v[54:57], v[196:199], v[160:163], v[54:57]
	v_mfma_f32_16x16x32_bf16 v[50:53], v[204:207], v[160:163], v[50:53]
	v_mfma_f32_16x16x32_bf16 v[38:41], v[196:199], v[172:175], v[38:41]
	v_mfma_f32_16x16x32_bf16 v[34:37], v[204:207], v[172:175], v[34:37]
	v_mfma_f32_16x16x32_bf16 v[14:17], v[196:199], v[180:183], v[14:17]
	v_mfma_f32_16x16x32_bf16 v[10:13], v[204:207], v[180:183], v[10:13]
	v_mfma_f32_16x16x32_bf16 v[6:9], v[196:199], v[188:191], v[6:9]
	v_mfma_f32_16x16x32_bf16 v[2:5], v[204:207], v[188:191], v[2:5]
	s_add_i32 s81, s81, 2
	s_add_u32 s79, s79, 0x100
	s_addc_u32 s80, s80, 0
	s_mov_b64 s[28:29], s[56:57]
	s_add_u32 s56, s28, 0x100
	s_addc_u32 s57, s29, 0
	s_cmp_eq_u32 s81, 28
	s_cselect_b32 s61, s51, s57
	s_cselect_b32 s60, s77, s56
	s_cselect_b32 s59, s49, s80
	s_cselect_b32 s58, s78, s79
	s_cmp_gt_u32 s81, 29
	s_barrier
	s_cbranch_scc0 .LBB0_99
	s_cmp_lt_i32 s8, 64
	s_cselect_b64 s[58:59], -1, 0
	s_cmp_gt_i32 s8, 63
	s_cbranch_scc0 .LBB0_90
	s_mov_b64 s[60:61], 0x18000
	s_mov_b64 s[28:29], s[46:47]
	s_mov_b64 s[56:57], s[24:25]
	s_branch .LBB0_91

; #define PG8_STAGE(bufoff, gbase, voff) do { _Pragma("unroll") for (int _i = 0; _i < 2; ++_i) \
;         __builtin_amdgcn_global_load_lds((const unsigned*)((const char*)(gbase) + (voff)[_i]), (LAS unsigned*)(lds + (bufoff) + ldsw + _i * 8192), 16, 0, 0); } while (0)
; #define PG8_LDA(dst, b, h) do { _Pragma("unroll") for (int m = 0; m < 4; ++m) _Pragma("unroll") for (int k = 0; k < 2; ++k) dst[m][k] = *(const LAS bf16x8*)(lds + PG8_SA(b, h) + aoff + m * 2048 + k * 1024); } while (0)
; #define PG8_LDB(dst, b, h) do { _Pragma("unroll") for (int n = 0; n < 2; ++n) _Pragma("unroll") for (int k = 0; k < 2; ++k) dst[n][k] = *(const LAS bf16x8*)(lds + PG8_SB(b, h) + boff + n * 2048 + k * 1024); } while (0)
; #define PG8_SCHED __builtin_amdgcn_sched_barrier(0)
; template <class Epi, class Sched>
; __device__ __forceinline__ void gemm_phase(LAS unsigned char* lds, const Gemm g, const Sched& S, const Epi& E) {
;     ...
;         const bool has_next = S.next(ui + 1, nxt);
;         const char* nA = has_next ? (const char*)g.A + (size_t)nxt.pm * tstep + (size_t)nxt.ks * sstep : cA; const char* nB = has_next ? (const char*)g.Bt + (size_t)nxt.pn * tstep + (size_t)nxt.ks * sstep : cB;
;         for (int t = 0; t < nt; t += 2) {
;             const bool last = (t == nt - 2);
;             const char* a1 = cA + (size_t)(t + 1) * kstep;
;             const char* a2 = last ? nA : cA + (size_t)(t + 2) * kstep; const char* b2 = last ? nB : cB + (size_t)(t + 2) * kstep;
;             const char* a3 = a2 + kstep; const char* b3 = b2 + kstep;
;             PG8_LDB(B0, 0, 0); PG8_SCHED; PG8_LDA(At, 0, 0); PG8_STAGE(PG8_SA(1, 1), a1 + hstep, voffA);
;     ...
; #pragma unroll
;         for (int a = 0; a < 2; ++a)
; #pragma unroll
;             for (int b = 0; b < 2; ++b)
; #pragma unroll
;                 for (int m = 0; m < 4; ++m)
; #pragma unroll
;                     for (int n = 0; n < 2; ++n) acc[a][b][m][n] = (f32x4){0.f, 0.f, 0.f, 0.f};
;         cur = nxt; cA = nA; cB = nB; ++ui;
.LBB0_112:
	s_ashr_i32 s45, s44, 31
	s_lshl_b64 s[38:39], s[44:45], 20
	s_add_u32 s11, s61, s38
	s_addc_u32 s41, s64, s39
	s_ashr_i32 s29, s28, 31
	s_lshl_b64 s[38:39], s[28:29], 10
	s_add_u32 s48, s11, s38
	s_addc_u32 s49, s41, s39
	s_and_b64 s[50:51], s[56:57], exec
	s_cselect_b32 s11, s49, s53
	s_cselect_b32 s29, s48, s52
	s_ashr_i32 s41, s40, 31
	s_lshl_b64 s[50:51], s[40:41], 20
	s_add_u32 s41, s13, s50
	s_addc_u32 s45, s62, s51
	s_add_u32 s50, s41, s38
	s_addc_u32 s51, s45, s39
	s_and_b64 s[38:39], s[56:57], exec
	s_cselect_b32 s41, s51, s55
	s_cselect_b32 s45, s50, s54
	s_add_u32 s71, s54, 0x100
	v_mov_b32_e32 v2, 0
	s_addc_u32 s72, s55, 0
	s_mov_b32 s73, -2
	v_mov_b32_e32 v3, v2
	v_mov_b32_e32 v4, v2
	v_mov_b32_e32 v5, v2
	v_mov_b32_e32 v6, v2
	v_mov_b32_e32 v7, v2
	v_mov_b32_e32 v8, v2
	v_mov_b32_e32 v9, v2
	v_mov_b32_e32 v10, v2
	v_mov_b32_e32 v11, v2
	v_mov_b32_e32 v12, v2
	v_mov_b32_e32 v13, v2
	v_mov_b32_e32 v14, v2
	v_mov_b32_e32 v15, v2
	v_mov_b32_e32 v16, v2
	v_mov_b32_e32 v17, v2
	v_mov_b32_e32 v26, v2
	v_mov_b32_e32 v27, v2
	v_mov_b32_e32 v28, v2
	v_mov_b32_e32 v29, v2
	v_mov_b32_e32 v30, v2
	v_mov_b32_e32 v31, v2
	v_mov_b32_e32 v32, v2
	v_mov_b32_e32 v33, v2
	v_mov_b32_e32 v42, v2
	v_mov_b32_e32 v43, v2
	v_mov_b32_e32 v44, v2
	v_mov_b32_e32 v45, v2
	v_mov_b32_e32 v46, v2
	v_mov_b32_e32 v47, v2
	v_mov_b32_e32 v48, v2
	v_mov_b32_e32 v49, v2
	v_mov_b32_e32 v18, v2
	v_mov_b32_e32 v19, v2
	v_mov_b32_e32 v20, v2
	v_mov_b32_e32 v21, v2
	v_mov_b32_e32 v22, v2
	v_mov_b32_e32 v23, v2
	v_mov_b32_e32 v24, v2
	v_mov_b32_e32 v25, v2
	v_mov_b32_e32 v34, v2
	v_mov_b32_e32 v35, v2
	v_mov_b32_e32 v36, v2
	v_mov_b32_e32 v37, v2
	v_mov_b32_e32 v38, v2
	v_mov_b32_e32 v39, v2
	v_mov_b32_e32 v40, v2
	v_mov_b32_e32 v41, v2
	v_mov_b32_e32 v50, v2
	v_mov_b32_e32 v51, v2
	v_mov_b32_e32 v52, v2
	v_mov_b32_e32 v53, v2
	v_mov_b32_e32 v54, v2
	v_mov_b32_e32 v55, v2
	v_mov_b32_e32 v56, v2
	v_mov_b32_e32 v57, v2
	v_mov_b32_e32 v58, v2
	v_mov_b32_e32 v59, v2
	v_mov_b32_e32 v60, v2
	v_mov_b32_e32 v61, v2
	v_mov_b32_e32 v62, v2
	v_mov_b32_e32 v63, v2
	v_mov_b32_e32 v64, v2
	v_mov_b32_e32 v65, v2
	v_mov_b32_e32 v66, v2
	v_mov_b32_e32 v67, v2
	v_mov_b32_e32 v68, v2
	v_mov_b32_e32 v69, v2
	v_mov_b32_e32 v70, v2
	v_mov_b32_e32 v71, v2
	v_mov_b32_e32 v72, v2
	v_mov_b32_e32 v73, v2
	v_mov_b32_e32 v74, v2
	v_mov_b32_e32 v75, v2
	v_mov_b32_e32 v76, v2
	v_mov_b32_e32 v77, v2
	v_mov_b32_e32 v78, v2
	v_mov_b32_e32 v79, v2
	v_mov_b32_e32 v80, v2
	v_mov_b32_e32 v81, v2
	v_mov_b32_e32 v86, v2
	v_mov_b32_e32 v87, v2
	v_mov_b32_e32 v88, v2
	v_mov_b32_e32 v89, v2
	v_mov_b32_e32 v94, v2
	v_mov_b32_e32 v95, v2
	v_mov_b32_e32 v96, v2
	v_mov_b32_e32 v97, v2
	v_mov_b32_e32 v102, v2
	v_mov_b32_e32 v103, v2
	v_mov_b32_e32 v104, v2
	v_mov_b32_e32 v105, v2
	v_mov_b32_e32 v110, v2
	v_mov_b32_e32 v111, v2
	v_mov_b32_e32 v112, v2
	v_mov_b32_e32 v113, v2
	v_mov_b32_e32 v82, v2
	v_mov_b32_e32 v83, v2
	v_mov_b32_e32 v84, v2
	v_mov_b32_e32 v85, v2
	v_mov_b32_e32 v90, v2
	v_mov_b32_e32 v91, v2
	v_mov_b32_e32 v92, v2
	v_mov_b32_e32 v93, v2
	v_mov_b32_e32 v98, v2
	v_mov_b32_e32 v99, v2
	v_mov_b32_e32 v100, v2
	v_mov_b32_e32 v101, v2
	v_mov_b32_e32 v106, v2
	v_mov_b32_e32 v107, v2
	v_mov_b32_e32 v108, v2
	v_mov_b32_e32 v109, v2
	v_mov_b32_e32 v114, v2
	v_mov_b32_e32 v115, v2
	v_mov_b32_e32 v116, v2
	v_mov_b32_e32 v117, v2
	v_mov_b32_e32 v118, v2
	v_mov_b32_e32 v119, v2
	v_mov_b32_e32 v120, v2
	v_mov_b32_e32 v121, v2
	v_mov_b32_e32 v122, v2
	v_mov_b32_e32 v123, v2
	v_mov_b32_e32 v124, v2
	v_mov_b32_e32 v125, v2
	v_mov_b32_e32 v126, v2
	v_mov_b32_e32 v127, v2
	v_mov_b32_e32 v128, v2
	v_mov_b32_e32 v129, v2
	s_add_u32 s54, s52, 0x100
	s_addc_u32 s55, s53, 0
	s_cmp_eq_u32 s73, 4
	s_cselect_b32 s59, s11, s55
	s_cselect_b32 s58, s29, s54
	s_cselect_b32 s57, s41, s72
	s_cselect_b32 s56, s45, s71
.LBB0_113:
	s_add_i32 m0, s25, 0xc000
	ds_read_b128 v[140:143], v226
	global_load_lds_dwordx4 v134, s[52:53]
	s_add_i32 m0, s25, 0xe000
	ds_read_b128 v[144:147], v226 offset:1024
	global_load_lds_dwordx4 v132, s[52:53]
	s_add_i32 s38, 0, 0x10000
	ds_read_b128 v[148:151], v226 offset:2048
	ds_read_b128 v[152:155], v226 offset:3072
	ds_read_b128 v[160:163], v139
	ds_read_b128 v[164:167], v139 offset:1024
	ds_read_b128 v[168:171], v139 offset:2048
	ds_read_b128 v[172:175], v139 offset:3072
	ds_read_b128 v[176:179], v139 offset:4096
	ds_read_b128 v[180:183], v139 offset:5120
	ds_read_b128 v[184:187], v139 offset:6144
	ds_read_b128 v[188:191], v139 offset:7168
	s_add_i32 s52, 0, 0x14000
	ds_read_b128 v[192:195], v226 offset:16384
	ds_read_b128 v[196:199], v226 offset:17408
	ds_read_b128 v[200:203], v226 offset:18432
	ds_read_b128 v[204:207], v226 offset:19456
	s_waitcnt lgkmcnt(4)
	s_barrier
; #define PG8_STAGE(bufoff, gbase, voff) do { _Pragma("unroll") for (int _i = 0; _i < 2; ++_i) \
;         __builtin_amdgcn_global_load_lds((const unsigned*)((const char*)(gbase) + (voff)[_i]), (LAS unsigned*)(lds + (bufoff) + ldsw + _i * 8192), 16, 0, 0); } while (0)
; #define PG8_LDA(dst, b, h) do { _Pragma("unroll") for (int m = 0; m < 4; ++m) _Pragma("unroll") for (int k = 0; k < 2; ++k) dst[m][k] = *(const LAS bf16x8*)(lds + PG8_SA(b, h) + aoff + m * 2048 + k * 1024); } while (0)
; #define PG8_LDB(dst, b, h) do { _Pragma("unroll") for (int n = 0; n < 2; ++n) _Pragma("unroll") for (int k = 0; k < 2; ++k) dst[n][k] = *(const LAS bf16x8*)(lds + PG8_SB(b, h) + boff + n * 2048 + k * 1024); } while (0)
; #define PG8_MMA(ai, bj, At, Bt) do { __builtin_amdgcn_s_setprio(1); _Pragma("unroll") for (int m = 0; m < 4; ++m) _Pragma("unroll") for (int n = 0; n < 2; ++n) _Pragma("unroll") for (int k = 0; k < 2; ++k) \
;         acc[ai][bj][m][n] = __builtin_amdgcn_mfma_f32_16x16x32_bf16(Bt[n][k], At[m][k], acc[ai][bj][m][n], 0, 0, 0); __builtin_amdgcn_s_setprio(0); } while (0)
; #define PG8_WAIT_V(n) asm volatile("s_waitcnt vmcnt(" #n ")" ::: "memory")
; #define PG8_WAIT_L(n) asm volatile("s_waitcnt lgkmcnt(" #n ")" ::: "memory")
; #define PG8_BAR __builtin_amdgcn_s_barrier()
; #define PG8_SCHED __builtin_amdgcn_sched_barrier(0)
; template <class Epi, class Sched>
; __device__ __forceinline__ void gemm_phase(LAS unsigned char* lds, const Gemm g, const Sched& S, const Epi& E) {
;     ...
;             PG8_LDB(B0, 0, 0); PG8_SCHED; PG8_LDA(At, 0, 0); PG8_STAGE(PG8_SA(1, 1), a1 + hstep, voffA);
;             PG8_WAIT_L(8); PG8_BAR; PG8_WAIT_L(0); PG8_MMA(0, 0, At, B0); PG8_BAR; PG8_SCHED;
;             PG8_LDB(B1, 0, 1); PG8_STAGE(PG8_SB(0, 0), b2, voffB);
;             PG8_BAR; PG8_WAIT_L(0); PG8_MMA(0, 1, At, B1); PG8_BAR;
;             PG8_LDA(At, 0, 1); PG8_STAGE(PG8_SA(0, 0), a2, voffA);
;             PG8_BAR; PG8_WAIT_L(0); PG8_MMA(1, 0, At, B0); PG8_BAR; PG8_SCHED;
;             PG8_STAGE(PG8_SB(0, 1), b2 + hstep, voffB);
;             PG8_WAIT_V(6); PG8_BAR; PG8_MMA(1, 1, At, B1); PG8_BAR;
	s_waitcnt lgkmcnt(0)
	v_mfma_f32_16x16x32_bf16 v[126:129], v[140:143], v[160:163], v[126:129]
	v_mfma_f32_16x16x32_bf16 v[122:125], v[148:151], v[160:163], v[122:125]
	v_mfma_f32_16x16x32_bf16 v[118:121], v[140:143], v[168:171], v[118:121]
	v_mfma_f32_16x16x32_bf16 v[114:117], v[148:151], v[168:171], v[114:117]
	v_mfma_f32_16x16x32_bf16 v[106:109], v[140:143], v[176:179], v[106:109]
	v_mfma_f32_16x16x32_bf16 v[98:101], v[148:151], v[176:179], v[98:101]
	v_mfma_f32_16x16x32_bf16 v[90:93], v[140:143], v[184:187], v[90:93]
	v_mfma_f32_16x16x32_bf16 v[82:85], v[148:151], v[184:187], v[82:85]
	v_mfma_f32_16x16x32_bf16 v[126:129], v[144:147], v[164:167], v[126:129]
	v_mfma_f32_16x16x32_bf16 v[122:125], v[152:155], v[164:167], v[122:125]
	v_mfma_f32_16x16x32_bf16 v[118:121], v[144:147], v[172:175], v[118:121]
	v_mfma_f32_16x16x32_bf16 v[114:117], v[152:155], v[172:175], v[114:117]
	v_mfma_f32_16x16x32_bf16 v[106:109], v[144:147], v[180:183], v[106:109]
	v_mfma_f32_16x16x32_bf16 v[98:101], v[152:155], v[180:183], v[98:101]
	v_mfma_f32_16x16x32_bf16 v[90:93], v[144:147], v[188:191], v[90:93]
	v_mfma_f32_16x16x32_bf16 v[82:85], v[152:155], v[188:191], v[82:85]
	v_mfma_f32_16x16x32_bf16 v[110:113], v[192:195], v[160:163], v[110:113]
	v_mfma_f32_16x16x32_bf16 v[102:105], v[200:203], v[160:163], v[102:105]
	v_mfma_f32_16x16x32_bf16 v[94:97], v[192:195], v[168:171], v[94:97]
	v_mfma_f32_16x16x32_bf16 v[86:89], v[200:203], v[168:171], v[86:89]
	v_mfma_f32_16x16x32_bf16 v[78:81], v[192:195], v[176:179], v[78:81]
	v_mfma_f32_16x16x32_bf16 v[74:77], v[200:203], v[176:179], v[74:77]
	v_mfma_f32_16x16x32_bf16 v[70:73], v[192:195], v[184:187], v[70:73]
	v_mfma_f32_16x16x32_bf16 v[66:69], v[200:203], v[184:187], v[66:69]
	v_mfma_f32_16x16x32_bf16 v[110:113], v[196:199], v[164:167], v[110:113]
	v_mfma_f32_16x16x32_bf16 v[102:105], v[204:207], v[164:167], v[102:105]
	v_mfma_f32_16x16x32_bf16 v[94:97], v[196:199], v[172:175], v[94:97]
	v_mfma_f32_16x16x32_bf16 v[86:89], v[204:207], v[172:175], v[86:89]
	v_mfma_f32_16x16x32_bf16 v[78:81], v[196:199], v[180:183], v[78:81]
	v_mfma_f32_16x16x32_bf16 v[74:77], v[204:207], v[180:183], v[74:77]
	v_mfma_f32_16x16x32_bf16 v[70:73], v[196:199], v[188:191], v[70:73]
	v_mfma_f32_16x16x32_bf16 v[66:69], v[204:207], v[188:191], v[66:69]
	s_barrier
	s_add_i32 s38, s38, s65
	s_mov_b32 m0, s38
	ds_read_b128 v[160:163], v139 offset:16384
	global_load_lds_dwordx4 v0, s[56:57]
	s_add_i32 m0, s38, 0x2000
	ds_read_b128 v[164:167], v139 offset:17408
	global_load_lds_dwordx4 v130, s[56:57]
	s_mov_b32 m0, s25
	ds_read_b128 v[168:171], v139 offset:18432
	global_load_lds_dwordx4 v0, s[58:59]
	s_mov_b32 m0, s27
	ds_read_b128 v[172:175], v139 offset:19456
	global_load_lds_dwordx4 v130, s[58:59]
	ds_read_b128 v[176:179], v139 offset:20480
	ds_read_b128 v[180:183], v139 offset:21504
	ds_read_b128 v[184:187], v139 offset:22528
	ds_read_b128 v[188:191], v139 offset:23552
	s_waitcnt vmcnt(4)
	s_waitcnt lgkmcnt(0)
	s_barrier
	v_mfma_f32_16x16x32_bf16 v[62:65], v[140:143], v[160:163], v[62:65]
	v_mfma_f32_16x16x32_bf16 v[58:61], v[148:151], v[160:163], v[58:61]
	v_mfma_f32_16x16x32_bf16 v[54:57], v[140:143], v[168:171], v[54:57]
	v_mfma_f32_16x16x32_bf16 v[50:53], v[148:151], v[168:171], v[50:53]
	v_mfma_f32_16x16x32_bf16 v[38:41], v[140:143], v[176:179], v[38:41]
	v_mfma_f32_16x16x32_bf16 v[34:37], v[148:151], v[176:179], v[34:37]
	v_mfma_f32_16x16x32_bf16 v[22:25], v[140:143], v[184:187], v[22:25]
	v_mfma_f32_16x16x32_bf16 v[18:21], v[148:151], v[184:187], v[18:21]
	v_mfma_f32_16x16x32_bf16 v[62:65], v[144:147], v[164:167], v[62:65]
	v_mfma_f32_16x16x32_bf16 v[58:61], v[152:155], v[164:167], v[58:61]
	v_mfma_f32_16x16x32_bf16 v[54:57], v[144:147], v[172:175], v[54:57]
	v_mfma_f32_16x16x32_bf16 v[50:53], v[152:155], v[172:175], v[50:53]
	v_mfma_f32_16x16x32_bf16 v[38:41], v[144:147], v[180:183], v[38:41]
	v_mfma_f32_16x16x32_bf16 v[34:37], v[152:155], v[180:183], v[34:37]
	v_mfma_f32_16x16x32_bf16 v[22:25], v[144:147], v[188:191], v[22:25]
	v_mfma_f32_16x16x32_bf16 v[18:21], v[152:155], v[188:191], v[18:21]
	v_mfma_f32_16x16x32_bf16 v[46:49], v[192:195], v[160:163], v[46:49]
	v_mfma_f32_16x16x32_bf16 v[42:45], v[200:203], v[160:163], v[42:45]
	v_mfma_f32_16x16x32_bf16 v[30:33], v[192:195], v[168:171], v[30:33]
	v_mfma_f32_16x16x32_bf16 v[26:29], v[200:203], v[168:171], v[26:29]
	v_mfma_f32_16x16x32_bf16 v[14:17], v[192:195], v[176:179], v[14:17]
	v_mfma_f32_16x16x32_bf16 v[10:13], v[200:203], v[176:179], v[10:13]
	v_mfma_f32_16x16x32_bf16 v[6:9], v[192:195], v[184:187], v[6:9]
	v_mfma_f32_16x16x32_bf16 v[2:5], v[200:203], v[184:187], v[2:5]
	v_mfma_f32_16x16x32_bf16 v[46:49], v[196:199], v[164:167], v[46:49]
	v_mfma_f32_16x16x32_bf16 v[42:45], v[204:207], v[164:167], v[42:45]
	v_mfma_f32_16x16x32_bf16 v[30:33], v[196:199], v[172:175], v[30:33]
	v_mfma_f32_16x16x32_bf16 v[26:29], v[204:207], v[172:175], v[26:29]
	v_mfma_f32_16x16x32_bf16 v[14:17], v[196:199], v[180:183], v[14:17]
	v_mfma_f32_16x16x32_bf16 v[10:13], v[204:207], v[180:183], v[10:13]
	v_mfma_f32_16x16x32_bf16 v[6:9], v[196:199], v[188:191], v[6:9]
	v_mfma_f32_16x16x32_bf16 v[2:5], v[204:207], v[188:191], v[2:5]
	s_barrier
; #define PG8_STAGE(bufoff, gbase, voff) do { _Pragma("unroll") for (int _i = 0; _i < 2; ++_i) \
;         __builtin_amdgcn_global_load_lds((const unsigned*)((const char*)(gbase) + (voff)[_i]), (LAS unsigned*)(lds + (bufoff) + ldsw + _i * 8192), 16, 0, 0); } while (0)
; #define PG8_LDA(dst, b, h) do { _Pragma("unroll") for (int m = 0; m < 4; ++m) _Pragma("unroll") for (int k = 0; k < 2; ++k) dst[m][k] = *(const LAS bf16x8*)(lds + PG8_SA(b, h) + aoff + m * 2048 + k * 1024); } while (0)
; #define PG8_LDB(dst, b, h) do { _Pragma("unroll") for (int n = 0; n < 2; ++n) _Pragma("unroll") for (int k = 0; k < 2; ++k) dst[n][k] = *(const LAS bf16x8*)(lds + PG8_SB(b, h) + boff + n * 2048 + k * 1024); } while (0)
; #define PG8_MMA(ai, bj, At, Bt) do { __builtin_amdgcn_s_setprio(1); _Pragma("unroll") for (int m = 0; m < 4; ++m) _Pragma("unroll") for (int n = 0; n < 2; ++n) _Pragma("unroll") for (int k = 0; k < 2; ++k) \
;         acc[ai][bj][m][n] = __builtin_amdgcn_mfma_f32_16x16x32_bf16(Bt[n][k], At[m][k], acc[ai][bj][m][n], 0, 0, 0); __builtin_amdgcn_s_setprio(0); } while (0)
; #define PG8_WAIT_L(n) asm volatile("s_waitcnt lgkmcnt(" #n ")" ::: "memory")
; #define PG8_BAR __builtin_amdgcn_s_barrier()
; #define PG8_SCHED __builtin_amdgcn_sched_barrier(0)
; template <class Epi, class Sched>
; __device__ __forceinline__ void gemm_phase(LAS unsigned char* lds, const Gemm g, const Sched& S, const Epi& E) {
;     ...
;             PG8_LDB(B0, 1, 0); PG8_SCHED; PG8_LDA(At, 1, 0); PG8_STAGE(PG8_SA(0, 1), a2 + hstep, voffA);
;             PG8_WAIT_L(8); PG8_BAR; PG8_WAIT_L(0); PG8_MMA(0, 0, At, B0); PG8_BAR; PG8_SCHED;
;             PG8_LDB(B1, 1, 1); PG8_STAGE(PG8_SB(1, 0), b3, voffB);
;             PG8_BAR; PG8_WAIT_L(0); PG8_MMA(0, 1, At, B1); PG8_BAR;
;             PG8_LDA(At, 1, 1); PG8_STAGE(PG8_SA(1, 0), a3, voffA);
;             PG8_BAR; PG8_WAIT_L(0); PG8_MMA(1, 0, At, B0); PG8_BAR; PG8_SCHED;
	s_add_u32 s38, s56, 0x80000
	s_addc_u32 s39, s57, 0
	s_add_i32 s52, s52, s65
	s_mov_b32 m0, s52
	ds_read_b128 v[140:143], v226 offset:32768
	global_load_lds_dwordx4 v0, s[38:39]
	s_add_i32 m0, s52, 0x2000
	ds_read_b128 v[144:147], v226 offset:33792
	global_load_lds_dwordx4 v130, s[38:39]
	s_add_u32 s38, s58, 0x80000
	s_addc_u32 s39, s59, 0
	s_mov_b32 m0, s66
	ds_read_b128 v[148:151], v226 offset:34816
	global_load_lds_dwordx4 v0, s[38:39]
	s_mov_b32 m0, s67
	ds_read_b128 v[152:155], v226 offset:35840
	global_load_lds_dwordx4 v130, s[38:39]
	s_add_i32 s52, 0, 0x18000
	ds_read_b128 v[160:163], v139 offset:32768
	ds_read_b128 v[164:167], v139 offset:33792
	ds_read_b128 v[168:171], v139 offset:34816
	ds_read_b128 v[172:175], v139 offset:35840
	ds_read_b128 v[176:179], v139 offset:36864
	ds_read_b128 v[180:183], v139 offset:37888
	ds_read_b128 v[184:187], v139 offset:38912
	ds_read_b128 v[188:191], v139 offset:39936
	s_add_i32 s53, 0, 0x1c000
	ds_read_b128 v[192:195], v226 offset:49152
	ds_read_b128 v[196:199], v226 offset:50176
	ds_read_b128 v[200:203], v226 offset:51200
	ds_read_b128 v[204:207], v226 offset:52224
	s_waitcnt lgkmcnt(4)
	s_barrier
	s_waitcnt lgkmcnt(0)
	v_mfma_f32_16x16x32_bf16 v[126:129], v[140:143], v[160:163], v[126:129]
	v_mfma_f32_16x16x32_bf16 v[122:125], v[148:151], v[160:163], v[122:125]
	v_mfma_f32_16x16x32_bf16 v[118:121], v[140:143], v[168:171], v[118:121]
	v_mfma_f32_16x16x32_bf16 v[114:117], v[148:151], v[168:171], v[114:117]
	v_mfma_f32_16x16x32_bf16 v[106:109], v[140:143], v[176:179], v[106:109]
	v_mfma_f32_16x16x32_bf16 v[98:101], v[148:151], v[176:179], v[98:101]
	v_mfma_f32_16x16x32_bf16 v[90:93], v[140:143], v[184:187], v[90:93]
	v_mfma_f32_16x16x32_bf16 v[82:85], v[148:151], v[184:187], v[82:85]
	v_mfma_f32_16x16x32_bf16 v[126:129], v[144:147], v[164:167], v[126:129]
	v_mfma_f32_16x16x32_bf16 v[122:125], v[152:155], v[164:167], v[122:125]
	v_mfma_f32_16x16x32_bf16 v[118:121], v[144:147], v[172:175], v[118:121]
	v_mfma_f32_16x16x32_bf16 v[114:117], v[152:155], v[172:175], v[114:117]
	v_mfma_f32_16x16x32_bf16 v[106:109], v[144:147], v[180:183], v[106:109]
	v_mfma_f32_16x16x32_bf16 v[98:101], v[152:155], v[180:183], v[98:101]
	v_mfma_f32_16x16x32_bf16 v[90:93], v[144:147], v[188:191], v[90:93]
	v_mfma_f32_16x16x32_bf16 v[82:85], v[152:155], v[188:191], v[82:85]
	v_mfma_f32_16x16x32_bf16 v[110:113], v[192:195], v[160:163], v[110:113]
	v_mfma_f32_16x16x32_bf16 v[102:105], v[200:203], v[160:163], v[102:105]
	v_mfma_f32_16x16x32_bf16 v[94:97], v[192:195], v[168:171], v[94:97]
	v_mfma_f32_16x16x32_bf16 v[86:89], v[200:203], v[168:171], v[86:89]
	v_mfma_f32_16x16x32_bf16 v[78:81], v[192:195], v[176:179], v[78:81]
	v_mfma_f32_16x16x32_bf16 v[74:77], v[200:203], v[176:179], v[74:77]
	v_mfma_f32_16x16x32_bf16 v[70:73], v[192:195], v[184:187], v[70:73]
	v_mfma_f32_16x16x32_bf16 v[66:69], v[200:203], v[184:187], v[66:69]
	v_mfma_f32_16x16x32_bf16 v[110:113], v[196:199], v[164:167], v[110:113]
	v_mfma_f32_16x16x32_bf16 v[102:105], v[204:207], v[164:167], v[102:105]
	v_mfma_f32_16x16x32_bf16 v[94:97], v[196:199], v[172:175], v[94:97]
	v_mfma_f32_16x16x32_bf16 v[86:89], v[204:207], v[172:175], v[86:89]
	v_mfma_f32_16x16x32_bf16 v[78:81], v[196:199], v[180:183], v[78:81]
	v_mfma_f32_16x16x32_bf16 v[74:77], v[204:207], v[180:183], v[74:77]
	v_mfma_f32_16x16x32_bf16 v[70:73], v[196:199], v[188:191], v[70:73]
	v_mfma_f32_16x16x32_bf16 v[66:69], v[204:207], v[188:191], v[66:69]
	s_barrier
	s_add_i32 s38, s52, s65
	s_add_u32 s100, s56, s36
	s_addc_u32 s101, s57, s37
	s_mov_b32 m0, s38
	ds_read_b128 v[160:163], v139 offset:49152
	global_load_lds_dwordx4 v0, s[100:101]
	s_add_i32 m0, s38, 0x2000
	ds_read_b128 v[164:167], v139 offset:50176
	global_load_lds_dwordx4 v130, s[100:101]
	s_mov_b32 m0, s68
	s_add_u32 s100, s58, s36
	s_addc_u32 s101, s59, s37
	global_load_lds_dwordx4 v0, s[100:101]
	s_mov_b32 m0, s69
	ds_read_b128 v[168:171], v139 offset:51200
	global_load_lds_dwordx4 v130, s[100:101]
	ds_read_b128 v[172:175], v139 offset:52224
	ds_read_b128 v[176:179], v139 offset:53248
	ds_read_b128 v[180:183], v139 offset:54272
	ds_read_b128 v[184:187], v139 offset:55296
	ds_read_b128 v[188:191], v139 offset:56320
	s_waitcnt vmcnt(4)
	s_waitcnt lgkmcnt(0)
	s_barrier
; #define PG8_STAGE(bufoff, gbase, voff) do { _Pragma("unroll") for (int _i = 0; _i < 2; ++_i) \
;         __builtin_amdgcn_global_load_lds((const unsigned*)((const char*)(gbase) + (voff)[_i]), (LAS unsigned*)(lds + (bufoff) + ldsw + _i * 8192), 16, 0, 0); } while (0)
; #define PG8_LDA(dst, b, h) do { _Pragma("unroll") for (int m = 0; m < 4; ++m) _Pragma("unroll") for (int k = 0; k < 2; ++k) dst[m][k] = *(const LAS bf16x8*)(lds + PG8_SA(b, h) + aoff + m * 2048 + k * 1024); } while (0)
; #define PG8_LDB(dst, b, h) do { _Pragma("unroll") for (int n = 0; n < 2; ++n) _Pragma("unroll") for (int k = 0; k < 2; ++k) dst[n][k] = *(const LAS bf16x8*)(lds + PG8_SB(b, h) + boff + n * 2048 + k * 1024); } while (0)
; #define PG8_MMA(ai, bj, At, Bt) do { __builtin_amdgcn_s_setprio(1); _Pragma("unroll") for (int m = 0; m < 4; ++m) _Pragma("unroll") for (int n = 0; n < 2; ++n) _Pragma("unroll") for (int k = 0; k < 2; ++k) \
;         acc[ai][bj][m][n] = __builtin_amdgcn_mfma_f32_16x16x32_bf16(Bt[n][k], At[m][k], acc[ai][bj][m][n], 0, 0, 0); __builtin_amdgcn_s_setprio(0); } while (0)
;     __device__ __forceinline__ void operator()(const f32x4 (&acc)[2][2][4][2], const Unit& u, int wr, int wc, int fr, int fq) const {
;         const int row0 = u.pm * BM + wr * 64 + fr, col0 = u.pn * BM + wc * 32 + 4 * fq;
;         float* base = part + (size_t)u.ks * Mp * ldc;
; #pragma unroll
;         for (int ai = 0; ai < 2; ++ai)
; #pragma unroll
;             for (int m = 0; m < 4; ++m) { float* rowp = base + (size_t)(row0 + ai * HALF + m * 16) * ldc + col0;
; #pragma unroll
;                 for (int bj = 0; bj < 2; ++bj)
; #pragma unroll
;                     for (int n = 0; n < 2; ++n) *(f32x4*)(rowp + bj * HALF + n * 16) = acc[ai][bj][m][n]; }
;     }
; template <class Epi, class Sched>
; __device__ __forceinline__ void gemm_phase(LAS unsigned char* lds, const Gemm g, const Sched& S, const Epi& E) {
;     ...
;             PG8_LDB(B1, 1, 1); PG8_STAGE(PG8_SB(1, 0), b3, voffB);
;             PG8_BAR; PG8_WAIT_L(0); PG8_MMA(0, 1, At, B1); PG8_BAR;
;             PG8_LDA(At, 1, 1); PG8_STAGE(PG8_SA(1, 0), a3, voffA);
;             PG8_BAR; PG8_WAIT_L(0); PG8_MMA(1, 0, At, B0); PG8_BAR; PG8_SCHED;
;             PG8_STAGE(PG8_SB(1, 1), b3 + hstep, voffB);
;             PG8_WAIT_V(6); PG8_BAR; PG8_MMA(1, 1, At, B1); PG8_BAR;
;     ...
;     PG8_WAIT_V(0);
;     if (wr == 0) PG8_BAR;
	v_mfma_f32_16x16x32_bf16 v[62:65], v[140:143], v[160:163], v[62:65]
	v_mfma_f32_16x16x32_bf16 v[58:61], v[148:151], v[160:163], v[58:61]
	v_mfma_f32_16x16x32_bf16 v[54:57], v[140:143], v[168:171], v[54:57]
	v_mfma_f32_16x16x32_bf16 v[50:53], v[148:151], v[168:171], v[50:53]
	v_mfma_f32_16x16x32_bf16 v[38:41], v[140:143], v[176:179], v[38:41]
	v_mfma_f32_16x16x32_bf16 v[34:37], v[148:151], v[176:179], v[34:37]
	v_mfma_f32_16x16x32_bf16 v[22:25], v[140:143], v[184:187], v[22:25]
	v_mfma_f32_16x16x32_bf16 v[18:21], v[148:151], v[184:187], v[18:21]
	v_mfma_f32_16x16x32_bf16 v[62:65], v[144:147], v[164:167], v[62:65]
	v_mfma_f32_16x16x32_bf16 v[58:61], v[152:155], v[164:167], v[58:61]
	v_mfma_f32_16x16x32_bf16 v[54:57], v[144:147], v[172:175], v[54:57]
	v_mfma_f32_16x16x32_bf16 v[50:53], v[152:155], v[172:175], v[50:53]
	v_mfma_f32_16x16x32_bf16 v[38:41], v[144:147], v[180:183], v[38:41]
	v_mfma_f32_16x16x32_bf16 v[34:37], v[152:155], v[180:183], v[34:37]
	v_mfma_f32_16x16x32_bf16 v[22:25], v[144:147], v[188:191], v[22:25]
	v_mfma_f32_16x16x32_bf16 v[18:21], v[152:155], v[188:191], v[18:21]
	s_add_u32 s38, s56, 0x80080
	s_addc_u32 s39, s57, 0
	s_add_i32 s52, s53, s65
	s_mov_b32 m0, s52
	s_nop 0
	global_load_lds_dwordx4 v0, s[38:39]
	s_add_i32 m0, s52, 0x2000
	s_nop 0
	global_load_lds_dwordx4 v130, s[38:39]
	v_mfma_f32_16x16x32_bf16 v[46:49], v[192:195], v[160:163], v[46:49]
	v_mfma_f32_16x16x32_bf16 v[42:45], v[200:203], v[160:163], v[42:45]
	v_mfma_f32_16x16x32_bf16 v[30:33], v[192:195], v[168:171], v[30:33]
	v_mfma_f32_16x16x32_bf16 v[26:29], v[200:203], v[168:171], v[26:29]
	v_mfma_f32_16x16x32_bf16 v[14:17], v[192:195], v[176:179], v[14:17]
	v_mfma_f32_16x16x32_bf16 v[10:13], v[200:203], v[176:179], v[10:13]
	v_mfma_f32_16x16x32_bf16 v[6:9], v[192:195], v[184:187], v[6:9]
	v_mfma_f32_16x16x32_bf16 v[2:5], v[200:203], v[184:187], v[2:5]
	v_mfma_f32_16x16x32_bf16 v[46:49], v[196:199], v[164:167], v[46:49]
	v_mfma_f32_16x16x32_bf16 v[42:45], v[204:207], v[164:167], v[42:45]
	v_mfma_f32_16x16x32_bf16 v[30:33], v[196:199], v[172:175], v[30:33]
	v_mfma_f32_16x16x32_bf16 v[26:29], v[204:207], v[172:175], v[26:29]
	v_mfma_f32_16x16x32_bf16 v[14:17], v[196:199], v[180:183], v[14:17]
	v_mfma_f32_16x16x32_bf16 v[10:13], v[204:207], v[180:183], v[10:13]
	v_mfma_f32_16x16x32_bf16 v[6:9], v[196:199], v[188:191], v[6:9]
	v_mfma_f32_16x16x32_bf16 v[2:5], v[204:207], v[188:191], v[2:5]
	s_add_i32 s73, s73, 2
	s_add_u32 s71, s71, 0x100
	s_addc_u32 s72, s72, 0
	s_mov_b64 s[52:53], s[54:55]
	s_add_u32 s54, s52, 0x100
	s_addc_u32 s55, s53, 0
	s_cmp_eq_u32 s73, 4
	s_cselect_b32 s59, s11, s55
	s_cselect_b32 s58, s29, s54
	s_cselect_b32 s57, s41, s72
	s_cselect_b32 s56, s45, s71
	s_cmp_gt_u32 s73, 5
	s_barrier
	s_cbranch_scc0 .LBB0_113
	s_ashr_i32 s11, s10, 31
	s_lshl_b64 s[10:11], s[10:11], 24
	v_lshl_or_b32 v140, s26, 8, v138
	s_add_u32 s10, s8, s10
	v_lshl_add_u32 v142, s24, 8, v136
	s_addc_u32 s11, s9, s11
	v_ashrrev_i32_e32 v141, 31, v140
	v_ashrrev_i32_e32 v143, 31, v142
	v_lshl_add_u64 v[140:141], v[140:141], 2, s[10:11]
	v_lshlrev_b64 v[144:145], 13, v[142:143]
	v_lshl_add_u64 v[144:145], v[140:141], 0, v[144:145]
	global_store_dwordx4 v[144:145], v[126:129], off
	global_store_dwordx4 v[144:145], v[122:125], off offset:64
	global_store_dwordx4 v[144:145], v[110:113], off offset:512
	global_store_dwordx4 v[144:145], v[102:105], off offset:576
	s_mov_b64 s[10:11], 0x100000
	s_mov_b32 s26, s40
	v_or_b32_e32 v102, 16, v142
	v_ashrrev_i32_e32 v103, 31, v102
	v_lshlrev_b64 v[102:103], 13, v[102:103]
	v_lshl_add_u64 v[102:103], v[140:141], 0, v[102:103]
	global_store_dwordx4 v[102:103], v[118:121], off
	global_store_dwordx4 v[102:103], v[114:117], off offset:64
	global_store_dwordx4 v[102:103], v[94:97], off offset:512
	global_store_dwordx4 v[102:103], v[86:89], off offset:576
	s_mov_b32 s24, s44
	s_mov_b64 s[54:55], s[50:51]
	v_or_b32_e32 v86, 32, v142
	v_ashrrev_i32_e32 v87, 31, v86
	v_lshlrev_b64 v[86:87], 13, v[86:87]
	v_lshl_add_u64 v[86:87], v[140:141], 0, v[86:87]
	global_store_dwordx4 v[86:87], v[106:109], off
	global_store_dwordx4 v[86:87], v[98:101], off offset:64
	global_store_dwordx4 v[86:87], v[78:81], off offset:512
	global_store_dwordx4 v[86:87], v[74:77], off offset:576
	s_mov_b64 s[52:53], s[48:49]
	s_nop 0
	v_or_b32_e32 v74, 48, v142
	v_ashrrev_i32_e32 v75, 31, v74
	v_lshlrev_b64 v[74:75], 13, v[74:75]
	v_lshl_add_u64 v[74:75], v[140:141], 0, v[74:75]
	global_store_dwordx4 v[74:75], v[90:93], off
	global_store_dwordx4 v[74:75], v[82:85], off offset:64
	global_store_dwordx4 v[74:75], v[70:73], off offset:512
	global_store_dwordx4 v[74:75], v[66:69], off offset:576
	s_nop 1
	v_add_co_u32_e32 v68, vcc, s93, v144
	v_lshl_add_u64 v[66:67], v[144:145], 0, s[10:11]
	s_nop 0
	v_addc_co_u32_e32 v69, vcc, 0, v145, vcc
	s_mov_b64 s[10:11], 0x120000
	global_store_dwordx4 v[68:69], v[62:65], off
	global_store_dwordx4 v[66:67], v[58:61], off offset:64
	global_store_dwordx4 v[66:67], v[46:49], off offset:512
	global_store_dwordx4 v[66:67], v[42:45], off offset:576
	s_nop 1
	v_lshl_add_u64 v[42:43], v[144:145], 0, s[10:11]
	s_mov_b32 s10, 0x120000
	v_add_co_u32_e32 v44, vcc, s10, v144
	s_mov_b64 s[10:11], 0x140000
	s_nop 0
	v_addc_co_u32_e32 v45, vcc, 0, v145, vcc
	global_store_dwordx4 v[44:45], v[54:57], off
	global_store_dwordx4 v[42:43], v[50:53], off offset:64
	global_store_dwordx4 v[42:43], v[30:33], off offset:512
	global_store_dwordx4 v[42:43], v[26:29], off offset:576
	s_nop 1
	v_lshl_add_u64 v[26:27], v[144:145], 0, s[10:11]
	s_mov_b32 s10, 0x140000
	v_add_co_u32_e32 v28, vcc, s10, v144
	s_mov_b64 s[10:11], 0x160000
	s_nop 0
	v_addc_co_u32_e32 v29, vcc, 0, v145, vcc
	global_store_dwordx4 v[28:29], v[38:41], off
	global_store_dwordx4 v[26:27], v[34:37], off offset:64
	global_store_dwordx4 v[26:27], v[14:17], off offset:512
	global_store_dwordx4 v[26:27], v[10:13], off offset:576
	s_nop 1
	v_add_co_u32_e32 v12, vcc, 0x160000, v144
	v_lshl_add_u64 v[10:11], v[144:145], 0, s[10:11]
	s_nop 0
	v_addc_co_u32_e32 v13, vcc, 0, v145, vcc
	s_and_b64 vcc, exec, s[46:47]
	s_mov_b32 s10, s28
	global_store_dwordx4 v[12:13], v[22:25], off
	global_store_dwordx4 v[10:11], v[18:21], off offset:64
	global_store_dwordx4 v[10:11], v[6:9], off offset:512
	global_store_dwordx4 v[10:11], v[2:5], off offset:576
	s_cbranch_vccz .LBB0_110
	s_waitcnt vmcnt(0)
	s_cmpk_gt_u32 s60, 0xff
	s_cbranch_scc1 .LBB0_117
	s_barrier

; #define PG8_STAGE(bufoff, gbase, voff) do { _Pragma("unroll") for (int _i = 0; _i < 2; ++_i) \
;         __builtin_amdgcn_global_load_lds((const unsigned*)((const char*)(gbase) + (voff)[_i]), (LAS unsigned*)(lds + (bufoff) + ldsw + _i * 8192), 16, 0, 0); } while (0)
; #define PG8_LDA(dst, b, h) do { _Pragma("unroll") for (int m = 0; m < 4; ++m) _Pragma("unroll") for (int k = 0; k < 2; ++k) dst[m][k] = *(const LAS bf16x8*)(lds + PG8_SA(b, h) + aoff + m * 2048 + k * 1024); } while (0)
; #define PG8_LDB(dst, b, h) do { _Pragma("unroll") for (int n = 0; n < 2; ++n) _Pragma("unroll") for (int k = 0; k < 2; ++k) dst[n][k] = *(const LAS bf16x8*)(lds + PG8_SB(b, h) + boff + n * 2048 + k * 1024); } while (0)
; #define PG8_SCHED __builtin_amdgcn_sched_barrier(0)
; template <class Epi, class Sched>
; __device__ __forceinline__ void gemm_phase(LAS unsigned char* lds, const Gemm g, const Sched& S, const Epi& E) {
;     ...
;         const bool has_next = S.next(ui + 1, nxt);
;         const char* nA = has_next ? (const char*)g.A + (size_t)nxt.pm * tstep + (size_t)nxt.ks * sstep : cA; const char* nB = has_next ? (const char*)g.Bt + (size_t)nxt.pn * tstep + (size_t)nxt.ks * sstep : cB;
;         for (int t = 0; t < nt; t += 2) {
;             const bool last = (t == nt - 2);
;             const char* a1 = cA + (size_t)(t + 1) * kstep;
;             const char* a2 = last ? nA : cA + (size_t)(t + 2) * kstep; const char* b2 = last ? nB : cB + (size_t)(t + 2) * kstep;
;             const char* a3 = a2 + kstep; const char* b3 = b2 + kstep;
;             PG8_LDB(B0, 0, 0); PG8_SCHED; PG8_LDA(At, 0, 0); PG8_STAGE(PG8_SA(1, 1), a1 + hstep, voffA);
;     ...
; #pragma unroll
;         for (int a = 0; a < 2; ++a)
; #pragma unroll
;             for (int b = 0; b < 2; ++b)
; #pragma unroll
;                 for (int m = 0; m < 4; ++m)
; #pragma unroll
;                     for (int n = 0; n < 2; ++n) acc[a][b][m][n] = (f32x4){0.f, 0.f, 0.f, 0.f};
;         cur = nxt; cA = nA; cB = nB; ++ui;
.LBB0_353:
	s_ashr_i32 s9, s8, 31
	s_xor_b64 s[46:47], s[54:55], -1
	s_lshl_b64 s[44:45], s[8:9], 20
	s_add_u32 s44, s26, s44
	s_addc_u32 s45, s27, s45
	s_and_b64 s[48:49], s[54:55], exec
	s_cselect_b32 s9, s45, s53
	s_cselect_b32 s66, s44, s52
	s_ashr_i32 s43, s42, 31
	s_lshl_b64 s[48:49], s[42:43], 20
	s_add_u32 s48, s75, s48
	s_addc_u32 s49, s76, s49
	s_and_b64 s[54:55], s[54:55], exec
	s_cselect_b32 s43, s49, s51
	s_cselect_b32 s67, s48, s50
	s_add_u32 s68, s50, 0x100
	s_addc_u32 s69, s51, 0
	s_add_u32 s50, s52, 0x80080
	v_mov_b32_e32 v2, 0
	s_addc_u32 s51, s53, 0
	s_mov_b32 s70, -2
	v_mov_b32_e32 v3, v2
	v_mov_b32_e32 v4, v2
	v_mov_b32_e32 v5, v2
	v_mov_b32_e32 v6, v2
	v_mov_b32_e32 v7, v2
	v_mov_b32_e32 v8, v2
	v_mov_b32_e32 v9, v2
	v_mov_b32_e32 v10, v2
	v_mov_b32_e32 v11, v2
	v_mov_b32_e32 v12, v2
	v_mov_b32_e32 v13, v2
	v_mov_b32_e32 v18, v2
	v_mov_b32_e32 v19, v2
	v_mov_b32_e32 v20, v2
	v_mov_b32_e32 v21, v2
	v_mov_b32_e32 v26, v2
	v_mov_b32_e32 v27, v2
	v_mov_b32_e32 v28, v2
	v_mov_b32_e32 v29, v2
	v_mov_b32_e32 v34, v2
	v_mov_b32_e32 v35, v2
	v_mov_b32_e32 v36, v2
	v_mov_b32_e32 v37, v2
	v_mov_b32_e32 v42, v2
	v_mov_b32_e32 v43, v2
	v_mov_b32_e32 v44, v2
	v_mov_b32_e32 v45, v2
	v_mov_b32_e32 v50, v2
	v_mov_b32_e32 v51, v2
	v_mov_b32_e32 v52, v2
	v_mov_b32_e32 v53, v2
	v_mov_b32_e32 v14, v2
	v_mov_b32_e32 v15, v2
	v_mov_b32_e32 v16, v2
	v_mov_b32_e32 v17, v2
	v_mov_b32_e32 v22, v2
	v_mov_b32_e32 v23, v2
	v_mov_b32_e32 v24, v2
	v_mov_b32_e32 v25, v2
	v_mov_b32_e32 v30, v2
	v_mov_b32_e32 v31, v2
	v_mov_b32_e32 v32, v2
	v_mov_b32_e32 v33, v2
	v_mov_b32_e32 v38, v2
	v_mov_b32_e32 v39, v2
	v_mov_b32_e32 v40, v2
	v_mov_b32_e32 v41, v2
	v_mov_b32_e32 v46, v2
	v_mov_b32_e32 v47, v2
	v_mov_b32_e32 v48, v2
	v_mov_b32_e32 v49, v2
	v_mov_b32_e32 v54, v2
	v_mov_b32_e32 v55, v2
	v_mov_b32_e32 v56, v2
	v_mov_b32_e32 v57, v2
	v_mov_b32_e32 v58, v2
	v_mov_b32_e32 v59, v2
	v_mov_b32_e32 v60, v2
	v_mov_b32_e32 v61, v2
	v_mov_b32_e32 v62, v2
	v_mov_b32_e32 v63, v2
	v_mov_b32_e32 v64, v2
	v_mov_b32_e32 v65, v2
	v_mov_b32_e32 v66, v2
	v_mov_b32_e32 v67, v2
	v_mov_b32_e32 v68, v2
	v_mov_b32_e32 v69, v2
	v_mov_b32_e32 v70, v2
	v_mov_b32_e32 v71, v2
	v_mov_b32_e32 v72, v2
	v_mov_b32_e32 v73, v2
	v_mov_b32_e32 v74, v2
	v_mov_b32_e32 v75, v2
	v_mov_b32_e32 v76, v2
	v_mov_b32_e32 v77, v2
	v_mov_b32_e32 v82, v2
	v_mov_b32_e32 v83, v2
	v_mov_b32_e32 v84, v2
	v_mov_b32_e32 v85, v2
	v_mov_b32_e32 v90, v2
	v_mov_b32_e32 v91, v2
	v_mov_b32_e32 v92, v2
	v_mov_b32_e32 v93, v2
	v_mov_b32_e32 v98, v2
	v_mov_b32_e32 v99, v2
	v_mov_b32_e32 v100, v2
	v_mov_b32_e32 v101, v2
	v_mov_b32_e32 v106, v2
	v_mov_b32_e32 v107, v2
	v_mov_b32_e32 v108, v2
	v_mov_b32_e32 v109, v2
	v_mov_b32_e32 v114, v2
	v_mov_b32_e32 v115, v2
	v_mov_b32_e32 v116, v2
	v_mov_b32_e32 v117, v2
	v_mov_b32_e32 v78, v2
	v_mov_b32_e32 v79, v2
	v_mov_b32_e32 v80, v2
	v_mov_b32_e32 v81, v2
	v_mov_b32_e32 v86, v2
	v_mov_b32_e32 v87, v2
	v_mov_b32_e32 v88, v2
	v_mov_b32_e32 v89, v2
	v_mov_b32_e32 v94, v2
	v_mov_b32_e32 v95, v2
	v_mov_b32_e32 v96, v2
	v_mov_b32_e32 v97, v2
	v_mov_b32_e32 v102, v2
	v_mov_b32_e32 v103, v2
	v_mov_b32_e32 v104, v2
	v_mov_b32_e32 v105, v2
	v_mov_b32_e32 v110, v2
	v_mov_b32_e32 v111, v2
	v_mov_b32_e32 v112, v2
	v_mov_b32_e32 v113, v2
	v_mov_b32_e32 v118, v2
	v_mov_b32_e32 v119, v2
	v_mov_b32_e32 v120, v2
	v_mov_b32_e32 v121, v2
	v_mov_b32_e32 v122, v2
	v_mov_b32_e32 v123, v2
	v_mov_b32_e32 v124, v2
	v_mov_b32_e32 v125, v2
	v_mov_b32_e32 v126, v2
	v_mov_b32_e32 v127, v2
	v_mov_b32_e32 v128, v2
	v_mov_b32_e32 v129, v2
	s_add_u32 s38, s50, 0xfff80080
	s_addc_u32 s39, s51, -1
	s_cmp_eq_u32 s70, 28
	s_cselect_b32 s55, s9, s39
	s_cselect_b32 s54, s66, s38
	s_cselect_b32 s53, s43, s69
	s_cselect_b32 s52, s67, s68
.LBB0_354:
	s_add_i32 m0, s29, 0xc000
	ds_read_b128 v[140:143], v226
	global_load_lds_dwordx4 v138, s[50:51]
	s_add_i32 m0, s29, 0xe000
	ds_read_b128 v[148:151], v226 offset:1024
	global_load_lds_dwordx4 v136, s[50:51]
	s_add_i32 s71, 0, 0x10000
	ds_read_b128 v[152:155], v226 offset:2048
	ds_read_b128 v[160:163], v226 offset:3072
	ds_read_b128 v[164:167], v147
	ds_read_b128 v[168:171], v147 offset:1024
	ds_read_b128 v[172:175], v147 offset:2048
	ds_read_b128 v[176:179], v147 offset:3072
	ds_read_b128 v[180:183], v147 offset:4096
	ds_read_b128 v[184:187], v147 offset:5120
	ds_read_b128 v[188:191], v147 offset:6144
	ds_read_b128 v[192:195], v147 offset:7168
	s_add_i32 s38, 0, 0x14000
	ds_read_b128 v[196:199], v226 offset:16384
	ds_read_b128 v[200:203], v226 offset:17408
	ds_read_b128 v[204:207], v226 offset:18432
	ds_read_b128 v[210:213], v226 offset:19456
	s_waitcnt lgkmcnt(4)
	s_barrier
; #define PG8_STAGE(bufoff, gbase, voff) do { _Pragma("unroll") for (int _i = 0; _i < 2; ++_i) \
;         __builtin_amdgcn_global_load_lds((const unsigned*)((const char*)(gbase) + (voff)[_i]), (LAS unsigned*)(lds + (bufoff) + ldsw + _i * 8192), 16, 0, 0); } while (0)
; #define PG8_LDA(dst, b, h) do { _Pragma("unroll") for (int m = 0; m < 4; ++m) _Pragma("unroll") for (int k = 0; k < 2; ++k) dst[m][k] = *(const LAS bf16x8*)(lds + PG8_SA(b, h) + aoff + m * 2048 + k * 1024); } while (0)
; #define PG8_LDB(dst, b, h) do { _Pragma("unroll") for (int n = 0; n < 2; ++n) _Pragma("unroll") for (int k = 0; k < 2; ++k) dst[n][k] = *(const LAS bf16x8*)(lds + PG8_SB(b, h) + boff + n * 2048 + k * 1024); } while (0)
; #define PG8_MMA(ai, bj, At, Bt) do { __builtin_amdgcn_s_setprio(1); _Pragma("unroll") for (int m = 0; m < 4; ++m) _Pragma("unroll") for (int n = 0; n < 2; ++n) _Pragma("unroll") for (int k = 0; k < 2; ++k) \
;         acc[ai][bj][m][n] = __builtin_amdgcn_mfma_f32_16x16x32_bf16(Bt[n][k], At[m][k], acc[ai][bj][m][n], 0, 0, 0); __builtin_amdgcn_s_setprio(0); } while (0)
; #define PG8_WAIT_V(n) asm volatile("s_waitcnt vmcnt(" #n ")" ::: "memory")
; #define PG8_WAIT_L(n) asm volatile("s_waitcnt lgkmcnt(" #n ")" ::: "memory")
; #define PG8_BAR __builtin_amdgcn_s_barrier()
; #define PG8_SCHED __builtin_amdgcn_sched_barrier(0)
; template <class Epi, class Sched>
; __device__ __forceinline__ void gemm_phase(LAS unsigned char* lds, const Gemm g, const Sched& S, const Epi& E) {
;     ...
;             PG8_LDB(B0, 0, 0); PG8_SCHED; PG8_LDA(At, 0, 0); PG8_STAGE(PG8_SA(1, 1), a1 + hstep, voffA);
;             PG8_WAIT_L(8); PG8_BAR; PG8_WAIT_L(0); PG8_MMA(0, 0, At, B0); PG8_BAR; PG8_SCHED;
;             PG8_LDB(B1, 0, 1); PG8_STAGE(PG8_SB(0, 0), b2, voffB);
;             PG8_BAR; PG8_WAIT_L(0); PG8_MMA(0, 1, At, B1); PG8_BAR;
;             PG8_LDA(At, 0, 1); PG8_STAGE(PG8_SA(0, 0), a2, voffA);
;             PG8_BAR; PG8_WAIT_L(0); PG8_MMA(1, 0, At, B0); PG8_BAR; PG8_SCHED;
;             PG8_STAGE(PG8_SB(0, 1), b2 + hstep, voffB);
;             PG8_WAIT_V(6); PG8_BAR; PG8_MMA(1, 1, At, B1); PG8_BAR;
	s_waitcnt lgkmcnt(0)
	v_mfma_f32_16x16x32_bf16 v[126:129], v[140:143], v[164:167], v[126:129]
	v_mfma_f32_16x16x32_bf16 v[122:125], v[152:155], v[164:167], v[122:125]
	v_mfma_f32_16x16x32_bf16 v[118:121], v[140:143], v[172:175], v[118:121]
	v_mfma_f32_16x16x32_bf16 v[110:113], v[152:155], v[172:175], v[110:113]
	v_mfma_f32_16x16x32_bf16 v[102:105], v[140:143], v[180:183], v[102:105]
	v_mfma_f32_16x16x32_bf16 v[94:97], v[152:155], v[180:183], v[94:97]
	v_mfma_f32_16x16x32_bf16 v[86:89], v[140:143], v[188:191], v[86:89]
	v_mfma_f32_16x16x32_bf16 v[78:81], v[152:155], v[188:191], v[78:81]
	v_mfma_f32_16x16x32_bf16 v[126:129], v[148:151], v[168:171], v[126:129]
	v_mfma_f32_16x16x32_bf16 v[122:125], v[160:163], v[168:171], v[122:125]
	v_mfma_f32_16x16x32_bf16 v[118:121], v[148:151], v[176:179], v[118:121]
	v_mfma_f32_16x16x32_bf16 v[110:113], v[160:163], v[176:179], v[110:113]
	v_mfma_f32_16x16x32_bf16 v[102:105], v[148:151], v[184:187], v[102:105]
	v_mfma_f32_16x16x32_bf16 v[94:97], v[160:163], v[184:187], v[94:97]
	v_mfma_f32_16x16x32_bf16 v[86:89], v[148:151], v[192:195], v[86:89]
	v_mfma_f32_16x16x32_bf16 v[78:81], v[160:163], v[192:195], v[78:81]
	v_mfma_f32_16x16x32_bf16 v[114:117], v[196:199], v[164:167], v[114:117]
	v_mfma_f32_16x16x32_bf16 v[106:109], v[204:207], v[164:167], v[106:109]
	v_mfma_f32_16x16x32_bf16 v[98:101], v[196:199], v[172:175], v[98:101]
	v_mfma_f32_16x16x32_bf16 v[90:93], v[204:207], v[172:175], v[90:93]
	v_mfma_f32_16x16x32_bf16 v[82:85], v[196:199], v[180:183], v[82:85]
	v_mfma_f32_16x16x32_bf16 v[74:77], v[204:207], v[180:183], v[74:77]
	v_mfma_f32_16x16x32_bf16 v[70:73], v[196:199], v[188:191], v[70:73]
	v_mfma_f32_16x16x32_bf16 v[66:69], v[204:207], v[188:191], v[66:69]
	v_mfma_f32_16x16x32_bf16 v[114:117], v[200:203], v[168:171], v[114:117]
	v_mfma_f32_16x16x32_bf16 v[106:109], v[210:213], v[168:171], v[106:109]
	v_mfma_f32_16x16x32_bf16 v[98:101], v[200:203], v[176:179], v[98:101]
	v_mfma_f32_16x16x32_bf16 v[90:93], v[210:213], v[176:179], v[90:93]
	v_mfma_f32_16x16x32_bf16 v[82:85], v[200:203], v[184:187], v[82:85]
	v_mfma_f32_16x16x32_bf16 v[74:77], v[210:213], v[184:187], v[74:77]
	v_mfma_f32_16x16x32_bf16 v[70:73], v[200:203], v[192:195], v[70:73]
	v_mfma_f32_16x16x32_bf16 v[66:69], v[210:213], v[192:195], v[66:69]
	s_barrier
	s_add_i32 s39, s71, s56
	s_mov_b32 m0, s39
	ds_read_b128 v[164:167], v147 offset:16384
	global_load_lds_dwordx4 v0, s[52:53]
	s_add_i32 m0, s39, 0x2000
	ds_read_b128 v[168:171], v147 offset:17408
	global_load_lds_dwordx4 v134, s[52:53]
	s_mov_b32 m0, s29
	ds_read_b128 v[172:175], v147 offset:18432
	global_load_lds_dwordx4 v130, s[54:55]
	s_mov_b32 m0, s41
	ds_read_b128 v[176:179], v147 offset:19456
	global_load_lds_dwordx4 v132, s[54:55]
	ds_read_b128 v[180:183], v147 offset:20480
	ds_read_b128 v[184:187], v147 offset:21504
	ds_read_b128 v[188:191], v147 offset:22528
	ds_read_b128 v[192:195], v147 offset:23552
	s_waitcnt vmcnt(4)
	s_waitcnt lgkmcnt(0)
	s_barrier
	v_mfma_f32_16x16x32_bf16 v[62:65], v[140:143], v[164:167], v[62:65]
	v_mfma_f32_16x16x32_bf16 v[58:61], v[152:155], v[164:167], v[58:61]
	v_mfma_f32_16x16x32_bf16 v[54:57], v[140:143], v[172:175], v[54:57]
	v_mfma_f32_16x16x32_bf16 v[46:49], v[152:155], v[172:175], v[46:49]
	v_mfma_f32_16x16x32_bf16 v[38:41], v[140:143], v[180:183], v[38:41]
	v_mfma_f32_16x16x32_bf16 v[30:33], v[152:155], v[180:183], v[30:33]
	v_mfma_f32_16x16x32_bf16 v[22:25], v[140:143], v[188:191], v[22:25]
	v_mfma_f32_16x16x32_bf16 v[14:17], v[152:155], v[188:191], v[14:17]
	v_mfma_f32_16x16x32_bf16 v[62:65], v[148:151], v[168:171], v[62:65]
	v_mfma_f32_16x16x32_bf16 v[58:61], v[160:163], v[168:171], v[58:61]
	v_mfma_f32_16x16x32_bf16 v[54:57], v[148:151], v[176:179], v[54:57]
	v_mfma_f32_16x16x32_bf16 v[46:49], v[160:163], v[176:179], v[46:49]
	v_mfma_f32_16x16x32_bf16 v[38:41], v[148:151], v[184:187], v[38:41]
	v_mfma_f32_16x16x32_bf16 v[30:33], v[160:163], v[184:187], v[30:33]
	v_mfma_f32_16x16x32_bf16 v[22:25], v[148:151], v[192:195], v[22:25]
	v_mfma_f32_16x16x32_bf16 v[14:17], v[160:163], v[192:195], v[14:17]
	v_mfma_f32_16x16x32_bf16 v[50:53], v[196:199], v[164:167], v[50:53]
	v_mfma_f32_16x16x32_bf16 v[42:45], v[204:207], v[164:167], v[42:45]
	v_mfma_f32_16x16x32_bf16 v[34:37], v[196:199], v[172:175], v[34:37]
	v_mfma_f32_16x16x32_bf16 v[26:29], v[204:207], v[172:175], v[26:29]
	v_mfma_f32_16x16x32_bf16 v[18:21], v[196:199], v[180:183], v[18:21]
	v_mfma_f32_16x16x32_bf16 v[10:13], v[204:207], v[180:183], v[10:13]
	v_mfma_f32_16x16x32_bf16 v[6:9], v[196:199], v[188:191], v[6:9]
	v_mfma_f32_16x16x32_bf16 v[2:5], v[204:207], v[188:191], v[2:5]
	v_mfma_f32_16x16x32_bf16 v[50:53], v[200:203], v[168:171], v[50:53]
	v_mfma_f32_16x16x32_bf16 v[42:45], v[210:213], v[168:171], v[42:45]
	v_mfma_f32_16x16x32_bf16 v[34:37], v[200:203], v[176:179], v[34:37]
	v_mfma_f32_16x16x32_bf16 v[26:29], v[210:213], v[176:179], v[26:29]
	v_mfma_f32_16x16x32_bf16 v[18:21], v[200:203], v[184:187], v[18:21]
	v_mfma_f32_16x16x32_bf16 v[10:13], v[210:213], v[184:187], v[10:13]
	v_mfma_f32_16x16x32_bf16 v[6:9], v[200:203], v[192:195], v[6:9]
	v_mfma_f32_16x16x32_bf16 v[2:5], v[210:213], v[192:195], v[2:5]
	s_barrier
; #define PG8_STAGE(bufoff, gbase, voff) do { _Pragma("unroll") for (int _i = 0; _i < 2; ++_i) \
;         __builtin_amdgcn_global_load_lds((const unsigned*)((const char*)(gbase) + (voff)[_i]), (LAS unsigned*)(lds + (bufoff) + ldsw + _i * 8192), 16, 0, 0); } while (0)
; #define PG8_LDA(dst, b, h) do { _Pragma("unroll") for (int m = 0; m < 4; ++m) _Pragma("unroll") for (int k = 0; k < 2; ++k) dst[m][k] = *(const LAS bf16x8*)(lds + PG8_SA(b, h) + aoff + m * 2048 + k * 1024); } while (0)
; #define PG8_LDB(dst, b, h) do { _Pragma("unroll") for (int n = 0; n < 2; ++n) _Pragma("unroll") for (int k = 0; k < 2; ++k) dst[n][k] = *(const LAS bf16x8*)(lds + PG8_SB(b, h) + boff + n * 2048 + k * 1024); } while (0)
; #define PG8_MMA(ai, bj, At, Bt) do { __builtin_amdgcn_s_setprio(1); _Pragma("unroll") for (int m = 0; m < 4; ++m) _Pragma("unroll") for (int n = 0; n < 2; ++n) _Pragma("unroll") for (int k = 0; k < 2; ++k) \
;         acc[ai][bj][m][n] = __builtin_amdgcn_mfma_f32_16x16x32_bf16(Bt[n][k], At[m][k], acc[ai][bj][m][n], 0, 0, 0); __builtin_amdgcn_s_setprio(0); } while (0)
; #define PG8_WAIT_L(n) asm volatile("s_waitcnt lgkmcnt(" #n ")" ::: "memory")
; #define PG8_BAR __builtin_amdgcn_s_barrier()
; #define PG8_SCHED __builtin_amdgcn_sched_barrier(0)
; template <class Epi, class Sched>
; __device__ __forceinline__ void gemm_phase(LAS unsigned char* lds, const Gemm g, const Sched& S, const Epi& E) {
;     ...
;             PG8_LDB(B0, 1, 0); PG8_SCHED; PG8_LDA(At, 1, 0); PG8_STAGE(PG8_SA(0, 1), a2 + hstep, voffA);
;             PG8_WAIT_L(8); PG8_BAR; PG8_WAIT_L(0); PG8_MMA(0, 0, At, B0); PG8_BAR; PG8_SCHED;
;             PG8_LDB(B1, 1, 1); PG8_STAGE(PG8_SB(1, 0), b3, voffB);
;             PG8_BAR; PG8_WAIT_L(0); PG8_MMA(0, 1, At, B1); PG8_BAR;
;             PG8_LDA(At, 1, 1); PG8_STAGE(PG8_SA(1, 0), a3, voffA);
;             PG8_BAR; PG8_WAIT_L(0); PG8_MMA(1, 0, At, B0); PG8_BAR; PG8_SCHED;
	s_add_u32 s72, s52, 0x80000
	s_addc_u32 s73, s53, 0
	s_add_i32 s38, s38, s56
	s_mov_b32 m0, s38
	ds_read_b128 v[140:143], v226 offset:32768
	global_load_lds_dwordx4 v0, s[72:73]
	s_add_i32 m0, s38, 0x2000
	ds_read_b128 v[148:151], v226 offset:33792
	global_load_lds_dwordx4 v134, s[72:73]
	s_add_u32 s54, s54, 0x80000
	s_addc_u32 s55, s55, 0
	s_mov_b32 m0, s57
	ds_read_b128 v[152:155], v226 offset:34816
	global_load_lds_dwordx4 v130, s[54:55]
	s_mov_b32 m0, s58
	ds_read_b128 v[160:163], v226 offset:35840
	global_load_lds_dwordx4 v132, s[54:55]
	s_add_i32 s38, 0, 0x18000
	ds_read_b128 v[164:167], v147 offset:32768
	ds_read_b128 v[168:171], v147 offset:33792
	ds_read_b128 v[172:175], v147 offset:34816
	ds_read_b128 v[176:179], v147 offset:35840
	ds_read_b128 v[180:183], v147 offset:36864
	ds_read_b128 v[184:187], v147 offset:37888
	ds_read_b128 v[188:191], v147 offset:38912
	ds_read_b128 v[192:195], v147 offset:39936
	s_add_i32 s39, 0, 0x1c000
	ds_read_b128 v[196:199], v226 offset:49152
	ds_read_b128 v[200:203], v226 offset:50176
	ds_read_b128 v[204:207], v226 offset:51200
	ds_read_b128 v[210:213], v226 offset:52224
	s_waitcnt lgkmcnt(4)
	s_barrier
	s_waitcnt lgkmcnt(0)
	v_mfma_f32_16x16x32_bf16 v[126:129], v[140:143], v[164:167], v[126:129]
	v_mfma_f32_16x16x32_bf16 v[122:125], v[152:155], v[164:167], v[122:125]
	v_mfma_f32_16x16x32_bf16 v[118:121], v[140:143], v[172:175], v[118:121]
	v_mfma_f32_16x16x32_bf16 v[110:113], v[152:155], v[172:175], v[110:113]
	v_mfma_f32_16x16x32_bf16 v[102:105], v[140:143], v[180:183], v[102:105]
	v_mfma_f32_16x16x32_bf16 v[94:97], v[152:155], v[180:183], v[94:97]
	v_mfma_f32_16x16x32_bf16 v[86:89], v[140:143], v[188:191], v[86:89]
	v_mfma_f32_16x16x32_bf16 v[78:81], v[152:155], v[188:191], v[78:81]
	v_mfma_f32_16x16x32_bf16 v[126:129], v[148:151], v[168:171], v[126:129]
	v_mfma_f32_16x16x32_bf16 v[122:125], v[160:163], v[168:171], v[122:125]
	v_mfma_f32_16x16x32_bf16 v[118:121], v[148:151], v[176:179], v[118:121]
	v_mfma_f32_16x16x32_bf16 v[110:113], v[160:163], v[176:179], v[110:113]
	v_mfma_f32_16x16x32_bf16 v[102:105], v[148:151], v[184:187], v[102:105]
	v_mfma_f32_16x16x32_bf16 v[94:97], v[160:163], v[184:187], v[94:97]
	v_mfma_f32_16x16x32_bf16 v[86:89], v[148:151], v[192:195], v[86:89]
	v_mfma_f32_16x16x32_bf16 v[78:81], v[160:163], v[192:195], v[78:81]
	v_mfma_f32_16x16x32_bf16 v[114:117], v[196:199], v[164:167], v[114:117]
	v_mfma_f32_16x16x32_bf16 v[106:109], v[204:207], v[164:167], v[106:109]
	v_mfma_f32_16x16x32_bf16 v[98:101], v[196:199], v[172:175], v[98:101]
	v_mfma_f32_16x16x32_bf16 v[90:93], v[204:207], v[172:175], v[90:93]
	v_mfma_f32_16x16x32_bf16 v[82:85], v[196:199], v[180:183], v[82:85]
	v_mfma_f32_16x16x32_bf16 v[74:77], v[204:207], v[180:183], v[74:77]
	v_mfma_f32_16x16x32_bf16 v[70:73], v[196:199], v[188:191], v[70:73]
	v_mfma_f32_16x16x32_bf16 v[66:69], v[204:207], v[188:191], v[66:69]
	v_mfma_f32_16x16x32_bf16 v[114:117], v[200:203], v[168:171], v[114:117]
	v_mfma_f32_16x16x32_bf16 v[106:109], v[210:213], v[168:171], v[106:109]
	v_mfma_f32_16x16x32_bf16 v[98:101], v[200:203], v[176:179], v[98:101]
	v_mfma_f32_16x16x32_bf16 v[90:93], v[210:213], v[176:179], v[90:93]
	v_mfma_f32_16x16x32_bf16 v[82:85], v[200:203], v[184:187], v[82:85]
	v_mfma_f32_16x16x32_bf16 v[74:77], v[210:213], v[184:187], v[74:77]
	v_mfma_f32_16x16x32_bf16 v[70:73], v[200:203], v[192:195], v[70:73]
	v_mfma_f32_16x16x32_bf16 v[66:69], v[210:213], v[192:195], v[66:69]
	s_barrier
	s_add_i32 s38, s38, s56
	s_add_u32 s100, s52, s36
	s_addc_u32 s101, s53, s37
	s_mov_b32 m0, s38
	ds_read_b128 v[164:167], v147 offset:49152
	global_load_lds_dwordx4 v0, s[100:101]
	s_add_i32 m0, s38, 0x2000
	ds_read_b128 v[168:171], v147 offset:50176
	global_load_lds_dwordx4 v134, s[100:101]
	s_mov_b32 m0, s59
	s_add_u32 s100, s54, s36
	s_addc_u32 s101, s55, s37
	s_sub_u32 s100, s100, 0x80000
	s_subb_u32 s101, s101, 0
	global_load_lds_dwordx4 v130, s[100:101]
	s_mov_b32 m0, s60
	ds_read_b128 v[172:175], v147 offset:51200
	global_load_lds_dwordx4 v132, s[100:101]
	ds_read_b128 v[176:179], v147 offset:52224
	ds_read_b128 v[180:183], v147 offset:53248
	ds_read_b128 v[184:187], v147 offset:54272
	ds_read_b128 v[188:191], v147 offset:55296
	ds_read_b128 v[192:195], v147 offset:56320
	s_waitcnt vmcnt(4)
	s_waitcnt lgkmcnt(0)
	s_barrier
; #define PG8_STAGE(bufoff, gbase, voff) do { _Pragma("unroll") for (int _i = 0; _i < 2; ++_i) \
;         __builtin_amdgcn_global_load_lds((const unsigned*)((const char*)(gbase) + (voff)[_i]), (LAS unsigned*)(lds + (bufoff) + ldsw + _i * 8192), 16, 0, 0); } while (0)
; #define PG8_LDA(dst, b, h) do { _Pragma("unroll") for (int m = 0; m < 4; ++m) _Pragma("unroll") for (int k = 0; k < 2; ++k) dst[m][k] = *(const LAS bf16x8*)(lds + PG8_SA(b, h) + aoff + m * 2048 + k * 1024); } while (0)
; #define PG8_LDB(dst, b, h) do { _Pragma("unroll") for (int n = 0; n < 2; ++n) _Pragma("unroll") for (int k = 0; k < 2; ++k) dst[n][k] = *(const LAS bf16x8*)(lds + PG8_SB(b, h) + boff + n * 2048 + k * 1024); } while (0)
; #define PG8_MMA(ai, bj, At, Bt) do { __builtin_amdgcn_s_setprio(1); _Pragma("unroll") for (int m = 0; m < 4; ++m) _Pragma("unroll") for (int n = 0; n < 2; ++n) _Pragma("unroll") for (int k = 0; k < 2; ++k) \
;         acc[ai][bj][m][n] = __builtin_amdgcn_mfma_f32_16x16x32_bf16(Bt[n][k], At[m][k], acc[ai][bj][m][n], 0, 0, 0); __builtin_amdgcn_s_setprio(0); } while (0)
; #define PG8_WAIT_V(n) asm volatile("s_waitcnt vmcnt(" #n ")" ::: "memory")
; #define PG8_WAIT_L(n) asm volatile("s_waitcnt lgkmcnt(" #n ")" ::: "memory")
; #define PG8_BAR __builtin_amdgcn_s_barrier()
; #define PG8_SCHED __builtin_amdgcn_sched_barrier(0)
; template <class Epi, class Sched>
; __device__ __forceinline__ void gemm_phase(LAS unsigned char* lds, const Gemm g, const Sched& S, const Epi& E) {
;     ...
;             PG8_LDB(B1, 1, 1); PG8_STAGE(PG8_SB(1, 0), b3, voffB);
;             PG8_BAR; PG8_WAIT_L(0); PG8_MMA(0, 1, At, B1); PG8_BAR;
;             PG8_LDA(At, 1, 1); PG8_STAGE(PG8_SA(1, 0), a3, voffA);
;             PG8_BAR; PG8_WAIT_L(0); PG8_MMA(1, 0, At, B0); PG8_BAR; PG8_SCHED;
;             PG8_STAGE(PG8_SB(1, 1), b3 + hstep, voffB);
;             PG8_WAIT_V(6); PG8_BAR; PG8_MMA(1, 1, At, B1); PG8_BAR;
	v_mfma_f32_16x16x32_bf16 v[62:65], v[140:143], v[164:167], v[62:65]
	v_mfma_f32_16x16x32_bf16 v[58:61], v[152:155], v[164:167], v[58:61]
	v_mfma_f32_16x16x32_bf16 v[54:57], v[140:143], v[172:175], v[54:57]
	v_mfma_f32_16x16x32_bf16 v[46:49], v[152:155], v[172:175], v[46:49]
	v_mfma_f32_16x16x32_bf16 v[38:41], v[140:143], v[180:183], v[38:41]
	v_mfma_f32_16x16x32_bf16 v[30:33], v[152:155], v[180:183], v[30:33]
	v_mfma_f32_16x16x32_bf16 v[22:25], v[140:143], v[188:191], v[22:25]
	v_mfma_f32_16x16x32_bf16 v[14:17], v[152:155], v[188:191], v[14:17]
	v_mfma_f32_16x16x32_bf16 v[62:65], v[148:151], v[168:171], v[62:65]
	v_mfma_f32_16x16x32_bf16 v[58:61], v[160:163], v[168:171], v[58:61]
	v_mfma_f32_16x16x32_bf16 v[54:57], v[148:151], v[176:179], v[54:57]
	v_mfma_f32_16x16x32_bf16 v[46:49], v[160:163], v[176:179], v[46:49]
	v_mfma_f32_16x16x32_bf16 v[38:41], v[148:151], v[184:187], v[38:41]
	v_mfma_f32_16x16x32_bf16 v[30:33], v[160:163], v[184:187], v[30:33]
	v_mfma_f32_16x16x32_bf16 v[22:25], v[148:151], v[192:195], v[22:25]
	v_mfma_f32_16x16x32_bf16 v[14:17], v[160:163], v[192:195], v[14:17]
	s_add_u32 s52, s52, 0x80080
	s_addc_u32 s53, s53, 0
	s_add_i32 s38, s39, s56
	s_mov_b32 m0, s38
	s_nop 0
	global_load_lds_dwordx4 v0, s[52:53]
	s_add_i32 m0, s38, 0x2000
	s_nop 0
	global_load_lds_dwordx4 v134, s[52:53]
	v_mfma_f32_16x16x32_bf16 v[50:53], v[196:199], v[164:167], v[50:53]
	v_mfma_f32_16x16x32_bf16 v[42:45], v[204:207], v[164:167], v[42:45]
	v_mfma_f32_16x16x32_bf16 v[34:37], v[196:199], v[172:175], v[34:37]
	v_mfma_f32_16x16x32_bf16 v[26:29], v[204:207], v[172:175], v[26:29]
	v_mfma_f32_16x16x32_bf16 v[18:21], v[196:199], v[180:183], v[18:21]
	v_mfma_f32_16x16x32_bf16 v[10:13], v[204:207], v[180:183], v[10:13]
	v_mfma_f32_16x16x32_bf16 v[6:9], v[196:199], v[188:191], v[6:9]
	v_mfma_f32_16x16x32_bf16 v[2:5], v[204:207], v[188:191], v[2:5]
	v_mfma_f32_16x16x32_bf16 v[50:53], v[200:203], v[168:171], v[50:53]
	v_mfma_f32_16x16x32_bf16 v[42:45], v[210:213], v[168:171], v[42:45]
	v_mfma_f32_16x16x32_bf16 v[34:37], v[200:203], v[176:179], v[34:37]
	v_mfma_f32_16x16x32_bf16 v[26:29], v[210:213], v[176:179], v[26:29]
	v_mfma_f32_16x16x32_bf16 v[18:21], v[200:203], v[184:187], v[18:21]
	v_mfma_f32_16x16x32_bf16 v[10:13], v[210:213], v[184:187], v[10:13]
	v_mfma_f32_16x16x32_bf16 v[6:9], v[200:203], v[192:195], v[6:9]
	v_mfma_f32_16x16x32_bf16 v[2:5], v[210:213], v[192:195], v[2:5]
	s_add_i32 s70, s70, 2
	s_add_u32 s68, s68, 0x100
	s_addc_u32 s69, s69, 0
	s_add_u32 s50, s50, 0x100
	s_addc_u32 s51, s51, 0
	s_add_u32 s38, s50, 0xfff80080
	s_addc_u32 s39, s51, -1
	s_cmp_eq_u32 s70, 28
	s_cselect_b32 s55, s9, s39
	s_cselect_b32 s54, s66, s38
	s_cselect_b32 s53, s43, s69
	s_cselect_b32 s52, s67, s68
	s_cmp_gt_u32 s70, 29
	s_barrier
	s_cbranch_scc0 .LBB0_354
; __device__ __forceinline__ unsigned cvt_pk_bf16(float lo, float hi) { unsigned r; asm("v_cvt_pk_bf16_f32 %0, %1, %2" : "=v"(r) : "v"(lo), "v"(hi)); return r; }
; #define PG8_WAIT_V(n) asm volatile("s_waitcnt vmcnt(" #n ")" ::: "memory")
; #define PG8_BAR __builtin_amdgcn_s_barrier()
;     __device__ __forceinline__ void operator()(const f32x4 (&acc)[2][2][4][2], const Unit& u, int wr, int wc, int fr, int fq) const {
;         const int row0 = u.pm * BM + wr * 64 + fr, col0 = u.pn * BM + wc * 32 + 8 * fq;
; #pragma unroll
;         for (int ai = 0; ai < 2; ++ai)
; #pragma unroll
;             for (int m = 0; m < 4; ++m) { bf16_t* rowp = O + (size_t)(row0 + ai * HALF + m * 16) * ldc + col0;
; #pragma unroll
;                 for (int bj = 0; bj < 2; ++bj) { f32x4 v0 = acc[ai][bj][m][0], v1 = acc[ai][bj][m][1];
;                     if (ACT == 1) {
; #pragma unroll
;                         for (int j = 0; j < 4; ++j) { float a = fmaxf(v0[j], 0.f), b = fmaxf(v1[j], 0.f); v0[j] = a * a; v1[j] = b * b; } }
;                     u32x4 w; w.x = cvt_pk_bf16(v0[0], v0[1]); w.y = cvt_pk_bf16(v0[2], v0[3]); w.z = cvt_pk_bf16(v1[0], v1[1]); w.w = cvt_pk_bf16(v1[2], v1[3]);
;                     if (ACT == 1) __builtin_nontemporal_store(w, (u32x4*)(rowp + bj * HALF));
;                     else *(u32x4*)(rowp + bj * HALF) = w; } }
;     }
; template <class Epi, class Sched>
; __device__ __forceinline__ void gemm_phase(LAS unsigned char* lds, const Gemm g, const Sched& S, const Epi& E) {
;     ...
;         if (!has_next) break;
; #pragma unroll
;         for (int a = 0; a < 2; ++a)
; #pragma unroll
;             for (int b = 0; b < 2; ++b)
; #pragma unroll
;                 for (int m = 0; m < 4; ++m)
; #pragma unroll
;                     for (int n = 0; n < 2; ++n) acc[a][b][m][n] = (f32x4){0.f, 0.f, 0.f, 0.f};
;         cur = nxt; cA = nA; cB = nB; ++ui;
;     }
;     PG8_WAIT_V(0);
;     if (wr == 0) PG8_BAR;
	s_load_dwordx2 s[50:51], s[0:1], 0xc0
	v_lshl_add_u32 v150, s28, 8, v144
	v_lshl_or_b32 v142, s40, 8, v146
	v_ashrrev_i32_e32 v143, 31, v142
	v_cvt_pk_bf16_f32 v70, v70, v71
	s_waitcnt lgkmcnt(0)
	v_mov_b64_e32 v[140:141], s[50:51]
	v_cvt_pk_bf16_f32 v71, v72, v73
	v_cvt_pk_bf16_f32 v72, v66, v67
	v_add_u32_e32 v66, 0x80, v150
	v_mad_i64_i32 v[148:149], s[50:51], v150, s17, v[140:141]
	v_lshlrev_b64 v[142:143], 1, v[142:143]
	v_cvt_pk_bf16_f32 v114, v114, v115
	v_cvt_pk_bf16_f32 v115, v116, v117
	v_cvt_pk_bf16_f32 v116, v106, v107
	v_or_b32_e32 v106, 16, v150
	v_mad_i64_i32 v[66:67], s[50:51], v66, s17, v[140:141]
	v_cvt_pk_bf16_f32 v50, v50, v51
	v_cvt_pk_bf16_f32 v51, v52, v53
	v_cvt_pk_bf16_f32 v52, v42, v43
	v_add_u32_e32 v42, 0x90, v150
	v_lshl_add_u64 v[148:149], v[148:149], 0, v[142:143]
	v_mad_i64_i32 v[106:107], s[50:51], v106, s17, v[140:141]
	v_cvt_pk_bf16_f32 v98, v98, v99
	v_cvt_pk_bf16_f32 v99, v100, v101
	v_cvt_pk_bf16_f32 v100, v90, v91
	v_or_b32_e32 v90, 32, v150
	v_lshl_add_u64 v[66:67], v[66:67], 0, v[142:143]
	v_mad_i64_i32 v[42:43], s[50:51], v42, s17, v[140:141]
	v_cvt_pk_bf16_f32 v34, v34, v35
	v_cvt_pk_bf16_f32 v35, v36, v37
	v_cvt_pk_bf16_f32 v36, v26, v27
	v_add_u32_e32 v26, 0xa0, v150
	v_cvt_pk_bf16_f32 v117, v108, v109
	global_store_dwordx4 v[148:149], v[114:117], off offset:256
	v_mad_i64_i32 v[90:91], s[50:51], v90, s17, v[140:141]
	s_nop 0
	v_lshl_add_u64 v[114:115], v[106:107], 0, v[142:143]
	v_cvt_pk_bf16_f32 v82, v82, v83
	v_cvt_pk_bf16_f32 v83, v84, v85
	v_cvt_pk_bf16_f32 v84, v74, v75
	v_or_b32_e32 v74, 48, v150
	v_cvt_pk_bf16_f32 v53, v44, v45
	global_store_dwordx4 v[66:67], v[50:53], off offset:256
	v_mad_i64_i32 v[26:27], s[50:51], v26, s17, v[140:141]
	s_nop 0
	v_lshl_add_u64 v[50:51], v[42:43], 0, v[142:143]
	v_cvt_pk_bf16_f32 v18, v18, v19
	v_cvt_pk_bf16_f32 v19, v20, v21
	v_cvt_pk_bf16_f32 v20, v10, v11
	v_add_u32_e32 v10, 0xb0, v150
	v_cvt_pk_bf16_f32 v101, v92, v93
	global_store_dwordx4 v[114:115], v[98:101], off offset:256
	v_mad_i64_i32 v[74:75], s[50:51], v74, s17, v[140:141]
	s_nop 0
	v_lshl_add_u64 v[98:99], v[90:91], 0, v[142:143]
	v_cvt_pk_bf16_f32 v37, v28, v29
	global_store_dwordx4 v[50:51], v[34:37], off offset:256
	v_mad_i64_i32 v[10:11], s[50:51], v10, s17, v[140:141]
	s_nop 0
	v_lshl_add_u64 v[34:35], v[26:27], 0, v[142:143]
	v_cvt_pk_bf16_f32 v85, v76, v77
	global_store_dwordx4 v[98:99], v[82:85], off offset:256
	v_cvt_pk_bf16_f32 v21, v12, v13
	global_store_dwordx4 v[34:35], v[18:21], off offset:256
	s_and_b64 vcc, exec, s[46:47]
	v_lshl_add_u64 v[82:83], v[74:75], 0, v[142:143]
	v_lshl_add_u64 v[18:19], v[10:11], 0, v[142:143]
	s_mov_b32 s40, s42
	s_mov_b32 s28, s8
	s_mov_b32 s43, s42
	s_mov_b32 s46, s8
	s_mov_b64 s[50:51], s[48:49]
	s_mov_b64 s[52:53], s[44:45]
	v_cvt_pk_bf16_f32 v126, v126, v127
	v_cvt_pk_bf16_f32 v127, v128, v129
	v_cvt_pk_bf16_f32 v128, v122, v123
	v_cvt_pk_bf16_f32 v129, v124, v125
	global_store_dwordx4 v[148:149], v[126:129], off
	v_cvt_pk_bf16_f32 v106, v118, v119
	v_cvt_pk_bf16_f32 v107, v120, v121
	v_cvt_pk_bf16_f32 v108, v110, v111
	v_cvt_pk_bf16_f32 v109, v112, v113
	global_store_dwordx4 v[114:115], v[106:109], off
	v_cvt_pk_bf16_f32 v90, v102, v103
	v_cvt_pk_bf16_f32 v91, v104, v105
	v_cvt_pk_bf16_f32 v92, v94, v95
	v_cvt_pk_bf16_f32 v93, v96, v97
	global_store_dwordx4 v[98:99], v[90:93], off
	v_cvt_pk_bf16_f32 v74, v86, v87
	v_cvt_pk_bf16_f32 v75, v88, v89
	v_cvt_pk_bf16_f32 v76, v78, v79
	v_cvt_pk_bf16_f32 v77, v80, v81
	global_store_dwordx4 v[82:83], v[74:77], off
	v_cvt_pk_bf16_f32 v73, v68, v69
	global_store_dwordx4 v[82:83], v[70:73], off offset:256
	v_cvt_pk_bf16_f32 v62, v62, v63
	v_cvt_pk_bf16_f32 v63, v64, v65
	v_cvt_pk_bf16_f32 v64, v58, v59
	v_cvt_pk_bf16_f32 v65, v60, v61
	global_store_dwordx4 v[66:67], v[62:65], off
	v_cvt_pk_bf16_f32 v42, v54, v55
	v_cvt_pk_bf16_f32 v43, v56, v57
	v_cvt_pk_bf16_f32 v44, v46, v47
	v_cvt_pk_bf16_f32 v45, v48, v49
	global_store_dwordx4 v[50:51], v[42:45], off
	v_cvt_pk_bf16_f32 v26, v38, v39
	v_cvt_pk_bf16_f32 v27, v40, v41
	v_cvt_pk_bf16_f32 v28, v30, v31
	v_cvt_pk_bf16_f32 v29, v32, v33
	global_store_dwordx4 v[34:35], v[26:29], off
	v_cvt_pk_bf16_f32 v10, v22, v23
	v_cvt_pk_bf16_f32 v11, v24, v25
	v_cvt_pk_bf16_f32 v12, v14, v15
	v_cvt_pk_bf16_f32 v13, v16, v17
	global_store_dwordx4 v[18:19], v[10:13], off
	v_cvt_pk_bf16_f32 v6, v6, v7
	v_cvt_pk_bf16_f32 v7, v8, v9
	v_cvt_pk_bf16_f32 v8, v2, v3
	v_cvt_pk_bf16_f32 v9, v4, v5
	global_store_dwordx4 v[18:19], v[6:9], off offset:256
	s_cbranch_vccz .LBB0_346
	s_waitcnt vmcnt(0)
	s_cmpk_gt_u32 s25, 0xff
	s_cbranch_scc1 .LBB0_358
	s_barrier
